# software-pipelined weight-conversion loops (next item's loads issued before the current item's LDS transpose/stores) in G1/G3/G5 phases
# speedup vs baseline: 1.0142x; 1.0142x over previous
.LBB0_32:
	s_add_u32 s4, s10, s4
	s_addc_u32 s5, s11, s5
	s_and_b32 s6, 0xffff, s14
	s_lshl_b32 s6, s6, 1
	s_add_u32 s4, s4, s6
	s_addc_u32 s5, s5, 0
	v_mov_b32_e32 v21, v17
	v_lshl_add_u64 v[6:7], s[4:5], 0, v[20:21]
	v_lshlrev_b64 v[12:13], 12, v[16:17]
	v_lshl_add_u64 v[12:13], v[6:7], 0, v[12:13]
	ds_read2_b32 v[10:11], v27 offset0:8 offset1:41
	global_store_dwordx4 v[12:13], v[2:5], off
	v_or_b32_e32 v9, s9, v15
	s_cmp_gt_i32 s8, 2
	s_waitcnt lgkmcnt(0)
	v_cvt_pk_bf16_f32 v2, v10, v11
	ds_read2_b32 v[4:5], v27 offset0:74 offset1:107
	s_waitcnt lgkmcnt(0)
	v_cvt_pk_bf16_f32 v3, v4, v5
	ds_read2_b32 v[4:5], v27 offset0:140 offset1:173
	s_mov_b64 s[4:5], -1
	s_waitcnt lgkmcnt(0)
	v_cvt_pk_bf16_f32 v4, v4, v5
	ds_read2_b32 v[10:11], v27 offset0:206 offset1:239
	s_waitcnt lgkmcnt(0)
	v_cvt_pk_bf16_f32 v5, v10, v11
	s_cbranch_scc0 .LBB0_34
	v_and_or_b32 v16, v9, s28, v29
	s_mov_b64 s[4:5], 0

.LBB0_38:
	v_lshlrev_b64 v[12:13], 12, v[16:17]
	v_lshl_add_u64 v[12:13], v[6:7], 0, v[12:13]
	ds_read2_b32 v[10:11], v27 offset0:16 offset1:49
	global_store_dwordx4 v[12:13], v[2:5], off
	v_or_b32_e32 v9, s9, v24
	s_cmp_gt_i32 s8, 2
	s_waitcnt lgkmcnt(0)
	v_cvt_pk_bf16_f32 v2, v10, v11
	ds_read2_b32 v[4:5], v27 offset0:82 offset1:115
	s_waitcnt lgkmcnt(0)
	v_cvt_pk_bf16_f32 v3, v4, v5
	ds_read2_b32 v[4:5], v27 offset0:148 offset1:181
	s_mov_b64 s[4:5], -1
	s_waitcnt lgkmcnt(0)
	v_cvt_pk_bf16_f32 v4, v4, v5
	ds_read2_b32 v[10:11], v27 offset0:214 offset1:247
	s_waitcnt lgkmcnt(0)
	v_cvt_pk_bf16_f32 v5, v10, v11
	s_cbranch_scc0 .LBB0_40
	v_and_or_b32 v16, v9, s28, v30
	s_mov_b64 s[4:5], 0

.LBB0_44:
	v_lshlrev_b64 v[12:13], 12, v[16:17]
	v_lshl_add_u64 v[12:13], v[6:7], 0, v[12:13]
	ds_read2_b32 v[10:11], v27 offset0:24 offset1:57
	global_store_dwordx4 v[12:13], v[2:5], off
	v_or_b32_e32 v9, s9, v25
	s_cmp_gt_i32 s8, 2
	s_waitcnt lgkmcnt(0)
	v_cvt_pk_bf16_f32 v2, v10, v11
	ds_read2_b32 v[4:5], v27 offset0:90 offset1:123
	s_waitcnt lgkmcnt(0)
	v_cvt_pk_bf16_f32 v3, v4, v5
	ds_read2_b32 v[4:5], v27 offset0:156 offset1:189
	s_mov_b64 s[4:5], -1
	s_waitcnt lgkmcnt(0)
	v_cvt_pk_bf16_f32 v4, v4, v5
	ds_read2_b32 v[10:11], v27 offset0:222 offset1:255
	s_waitcnt lgkmcnt(0)
	v_cvt_pk_bf16_f32 v5, v10, v11
	s_cbranch_scc0 .LBB0_46
	v_and_or_b32 v16, v9, s28, v31
	s_mov_b64 s[4:5], 0

.LBB0_50:
	v_lshlrev_b64 v[8:9], 12, v[16:17]
	v_lshl_add_u64 v[6:7], v[6:7], 0, v[8:9]
	global_store_dwordx4 v[6:7], v[2:5], off
	s_waitcnt lgkmcnt(0)
	s_branch .LBB0_18

.LBB0_54:
	v_lshl_add_u64 v[56:57], v[22:23], 0, s[8:9]
	v_add_co_u32_e32 v84, vcc, s33, v56
	global_load_dwordx4 v[52:55], v[56:57], off nt
	s_nop 0
	v_addc_co_u32_e32 v85, vcc, 0, v57, vcc
	v_add_co_u32_e32 v86, vcc, s34, v56
	v_mov_b32_e32 v19, s5
	s_nop 0
	v_addc_co_u32_e32 v87, vcc, 0, v57, vcc
	v_add_co_u32_e32 v88, vcc, s35, v56
	s_add_u32 s8, s8, 0x60000
	s_nop 0
	v_addc_co_u32_e32 v89, vcc, 0, v57, vcc
	v_add_co_u32_e32 v90, vcc, s36, v56
	s_addc_u32 s9, s9, 0
	s_nop 0
	v_addc_co_u32_e32 v91, vcc, 0, v57, vcc
	v_add_co_u32_e32 v92, vcc, s37, v56
	s_add_i32 s5, s5, 32
	s_nop 0
	v_addc_co_u32_e32 v93, vcc, 0, v57, vcc
	v_add_co_u32_e32 v94, vcc, s38, v56
	s_cmp_lg_u32 s8, 0xc00000
	s_nop 0
	v_addc_co_u32_e32 v95, vcc, 0, v57, vcc
	v_add_co_u32_e32 v96, vcc, s39, v56
	s_nop 1
	v_addc_co_u32_e32 v97, vcc, 0, v57, vcc
	global_load_dwordx4 v[56:59], v[84:85], off nt
	global_load_dwordx4 v[60:63], v[86:87], off nt
	global_load_dwordx4 v[64:67], v[88:89], off nt
	global_load_dwordx4 v[68:71], v[90:91], off nt
	global_load_dwordx4 v[72:75], v[92:93], off nt
	global_load_dwordx4 v[76:79], v[94:95], off nt
	global_load_dwordx4 v[80:83], v[96:97], off nt
	ds_read_b128 v[84:87], v19
	ds_read_b128 v[88:91], v19 offset:16
	ds_read_b128 v[92:95], v19 offset:1024
	ds_read_b128 v[96:99], v19 offset:1040
	ds_read_b128 v[100:103], v19 offset:2048
	ds_read_b128 v[104:107], v19 offset:2064
	s_waitcnt lgkmcnt(5)
	v_mov_b32_e32 v108, v87
	s_waitcnt lgkmcnt(3)
	v_mov_b32_e32 v110, v95
	v_mov_b32_e32 v114, v91
	s_waitcnt lgkmcnt(1)
	v_mov_b32_e32 v112, v103
	v_mov_b32_e32 v116, v99
	s_waitcnt lgkmcnt(0)
	v_mov_b32_e32 v118, v107
	s_waitcnt vmcnt(7)
	v_pk_fma_f32 v[8:9], v[54:55], v[84:85], v[8:9] op_sel_hi:[1,0,1]
	v_pk_fma_f32 v[6:7], v[52:53], v[84:85], v[6:7] op_sel_hi:[1,0,1]
	v_pk_fma_f32 v[12:13], v[54:55], v[92:93], v[12:13] op_sel_hi:[1,0,1]
	v_pk_fma_f32 v[10:11], v[52:53], v[92:93], v[10:11] op_sel_hi:[1,0,1]
	v_pk_fma_f32 v[4:5], v[54:55], v[100:101], v[4:5] op_sel_hi:[1,0,1]
	v_pk_fma_f32 v[2:3], v[52:53], v[100:101], v[2:3] op_sel_hi:[1,0,1]
	s_waitcnt vmcnt(6)
	v_pk_fma_f32 v[6:7], v[56:57], v[84:85], v[6:7] op_sel:[0,1,0]
	v_pk_fma_f32 v[8:9], v[58:59], v[84:85], v[8:9] op_sel:[0,1,0]
	v_pk_fma_f32 v[10:11], v[56:57], v[92:93], v[10:11] op_sel:[0,1,0]
	v_pk_fma_f32 v[12:13], v[58:59], v[92:93], v[12:13] op_sel:[0,1,0]
	v_pk_fma_f32 v[2:3], v[56:57], v[100:101], v[2:3] op_sel:[0,1,0]
	v_pk_fma_f32 v[4:5], v[58:59], v[100:101], v[4:5] op_sel:[0,1,0]
	s_waitcnt vmcnt(5)
	v_pk_fma_f32 v[8:9], v[62:63], v[86:87], v[8:9] op_sel_hi:[1,0,1]
	v_pk_fma_f32 v[6:7], v[60:61], v[86:87], v[6:7] op_sel_hi:[1,0,1]
	v_pk_fma_f32 v[12:13], v[62:63], v[94:95], v[12:13] op_sel_hi:[1,0,1]
	v_pk_fma_f32 v[10:11], v[60:61], v[94:95], v[10:11] op_sel_hi:[1,0,1]
	v_pk_fma_f32 v[4:5], v[62:63], v[102:103], v[4:5] op_sel_hi:[1,0,1]
	v_pk_fma_f32 v[2:3], v[60:61], v[102:103], v[2:3] op_sel_hi:[1,0,1]
	s_waitcnt vmcnt(4)
	v_pk_fma_f32 v[8:9], v[66:67], v[108:109], v[8:9] op_sel_hi:[1,0,1]
	v_pk_fma_f32 v[6:7], v[64:65], v[108:109], v[6:7] op_sel_hi:[1,0,1]
	v_pk_fma_f32 v[12:13], v[66:67], v[110:111], v[12:13] op_sel_hi:[1,0,1]
	v_pk_fma_f32 v[10:11], v[64:65], v[110:111], v[10:11] op_sel_hi:[1,0,1]
	v_pk_fma_f32 v[4:5], v[66:67], v[112:113], v[4:5] op_sel_hi:[1,0,1]
	v_pk_fma_f32 v[2:3], v[64:65], v[112:113], v[2:3] op_sel_hi:[1,0,1]
	s_waitcnt vmcnt(3)
	v_pk_fma_f32 v[8:9], v[70:71], v[88:89], v[8:9] op_sel_hi:[1,0,1]
	v_pk_fma_f32 v[6:7], v[68:69], v[88:89], v[6:7] op_sel_hi:[1,0,1]
	v_pk_fma_f32 v[12:13], v[70:71], v[96:97], v[12:13] op_sel_hi:[1,0,1]
	v_pk_fma_f32 v[10:11], v[68:69], v[96:97], v[10:11] op_sel_hi:[1,0,1]
	v_pk_fma_f32 v[4:5], v[70:71], v[104:105], v[4:5] op_sel_hi:[1,0,1]
	v_pk_fma_f32 v[2:3], v[68:69], v[104:105], v[2:3] op_sel_hi:[1,0,1]
	s_waitcnt vmcnt(2)
	v_pk_fma_f32 v[8:9], v[74:75], v[88:89], v[8:9] op_sel:[0,1,0]
	v_pk_fma_f32 v[6:7], v[72:73], v[88:89], v[6:7] op_sel:[0,1,0]
	v_pk_fma_f32 v[12:13], v[74:75], v[96:97], v[12:13] op_sel:[0,1,0]
	v_pk_fma_f32 v[10:11], v[72:73], v[96:97], v[10:11] op_sel:[0,1,0]
	v_pk_fma_f32 v[4:5], v[74:75], v[104:105], v[4:5] op_sel:[0,1,0]
	v_pk_fma_f32 v[2:3], v[72:73], v[104:105], v[2:3] op_sel:[0,1,0]
	s_waitcnt vmcnt(1)
	v_pk_fma_f32 v[8:9], v[78:79], v[90:91], v[8:9] op_sel_hi:[1,0,1]
	v_pk_fma_f32 v[6:7], v[76:77], v[90:91], v[6:7] op_sel_hi:[1,0,1]
	v_pk_fma_f32 v[12:13], v[78:79], v[98:99], v[12:13] op_sel_hi:[1,0,1]
	v_pk_fma_f32 v[10:11], v[76:77], v[98:99], v[10:11] op_sel_hi:[1,0,1]
	v_pk_fma_f32 v[4:5], v[78:79], v[106:107], v[4:5] op_sel_hi:[1,0,1]
	v_pk_fma_f32 v[2:3], v[76:77], v[106:107], v[2:3] op_sel_hi:[1,0,1]
	s_waitcnt vmcnt(0)
	v_pk_fma_f32 v[8:9], v[82:83], v[114:115], v[8:9] op_sel_hi:[1,0,1]
	v_pk_fma_f32 v[6:7], v[80:81], v[114:115], v[6:7] op_sel_hi:[1,0,1]
	v_pk_fma_f32 v[12:13], v[82:83], v[116:117], v[12:13] op_sel_hi:[1,0,1]
	v_pk_fma_f32 v[10:11], v[80:81], v[116:117], v[10:11] op_sel_hi:[1,0,1]
	v_pk_fma_f32 v[4:5], v[82:83], v[118:119], v[4:5] op_sel_hi:[1,0,1]
	v_pk_fma_f32 v[2:3], v[80:81], v[118:119], v[2:3] op_sel_hi:[1,0,1]
	s_cbranch_scc1 .LBB0_54
	s_lshl_b32 s4, s4, 3
	s_or_b32 s4, s4, s25
	s_mul_hi_i32 s5, s4, 0x24000
	s_mul_i32 s4, s4, 0x24000
	s_add_u32 s4, s23, s4
	s_addc_u32 s5, s24, s5
	s_add_u32 s4, s4, s6
	s_addc_u32 s5, s5, s7
	v_lshl_add_u64 v[22:23], s[4:5], 0, v[16:17]
	global_store_dwordx4 v16, v[6:9], s[4:5]
	s_nop 1
	v_add_co_u32_e32 v6, vcc, 0xc000, v22
	s_nop 1
	v_addc_co_u32_e32 v7, vcc, 0, v23, vcc
	global_store_dwordx4 v[6:7], v[10:13], off
	v_add_co_u32_e32 v6, vcc, 0x18000, v22
	s_nop 1
	v_addc_co_u32_e32 v7, vcc, 0, v23, vcc
	global_store_dwordx4 v[6:7], v[2:5], off
	s_waitcnt lgkmcnt(0)
	s_branch .LBB0_18

.LBB0_231:
	s_or_b64 exec, exec, s[8:9]
	s_lshl_b32 s6, s76, 9
	s_add_u32 s28, s10, 0x2a012000
	s_addc_u32 s29, s11, 0
	s_mul_i32 s9, s76, 0x880000
	s_mul_hi_u32 s8, s76, 0x880000
	s_add_u32 s9, s10, s9
	s_addc_u32 s8, s11, s8
	s_add_u32 s34, s9, 0x2a812000
	s_addc_u32 s35, s8, 0
	s_add_u32 s8, s14, 0x6000000
	s_addc_u32 s9, s15, 0
	s_lshl_b32 s23, s33, 2
	s_add_i32 s23, s23, 0
	s_mov_b32 s7, s50
	v_lshl_add_u32 v3, v189, 2, s23
	s_lshl_b32 s23, s22, 8
	s_and_b32 s33, s23, 0x100
	s_lshl_b64 s[6:7], s[6:7], 2
	s_cmp_lt_u32 s22, 2
	v_lshrrev_b32_e32 v0, 4, v0
	s_cselect_b64 s[22:23], -1, 0
	s_waitcnt lgkmcnt(0)
	s_barrier
	v_add_u32_e32 v3, 0x2000, v3
	s_and_b64 s[26:27], s[22:23], exec
	v_bfrev_b32_e32 v0, v0
	ds_read2_b32 v[154:155], v3 offset1:16
	ds_read2_b32 v[152:153], v3 offset0:32 offset1:48
	ds_read2_b32 v[150:151], v3 offset0:128 offset1:144
	ds_read2_b32 v[148:149], v3 offset0:160 offset1:176
	v_lshl_or_b32 v3, v191, 2, s33
	s_cselect_b32 s18, s18, s20
	v_lshrrev_b32_e32 v0, 27, v0
	v_or_b32_e32 v3, s30, v3
	s_cselect_b32 s19, s19, s21
	s_cselect_b32 s20, s28, s34
	s_cselect_b32 s21, s29, s35
	s_add_u32 s18, s18, s6
	v_or_b32_e32 v0, s30, v0
	s_addc_u32 s19, s19, s7
	v_or_b32_e32 v140, s33, v0
	v_lshlrev_b32_e32 v0, 2, v3
	global_load_dwordx4 v[136:139], v0, s[18:19]
	global_load_dwordx4 v[132:135], v0, s[18:19] offset:64
	v_lshlrev_b32_e32 v140, 1, v140
	v_mov_b32_e32 v141, v1
	v_lshl_add_u64 v[158:159], s[20:21], 0, v[140:141]
	s_waitcnt lgkmcnt(3)
	v_pk_mul_f32 v[140:141], v[66:67], v[154:155] op_sel_hi:[1,0]
	v_pk_mul_f32 v[144:145], v[64:65], v[154:155] op_sel_hi:[1,0]
	v_pk_mul_f32 v[156:157], v[60:61], v[154:155] op_sel_hi:[1,0]
	v_ashrrev_i32_e32 v3, 31, v2
	s_or_b64 s[6:7], s[22:23], s[24:25]
	s_ashr_i32 s20, s31, 7
	s_and_b32 s20, s20, -2
	s_and_b64 vcc, exec, s[6:7]
	s_waitcnt vmcnt(1)
	v_pk_mul_f32 v[142:143], v[140:141], v[138:139]
	v_pk_mul_f32 v[140:141], v[144:145], v[136:137]
	v_pk_mul_f32 v[144:145], v[62:63], v[154:155] op_sel_hi:[1,0]
	v_cvt_pk_bf16_f32 v162, v140, v141
	v_cvt_pk_bf16_f32 v163, v142, v143
	s_waitcnt vmcnt(0)
	v_pk_mul_f32 v[146:147], v[144:145], v[134:135]
	v_pk_mul_f32 v[144:145], v[156:157], v[132:133]
	v_lshlrev_b64 v[156:157], 10, v[2:3]
	v_cvt_pk_bf16_f32 v164, v144, v145
	v_cvt_pk_bf16_f32 v165, v146, v147
	v_lshl_add_u64 v[160:161], v[158:159], 0, v[156:157]
	s_nop 1
	v_permlane16_swap_b32 v162, v164
	v_permlane16_swap_b32 v163, v165
	s_nop 1
	v_lshlrev_b32_e32 v3, 11, v2
	global_store_dwordx4 v[160:161], v[162:165], off
	s_nop 1
	v_and_b32_e32 v162, 0x67800, v3
	s_cbranch_vccnz .LBB0_233
	s_or_b32 s22, s20, s76
	s_ashr_i32 s23, s22, 31
	s_lshl_b64 s[22:23], s[22:23], 19
	s_add_u32 s22, s8, s22
	s_addc_u32 s23, s9, s23
	v_mov_b32_e32 v163, v1
	v_lshl_add_u64 v[156:157], s[22:23], 0, v[162:163]
	v_lshl_add_u64 v[156:157], v[156:157], 0, v[0:1]
	global_store_dwordx4 v[156:157], v[140:143], off
	global_store_dwordx4 v[156:157], v[144:147], off offset:64
.LBB0_233:
	v_or_b32_e32 v156, 16, v2
	s_nop 0
	v_mov_b32_e32 v144, v155
	s_xor_b64 s[22:23], s[6:7], -1
	v_pk_mul_f32 v[140:141], v[58:59], v[144:145] op_sel_hi:[1,0]
	v_pk_mul_f32 v[146:147], v[56:57], v[144:145] op_sel_hi:[1,0]
	v_ashrrev_i32_e32 v157, 31, v156
	v_cndmask_b32_e64 v3, 0, 1, s[22:23]
	v_pk_mul_f32 v[142:143], v[140:141], v[138:139]
	v_pk_mul_f32 v[140:141], v[146:147], v[136:137]
	v_pk_mul_f32 v[146:147], v[54:55], v[144:145] op_sel_hi:[1,0]
	v_pk_mul_f32 v[144:145], v[52:53], v[144:145] op_sel_hi:[1,0]
	v_lshlrev_b64 v[168:169], 10, v[156:157]
	v_cmp_ne_u32_e64 s[6:7], 1, v3
	v_lshlrev_b32_e32 v3, 11, v156
	v_pk_mul_f32 v[146:147], v[146:147], v[134:135]
	v_pk_mul_f32 v[144:145], v[144:145], v[132:133]
	v_cvt_pk_bf16_f32 v164, v140, v141
	v_cvt_pk_bf16_f32 v165, v142, v143
	v_lshl_add_u64 v[176:177], v[158:159], 0, v[168:169]
	v_cvt_pk_bf16_f32 v166, v144, v145
	v_cvt_pk_bf16_f32 v167, v146, v147
	s_andn2_b64 vcc, exec, s[22:23]
	v_and_b32_e32 v168, 0x6f800, v3
	s_nop 1
	v_permlane16_swap_b32 v164, v166
	v_permlane16_swap_b32 v165, v167
	s_nop 1
	global_store_dwordx4 v[176:177], v[164:167], off
	s_cbranch_vccnz .LBB0_235
	s_or_b32 s22, s20, s76
	s_ashr_i32 s23, s22, 31
	s_lshl_b64 s[22:23], s[22:23], 19
	s_add_u32 s22, s8, s22
	s_addc_u32 s23, s9, s23
	v_mov_b32_e32 v169, v1
	v_lshl_add_u64 v[156:157], s[22:23], 0, v[168:169]
	v_lshl_add_u64 v[156:157], v[156:157], 0, v[0:1]
	global_store_dwordx4 v[156:157], v[140:143], off
	global_store_dwordx4 v[156:157], v[144:147], off offset:64
.LBB0_235:
	v_or_b32_e32 v156, 32, v2
	s_waitcnt lgkmcnt(2)
	v_pk_mul_f32 v[140:141], v[50:51], v[152:153] op_sel_hi:[1,0]
	v_pk_mul_f32 v[144:145], v[48:49], v[152:153] op_sel_hi:[1,0]
	v_pk_mul_f32 v[142:143], v[140:141], v[138:139]
	v_pk_mul_f32 v[140:141], v[144:145], v[136:137]
	v_pk_mul_f32 v[144:145], v[46:47], v[152:153] op_sel_hi:[1,0]
	v_pk_mul_f32 v[164:165], v[44:45], v[152:153] op_sel_hi:[1,0]
	v_ashrrev_i32_e32 v157, 31, v156
	v_pk_mul_f32 v[146:147], v[144:145], v[134:135]
	v_pk_mul_f32 v[144:145], v[164:165], v[132:133]
	v_cvt_pk_bf16_f32 v164, v140, v141
	v_cvt_pk_bf16_f32 v165, v142, v143
	v_lshlrev_b64 v[170:171], 10, v[156:157]
	v_cvt_pk_bf16_f32 v166, v144, v145
	v_cvt_pk_bf16_f32 v167, v146, v147
	v_lshl_add_u64 v[178:179], v[158:159], 0, v[170:171]
	s_nop 1
	v_permlane16_swap_b32 v164, v166
	v_permlane16_swap_b32 v165, v167
	s_nop 1
	v_lshlrev_b32_e32 v3, 11, v156
	global_store_dwordx4 v[178:179], v[164:167], off
	s_and_b64 vcc, exec, s[6:7]
	s_nop 0
	v_and_b32_e32 v166, 0x77800, v3
	s_cbranch_vccnz .LBB0_237
	s_or_b32 s22, s20, s76
	s_ashr_i32 s23, s22, 31
	s_lshl_b64 s[22:23], s[22:23], 19
	s_add_u32 s22, s8, s22
	s_addc_u32 s23, s9, s23
	v_mov_b32_e32 v167, v1
	v_lshl_add_u64 v[156:157], s[22:23], 0, v[166:167]
	v_lshl_add_u64 v[156:157], v[156:157], 0, v[0:1]
	global_store_dwordx4 v[156:157], v[140:143], off
	global_store_dwordx4 v[156:157], v[144:147], off offset:64
.LBB0_237:
	v_or_b32_e32 v156, 48, v2
	s_nop 0
	v_mov_b32_e32 v144, v153
	v_pk_mul_f32 v[140:141], v[42:43], v[144:145] op_sel_hi:[1,0]
	v_pk_mul_f32 v[146:147], v[40:41], v[144:145] op_sel_hi:[1,0]
	v_ashrrev_i32_e32 v157, 31, v156
	v_pk_mul_f32 v[142:143], v[140:141], v[138:139]
	v_pk_mul_f32 v[140:141], v[146:147], v[136:137]
	v_pk_mul_f32 v[146:147], v[38:39], v[144:145] op_sel_hi:[1,0]
	v_pk_mul_f32 v[144:145], v[36:37], v[144:145] op_sel_hi:[1,0]
	v_lshlrev_b64 v[164:165], 10, v[156:157]
	v_lshlrev_b32_e32 v3, 11, v156
	v_pk_mul_f32 v[146:147], v[146:147], v[134:135]
	v_pk_mul_f32 v[144:145], v[144:145], v[132:133]
	v_cvt_pk_bf16_f32 v170, v140, v141
	v_cvt_pk_bf16_f32 v171, v142, v143
	v_lshl_add_u64 v[180:181], v[158:159], 0, v[164:165]
	v_cvt_pk_bf16_f32 v172, v144, v145
	v_cvt_pk_bf16_f32 v173, v146, v147
	s_and_b64 vcc, exec, s[6:7]
	v_and_b32_e32 v164, 0x7f800, v3
	s_nop 1
	v_permlane16_swap_b32 v170, v172
	v_permlane16_swap_b32 v171, v173
	s_nop 1
	global_store_dwordx4 v[180:181], v[170:173], off
	s_cbranch_vccnz .LBB0_239
	s_or_b32 s22, s20, s76
	s_ashr_i32 s23, s22, 31
	s_lshl_b64 s[22:23], s[22:23], 19
	s_add_u32 s22, s8, s22
	s_addc_u32 s23, s9, s23
	v_mov_b32_e32 v165, v1
	v_lshl_add_u64 v[156:157], s[22:23], 0, v[164:165]
	v_lshl_add_u64 v[156:157], v[156:157], 0, v[0:1]
	global_store_dwordx4 v[156:157], v[140:143], off
	global_store_dwordx4 v[156:157], v[144:147], off offset:64
.LBB0_239:
	v_add_u32_e32 v174, 0x80, v2
	s_waitcnt lgkmcnt(1)
	v_pk_mul_f32 v[140:141], v[34:35], v[150:151] op_sel_hi:[1,0]
	v_pk_mul_f32 v[144:145], v[32:33], v[150:151] op_sel_hi:[1,0]
	v_ashrrev_i32_e32 v3, 7, v174
	v_pk_mul_f32 v[142:143], v[140:141], v[138:139]
	v_pk_mul_f32 v[140:141], v[144:145], v[136:137]
	v_pk_mul_f32 v[144:145], v[30:31], v[150:151] op_sel_hi:[1,0]
	v_pk_mul_f32 v[156:157], v[28:29], v[150:151] op_sel_hi:[1,0]
	v_ashrrev_i32_e32 v175, 31, v174
	v_and_b32_e32 v3, -2, v3
	v_pk_mul_f32 v[146:147], v[144:145], v[134:135]
	v_pk_mul_f32 v[144:145], v[156:157], v[132:133]
	v_lshlrev_b64 v[156:157], 10, v[174:175]
	v_lshl_add_u64 v[182:183], v[158:159], 0, v[156:157]
	v_or_b32_e32 v156, s76, v3
	v_lshlrev_b32_e32 v3, 11, v174
	v_cvt_pk_bf16_f32 v170, v140, v141
	v_cvt_pk_bf16_f32 v171, v142, v143
	v_cvt_pk_bf16_f32 v172, v144, v145
	v_cvt_pk_bf16_f32 v173, v146, v147
	s_and_b64 vcc, exec, s[6:7]
	v_ashrrev_i32_e32 v157, 31, v156
	v_and_b32_e32 v174, 0x67800, v3
	s_nop 1
	v_permlane16_swap_b32 v170, v172
	v_permlane16_swap_b32 v171, v173
	s_nop 1
	global_store_dwordx4 v[182:183], v[170:173], off
	s_cbranch_vccnz .LBB0_241
	s_nop 0
	v_lshlrev_b64 v[170:171], 19, v[156:157]
	v_lshl_add_u64 v[170:171], s[8:9], 0, v[170:171]
	v_mov_b32_e32 v175, v1
	v_lshl_add_u64 v[170:171], v[170:171], 0, v[174:175]
	v_lshl_add_u64 v[170:171], v[170:171], 0, v[0:1]
	global_store_dwordx4 v[170:171], v[140:143], off
	global_store_dwordx4 v[170:171], v[144:147], off offset:64
.LBB0_241:
	s_nop 1
	v_mov_b32_e32 v144, v151
	v_add_u32_e32 v186, 0x90, v2
	v_pk_mul_f32 v[140:141], v[26:27], v[144:145] op_sel_hi:[1,0]
	v_pk_mul_f32 v[146:147], v[24:25], v[144:145] op_sel_hi:[1,0]
	v_pk_mul_f32 v[142:143], v[138:139], v[140:141]
	v_pk_mul_f32 v[140:141], v[136:137], v[146:147]
	v_pk_mul_f32 v[146:147], v[22:23], v[144:145] op_sel_hi:[1,0]
	v_pk_mul_f32 v[144:145], v[20:21], v[144:145] op_sel_hi:[1,0]
	v_ashrrev_i32_e32 v187, 31, v186
	v_pk_mul_f32 v[146:147], v[146:147], v[134:135]
	v_pk_mul_f32 v[144:145], v[144:145], v[132:133]
	v_cvt_pk_bf16_f32 v170, v140, v141
	v_cvt_pk_bf16_f32 v171, v142, v143
	v_lshlrev_b64 v[184:185], 10, v[186:187]
	v_cvt_pk_bf16_f32 v172, v144, v145
	v_cvt_pk_bf16_f32 v173, v146, v147
	v_lshl_add_u64 v[184:185], v[158:159], 0, v[184:185]
	s_nop 1
	v_permlane16_swap_b32 v170, v172
	v_permlane16_swap_b32 v171, v173
	s_nop 1
	v_lshlrev_b32_e32 v3, 11, v186
	global_store_dwordx4 v[184:185], v[170:173], off
	s_and_b64 vcc, exec, s[6:7]
	s_nop 0
	v_and_b32_e32 v172, 0x6f800, v3
	s_cbranch_vccnz .LBB0_243
	v_lshlrev_b64 v[170:171], 19, v[156:157]
	v_lshl_add_u64 v[170:171], s[8:9], 0, v[170:171]
	v_mov_b32_e32 v173, v1
	v_lshl_add_u64 v[170:171], v[170:171], 0, v[172:173]
	v_lshl_add_u64 v[170:171], v[170:171], 0, v[0:1]
	global_store_dwordx4 v[170:171], v[140:143], off
	global_store_dwordx4 v[170:171], v[144:147], off offset:64
.LBB0_243:
	v_add_u32_e32 v170, 0xa0, v2
	s_waitcnt lgkmcnt(0)
	v_pk_mul_f32 v[140:141], v[18:19], v[148:149] op_sel_hi:[1,0]
	v_pk_mul_f32 v[144:145], v[16:17], v[148:149] op_sel_hi:[1,0]
	v_pk_mul_f32 v[142:143], v[138:139], v[140:141]
	v_pk_mul_f32 v[140:141], v[136:137], v[144:145]
	v_pk_mul_f32 v[144:145], v[14:15], v[148:149] op_sel_hi:[1,0]
	v_pk_mul_f32 v[186:187], v[12:13], v[148:149] op_sel_hi:[1,0]
	v_ashrrev_i32_e32 v171, 31, v170
	v_pk_mul_f32 v[146:147], v[134:135], v[144:145]
	v_pk_mul_f32 v[144:145], v[132:133], v[186:187]
	v_lshlrev_b64 v[186:187], 10, v[170:171]
	v_lshlrev_b32_e32 v3, 11, v170
	v_cvt_pk_bf16_f32 v192, v140, v141
	v_cvt_pk_bf16_f32 v193, v142, v143
	v_cvt_pk_bf16_f32 v194, v144, v145
	v_cvt_pk_bf16_f32 v195, v146, v147
	v_lshl_add_u64 v[186:187], v[158:159], 0, v[186:187]
	s_and_b64 vcc, exec, s[6:7]
	v_and_b32_e32 v170, 0x77800, v3
	s_nop 1
	v_permlane16_swap_b32 v192, v194
	v_permlane16_swap_b32 v193, v195
	s_nop 1
	global_store_dwordx4 v[186:187], v[192:195], off
	s_cbranch_vccnz .LBB0_245
	s_nop 0
	v_lshlrev_b64 v[192:193], 19, v[156:157]
	v_lshl_add_u64 v[192:193], s[8:9], 0, v[192:193]
	v_mov_b32_e32 v171, v1
	v_lshl_add_u64 v[192:193], v[192:193], 0, v[170:171]
	v_lshl_add_u64 v[192:193], v[192:193], 0, v[0:1]
	global_store_dwordx4 v[192:193], v[140:143], off
	global_store_dwordx4 v[192:193], v[144:147], off offset:64
.LBB0_245:
	s_nop 0
	v_mov_b32_e32 v142, v149
	v_add_u32_e32 v140, 0xb0, v2
	v_pk_mul_f32 v[144:145], v[10:11], v[142:143] op_sel_hi:[1,0]
	v_pk_mul_f32 v[146:147], v[8:9], v[142:143] op_sel_hi:[1,0]
	v_pk_mul_f32 v[138:139], v[138:139], v[144:145]
	v_pk_mul_f32 v[144:145], v[6:7], v[142:143] op_sel_hi:[1,0]
	v_pk_mul_f32 v[142:143], v[4:5], v[142:143] op_sel_hi:[1,0]
	v_ashrrev_i32_e32 v141, 31, v140
	v_pk_mul_f32 v[132:133], v[132:133], v[142:143]
	v_lshlrev_b64 v[142:143], 10, v[140:141]
	v_lshlrev_b32_e32 v3, 11, v140
	v_pk_mul_f32 v[136:137], v[136:137], v[146:147]
	v_pk_mul_f32 v[134:135], v[134:135], v[144:145]
	v_cvt_pk_bf16_f32 v144, v136, v137
	v_cvt_pk_bf16_f32 v145, v138, v139
	v_cvt_pk_bf16_f32 v146, v132, v133
	v_lshl_add_u64 v[142:143], v[158:159], 0, v[142:143]
	v_cvt_pk_bf16_f32 v147, v134, v135
	s_and_b64 vcc, exec, s[6:7]
	v_and_b32_e32 v140, 0x7f800, v3
	s_nop 1
	v_permlane16_swap_b32 v144, v146
	v_permlane16_swap_b32 v145, v147
	s_nop 1
	global_store_dwordx4 v[142:143], v[144:147], off
	s_cbranch_vccnz .LBB0_247
	s_nop 0
	v_lshlrev_b64 v[144:145], 19, v[156:157]
	v_lshl_add_u64 v[144:145], s[8:9], 0, v[144:145]
	v_mov_b32_e32 v141, v1
	v_lshl_add_u64 v[144:145], v[144:145], 0, v[140:141]
	v_lshl_add_u64 v[144:145], v[144:145], 0, v[0:1]
	global_store_dwordx4 v[144:145], v[136:139], off
	global_store_dwordx4 v[144:145], v[132:135], off offset:64
.LBB0_247:
	s_nop 1
	v_lshl_add_u64 v[132:133], s[18:19], 0, v[0:1]
	global_load_dwordx4 v[136:139], v[132:133], off offset:512
	s_nop 0
	global_load_dwordx4 v[132:135], v[132:133], off offset:576
	v_mov_b32_e32 v144, v154
	v_mov_b32_e32 v145, v154
	v_mov_b32_e32 v146, v154
	v_mov_b32_e32 v147, v154
	v_pk_mul_f32 v[130:131], v[130:131], v[146:147]
	v_pk_mul_f32 v[128:129], v[128:129], v[144:145]
	v_pk_mul_f32 v[146:147], v[126:127], v[146:147]
	v_pk_mul_f32 v[144:145], v[124:125], v[144:145]
	s_and_b64 vcc, exec, s[6:7]
	s_waitcnt vmcnt(1)
	v_pk_mul_f32 v[126:127], v[130:131], v[138:139]
	v_pk_mul_f32 v[124:125], v[128:129], v[136:137]
	s_waitcnt vmcnt(0)
	v_pk_mul_f32 v[130:131], v[146:147], v[134:135]
	v_pk_mul_f32 v[128:129], v[144:145], v[132:133]
	v_cvt_pk_bf16_f32 v144, v124, v125
	v_cvt_pk_bf16_f32 v145, v126, v127
	s_nop 0
	v_cvt_pk_bf16_f32 v146, v128, v129
	v_cvt_pk_bf16_f32 v147, v130, v131
	s_nop 0
	s_nop 1
	v_permlane16_swap_b32 v144, v146
	v_permlane16_swap_b32 v145, v147
	s_nop 1
	global_store_dwordx4 v[160:161], v[144:147], off offset:256
	s_cbranch_vccnz .LBB0_249
	s_or_b32 s18, s20, s76
	s_ashr_i32 s19, s18, 31
	s_lshl_b64 s[18:19], s[18:19], 19
	s_add_u32 s18, s8, s18
	s_addc_u32 s19, s9, s19
	v_mov_b32_e32 v163, v1
	v_lshl_add_u64 v[144:145], s[18:19], 0, v[162:163]
	v_lshl_add_u64 v[144:145], v[144:145], 0, v[0:1]
	global_store_dwordx4 v[144:145], v[124:127], off offset:512
	global_store_dwordx4 v[144:145], v[128:131], off offset:576
.LBB0_249:
	v_mov_b32_e32 v154, v155
	v_mov_b32_e32 v124, v155
	v_mov_b32_e32 v125, v155
	v_pk_mul_f32 v[122:123], v[122:123], v[124:125]
	v_pk_mul_f32 v[120:121], v[120:121], v[154:155]
	v_pk_mul_f32 v[118:119], v[118:119], v[124:125]
	v_pk_mul_f32 v[116:117], v[116:117], v[154:155]
	v_pk_mul_f32 v[122:123], v[122:123], v[138:139]
	v_pk_mul_f32 v[120:121], v[120:121], v[136:137]
	v_pk_mul_f32 v[118:119], v[118:119], v[134:135]
	v_pk_mul_f32 v[116:117], v[116:117], v[132:133]
	v_cvt_pk_bf16_f32 v124, v120, v121
	v_cvt_pk_bf16_f32 v125, v122, v123
	s_and_b64 vcc, exec, s[6:7]
	v_cvt_pk_bf16_f32 v126, v116, v117
	v_cvt_pk_bf16_f32 v127, v118, v119
	s_nop 0
	s_nop 1
	v_permlane16_swap_b32 v124, v126
	v_permlane16_swap_b32 v125, v127
	s_nop 1
	global_store_dwordx4 v[176:177], v[124:127], off offset:256
	s_cbranch_vccnz .LBB0_251
	s_or_b32 s18, s20, s76
	s_ashr_i32 s19, s18, 31
	s_lshl_b64 s[18:19], s[18:19], 19
	s_add_u32 s18, s8, s18
	s_addc_u32 s19, s9, s19
	v_mov_b32_e32 v169, v1
	v_lshl_add_u64 v[124:125], s[18:19], 0, v[168:169]
	v_lshl_add_u64 v[124:125], v[124:125], 0, v[0:1]
	global_store_dwordx4 v[124:125], v[120:123], off offset:512
	global_store_dwordx4 v[124:125], v[116:119], off offset:576
.LBB0_251:
	s_nop 1
	v_mov_b32_e32 v116, v152
	v_mov_b32_e32 v117, v152
	v_mov_b32_e32 v118, v152
	v_mov_b32_e32 v119, v152
	v_pk_mul_f32 v[114:115], v[114:115], v[118:119]
	v_pk_mul_f32 v[112:113], v[112:113], v[116:117]
	v_pk_mul_f32 v[110:111], v[110:111], v[118:119]
	v_pk_mul_f32 v[108:109], v[108:109], v[116:117]
	v_pk_mul_f32 v[114:115], v[114:115], v[138:139]
	v_pk_mul_f32 v[112:113], v[112:113], v[136:137]
	v_pk_mul_f32 v[110:111], v[110:111], v[134:135]
	v_pk_mul_f32 v[108:109], v[108:109], v[132:133]
	v_cvt_pk_bf16_f32 v116, v112, v113
	v_cvt_pk_bf16_f32 v117, v114, v115
	s_and_b64 vcc, exec, s[6:7]
	v_cvt_pk_bf16_f32 v118, v108, v109
	v_cvt_pk_bf16_f32 v119, v110, v111
	s_nop 0
	s_nop 1
	v_permlane16_swap_b32 v116, v118
	v_permlane16_swap_b32 v117, v119
	s_nop 1
	global_store_dwordx4 v[178:179], v[116:119], off offset:256
	s_cbranch_vccnz .LBB0_253
	s_or_b32 s18, s20, s76
	s_ashr_i32 s19, s18, 31
	s_lshl_b64 s[18:19], s[18:19], 19
	s_add_u32 s18, s8, s18
	s_addc_u32 s19, s9, s19
	v_mov_b32_e32 v167, v1
	v_lshl_add_u64 v[116:117], s[18:19], 0, v[166:167]
	v_lshl_add_u64 v[116:117], v[116:117], 0, v[0:1]
	global_store_dwordx4 v[116:117], v[112:115], off offset:512
	global_store_dwordx4 v[116:117], v[108:111], off offset:576
.LBB0_253:
	v_mov_b32_e32 v152, v153
	s_nop 0
	v_mov_b32_e32 v108, v153
	v_mov_b32_e32 v109, v153
	v_pk_mul_f32 v[106:107], v[106:107], v[108:109]
	v_pk_mul_f32 v[104:105], v[104:105], v[152:153]
	v_pk_mul_f32 v[102:103], v[102:103], v[108:109]
	v_pk_mul_f32 v[100:101], v[100:101], v[152:153]
	v_pk_mul_f32 v[106:107], v[106:107], v[138:139]
	v_pk_mul_f32 v[104:105], v[104:105], v[136:137]
	v_pk_mul_f32 v[102:103], v[102:103], v[134:135]
	v_pk_mul_f32 v[100:101], v[100:101], v[132:133]
	v_cvt_pk_bf16_f32 v108, v104, v105
	v_cvt_pk_bf16_f32 v109, v106, v107
	s_and_b64 vcc, exec, s[6:7]
	v_cvt_pk_bf16_f32 v110, v100, v101
	v_cvt_pk_bf16_f32 v111, v102, v103
	s_nop 0
	s_nop 1
	v_permlane16_swap_b32 v108, v110
	v_permlane16_swap_b32 v109, v111
	s_nop 1
	global_store_dwordx4 v[180:181], v[108:111], off offset:256
	s_cbranch_vccnz .LBB0_255
	s_or_b32 s18, s20, s76
	s_ashr_i32 s19, s18, 31
	s_lshl_b64 s[18:19], s[18:19], 19
	s_add_u32 s18, s8, s18
	s_addc_u32 s19, s9, s19
	v_mov_b32_e32 v165, v1
	v_lshl_add_u64 v[108:109], s[18:19], 0, v[164:165]
	v_lshl_add_u64 v[108:109], v[108:109], 0, v[0:1]
	global_store_dwordx4 v[108:109], v[104:107], off offset:512
	global_store_dwordx4 v[108:109], v[100:103], off offset:576
.LBB0_255:
	s_nop 1
	v_mov_b32_e32 v100, v150
	v_mov_b32_e32 v101, v150
	v_mov_b32_e32 v102, v150
	v_mov_b32_e32 v103, v150
	v_pk_mul_f32 v[98:99], v[98:99], v[102:103]
	v_pk_mul_f32 v[96:97], v[96:97], v[100:101]
	v_pk_mul_f32 v[94:95], v[94:95], v[102:103]
	v_pk_mul_f32 v[92:93], v[92:93], v[100:101]
	v_pk_mul_f32 v[98:99], v[98:99], v[138:139]
	v_pk_mul_f32 v[96:97], v[96:97], v[136:137]
	v_pk_mul_f32 v[94:95], v[94:95], v[134:135]
	v_pk_mul_f32 v[92:93], v[92:93], v[132:133]
	v_cvt_pk_bf16_f32 v100, v96, v97
	v_cvt_pk_bf16_f32 v101, v98, v99
	s_and_b64 vcc, exec, s[6:7]
	v_cvt_pk_bf16_f32 v102, v92, v93
	v_cvt_pk_bf16_f32 v103, v94, v95
	s_nop 0
	s_nop 1
	v_permlane16_swap_b32 v100, v102
	v_permlane16_swap_b32 v101, v103
	s_nop 1
	global_store_dwordx4 v[182:183], v[100:103], off offset:256
	s_cbranch_vccnz .LBB0_257
	s_nop 0
	v_lshlrev_b64 v[100:101], 19, v[156:157]
	v_lshl_add_u64 v[100:101], s[8:9], 0, v[100:101]
	v_mov_b32_e32 v175, v1
	v_lshl_add_u64 v[100:101], v[100:101], 0, v[174:175]
	v_lshl_add_u64 v[100:101], v[100:101], 0, v[0:1]
	global_store_dwordx4 v[100:101], v[96:99], off offset:512
	global_store_dwordx4 v[100:101], v[92:95], off offset:576
.LBB0_257:
	v_mov_b32_e32 v150, v151
	s_nop 0
	v_mov_b32_e32 v92, v151
	v_mov_b32_e32 v93, v151
	v_pk_mul_f32 v[90:91], v[90:91], v[92:93]
	v_pk_mul_f32 v[88:89], v[88:89], v[150:151]
	v_pk_mul_f32 v[86:87], v[86:87], v[92:93]
	v_pk_mul_f32 v[84:85], v[84:85], v[150:151]
	v_pk_mul_f32 v[90:91], v[90:91], v[138:139]
	v_pk_mul_f32 v[88:89], v[88:89], v[136:137]
	v_pk_mul_f32 v[86:87], v[86:87], v[134:135]
	v_pk_mul_f32 v[84:85], v[84:85], v[132:133]
	v_cvt_pk_bf16_f32 v92, v88, v89
	v_cvt_pk_bf16_f32 v93, v90, v91
	s_and_b64 vcc, exec, s[6:7]
	v_cvt_pk_bf16_f32 v94, v84, v85
	v_cvt_pk_bf16_f32 v95, v86, v87
	s_nop 0
	s_nop 1
	v_permlane16_swap_b32 v92, v94
	v_permlane16_swap_b32 v93, v95
	s_nop 1
	global_store_dwordx4 v[184:185], v[92:95], off offset:256
	s_cbranch_vccnz .LBB0_259
	s_nop 0
	v_lshlrev_b64 v[92:93], 19, v[156:157]
	v_lshl_add_u64 v[92:93], s[8:9], 0, v[92:93]
	v_mov_b32_e32 v173, v1
	v_lshl_add_u64 v[92:93], v[92:93], 0, v[172:173]
	v_lshl_add_u64 v[92:93], v[92:93], 0, v[0:1]
	global_store_dwordx4 v[92:93], v[88:91], off offset:512
	global_store_dwordx4 v[92:93], v[84:87], off offset:576
.LBB0_259:
	s_nop 1
	v_mov_b32_e32 v84, v148
	v_mov_b32_e32 v85, v148
	v_mov_b32_e32 v86, v148
	v_mov_b32_e32 v87, v148
	v_pk_mul_f32 v[82:83], v[82:83], v[86:87]
	v_pk_mul_f32 v[80:81], v[80:81], v[84:85]
	v_pk_mul_f32 v[78:79], v[78:79], v[86:87]
	v_pk_mul_f32 v[76:77], v[76:77], v[84:85]
	v_pk_mul_f32 v[82:83], v[82:83], v[138:139]
	v_pk_mul_f32 v[80:81], v[80:81], v[136:137]
	v_pk_mul_f32 v[78:79], v[78:79], v[134:135]
	v_pk_mul_f32 v[76:77], v[76:77], v[132:133]
	v_cvt_pk_bf16_f32 v84, v80, v81
	v_cvt_pk_bf16_f32 v85, v82, v83
	s_and_b64 vcc, exec, s[6:7]
	v_cvt_pk_bf16_f32 v86, v76, v77
	v_cvt_pk_bf16_f32 v87, v78, v79
	s_nop 0
	s_nop 1
	v_permlane16_swap_b32 v84, v86
	v_permlane16_swap_b32 v85, v87
	s_nop 1
	global_store_dwordx4 v[186:187], v[84:87], off offset:256
	s_cbranch_vccnz .LBB0_261
	s_nop 0
	v_lshlrev_b64 v[84:85], 19, v[156:157]
	v_lshl_add_u64 v[84:85], s[8:9], 0, v[84:85]
	v_mov_b32_e32 v171, v1
	v_lshl_add_u64 v[84:85], v[84:85], 0, v[170:171]
	v_lshl_add_u64 v[84:85], v[84:85], 0, v[0:1]
	global_store_dwordx4 v[84:85], v[80:83], off offset:512
	global_store_dwordx4 v[84:85], v[76:79], off offset:576
.LBB0_261:
	v_mov_b32_e32 v148, v149
	s_nop 0
	v_mov_b32_e32 v76, v149
	v_mov_b32_e32 v77, v149
	v_pk_mul_f32 v[74:75], v[74:75], v[76:77]
	v_pk_mul_f32 v[72:73], v[72:73], v[148:149]
	v_pk_mul_f32 v[70:71], v[70:71], v[76:77]
	v_pk_mul_f32 v[68:69], v[68:69], v[148:149]
	v_pk_mul_f32 v[74:75], v[74:75], v[138:139]
	v_pk_mul_f32 v[72:73], v[72:73], v[136:137]
	v_pk_mul_f32 v[70:71], v[70:71], v[134:135]
	v_pk_mul_f32 v[68:69], v[68:69], v[132:133]
	v_cvt_pk_bf16_f32 v76, v72, v73
	v_cvt_pk_bf16_f32 v77, v74, v75
	s_and_b64 vcc, exec, s[6:7]
	v_cvt_pk_bf16_f32 v78, v68, v69
	v_cvt_pk_bf16_f32 v79, v70, v71
	s_nop 0
	s_nop 1
	v_permlane16_swap_b32 v76, v78
	v_permlane16_swap_b32 v77, v79
	s_nop 1
	global_store_dwordx4 v[142:143], v[76:79], off offset:256
	s_cbranch_vccnz .LBB0_263
	s_nop 0
	v_lshlrev_b64 v[76:77], 19, v[156:157]
	v_lshl_add_u64 v[76:77], s[8:9], 0, v[76:77]
	v_mov_b32_e32 v141, v1
	v_lshl_add_u64 v[76:77], v[76:77], 0, v[140:141]
	v_lshl_add_u64 v[76:77], v[76:77], 0, v[0:1]
	global_store_dwordx4 v[76:77], v[72:75], off offset:512
	global_store_dwordx4 v[76:77], v[68:71], off offset:576

.LBB0_264:
	s_and_b64 vcc, exec, s[6:7]
	s_cbranch_vccz .LBB0_299
	s_cmp_gt_u32 s83, 1
	s_cbranch_scc1 .LBB0_299
	s_add_u32 s18, s10, 0x610000
	s_addc_u32 s19, s11, 0
	s_add_u32 s20, s14, 0x7000000
	s_addc_u32 s21, s15, 0
	s_cmp_eq_u32 s83, 0
	v_lshlrev_b32_e32 v3, 2, v191
	s_cselect_b64 s[6:7], -1, 0
	s_ashr_i32 s8, s31, 7
	s_and_b32 s24, s8, -2
	s_mov_b64 s[8:9], -1
	s_and_b64 vcc, exec, s[16:17]
	v_lshlrev_b32_e32 v68, 2, v3
	s_cbranch_vccz .LBB0_268
	s_or_b32 s8, s24, s76
	s_ashr_i32 s9, s8, 31
	s_lshl_b64 s[8:9], s[8:9], 16
	s_add_u32 s8, s20, s8
	v_lshlrev_b32_e32 v0, 8, v2
	s_addc_u32 s9, s21, s9
	v_and_b32_e32 v0, 0xcf00, v0
	v_lshl_add_u64 v[70:71], s[8:9], 0, v[0:1]
	s_lshl_b32 s8, s30, 2
	s_mov_b32 s9, s50
	v_lshl_add_u64 v[70:71], v[70:71], 0, s[8:9]
	v_mov_b32_e32 v69, v1
	v_lshl_add_u64 v[70:71], v[70:71], 0, v[68:69]
	global_store_dwordx4 v[70:71], v[64:67], off
	global_store_dwordx4 v[70:71], v[60:63], off offset:64
	s_mov_b64 s[8:9], 0

.LBB0_270:
	s_mul_i32 s9, s76, 0x110000
	s_mul_hi_u32 s8, s76, 0x110000
	s_add_u32 s9, s10, s9
	s_addc_u32 s8, s11, s8
	v_and_b32_e32 v0, 8, v3
	s_add_u32 s14, s9, 0x2b912000
	v_ashrrev_i32_e32 v3, 31, v2
	s_addc_u32 s15, s8, 0
	v_cvt_pk_bf16_f32 v64, v64, v65
	v_cvt_pk_bf16_f32 v65, v66, v67
	v_cvt_pk_bf16_f32 v66, v60, v61
	v_lshlrev_b64 v[60:61], 7, v[2:3]
	v_lshl_add_u64 v[60:61], s[14:15], 0, v[60:61]
	s_lshl_b32 s22, s30, 1
	s_mov_b32 s23, s50
	v_and_b32_e32 v69, 16, v190
	v_lshl_add_u64 v[60:61], v[60:61], 0, s[22:23]
	v_lshlrev_b32_e32 v0, 1, v0
	v_cvt_pk_bf16_f32 v67, v62, v63
	v_lshl_add_u64 v[62:63], v[60:61], 0, v[0:1]
	v_lshlrev_b32_e32 v60, 1, v69
	v_mov_b32_e32 v61, v1
	v_lshl_add_u64 v[62:63], v[62:63], 0, v[60:61]
	v_cndmask_b32_e64 v3, 0, 1, s[16:17]
	s_nop 1
	v_permlane16_swap_b32 v64, v66
	v_permlane16_swap_b32 v65, v67
	s_nop 1
	global_store_dwordx4 v[62:63], v[64:67], off
	v_or_b32_e32 v62, 16, v2
	v_cmp_ne_u32_e64 s[8:9], 1, v3
	s_andn2_b64 vcc, exec, s[16:17]
	s_mov_b64 s[16:17], -1
	s_cbranch_vccnz .LBB0_272
	s_or_b32 s16, s24, s76
	s_ashr_i32 s17, s16, 31
	s_lshl_b64 s[16:17], s[16:17], 16
	s_add_u32 s16, s20, s16
	v_lshlrev_b32_e32 v3, 8, v62
	s_addc_u32 s17, s21, s17
	v_and_b32_e32 v64, 0xdf00, v3
	v_mov_b32_e32 v65, v1
	v_lshl_add_u64 v[64:65], s[16:17], 0, v[64:65]
	s_lshl_b32 s16, s30, 2
	s_mov_b32 s17, s50
	v_lshl_add_u64 v[64:65], v[64:65], 0, s[16:17]
	v_mov_b32_e32 v69, v1
	v_lshl_add_u64 v[64:65], v[64:65], 0, v[68:69]
	s_mov_b64 s[16:17], 0
	global_store_dwordx4 v[64:65], v[56:59], off
	global_store_dwordx4 v[64:65], v[52:55], off offset:64

.LBB0_274:
	v_ashrrev_i32_e32 v63, 31, v62
	v_cvt_pk_bf16_f32 v56, v56, v57
	v_cvt_pk_bf16_f32 v57, v58, v59
	v_cvt_pk_bf16_f32 v58, v52, v53
	v_lshlrev_b64 v[52:53], 7, v[62:63]
	v_lshl_add_u64 v[52:53], s[14:15], 0, v[52:53]
	s_mov_b32 s23, s50
	v_lshl_add_u64 v[52:53], v[52:53], 0, s[22:23]
	v_lshl_add_u64 v[52:53], v[52:53], 0, v[0:1]
	v_mov_b32_e32 v61, v1
	v_cvt_pk_bf16_f32 v59, v54, v55
	v_lshl_add_u64 v[52:53], v[52:53], 0, v[60:61]
	s_nop 1
	v_permlane16_swap_b32 v56, v58
	v_permlane16_swap_b32 v57, v59
	s_nop 1
	global_store_dwordx4 v[52:53], v[56:59], off
	v_or_b32_e32 v52, 32, v2
	s_and_b64 vcc, exec, s[8:9]
	s_mov_b64 s[16:17], -1
	s_cbranch_vccnz .LBB0_276
	s_or_b32 s16, s24, s76
	s_ashr_i32 s17, s16, 31
	s_lshl_b64 s[16:17], s[16:17], 16
	s_add_u32 s16, s20, s16
	v_lshlrev_b32_e32 v53, 8, v52
	s_addc_u32 s17, s21, s17
	v_and_b32_e32 v54, 0xef00, v53
	v_mov_b32_e32 v55, v1
	v_lshl_add_u64 v[54:55], s[16:17], 0, v[54:55]
	s_lshl_b32 s16, s30, 2
	s_mov_b32 s17, s50
	v_lshl_add_u64 v[54:55], v[54:55], 0, s[16:17]
	v_mov_b32_e32 v69, v1
	v_lshl_add_u64 v[54:55], v[54:55], 0, v[68:69]
	s_mov_b64 s[16:17], 0
	global_store_dwordx4 v[54:55], v[48:51], off
	global_store_dwordx4 v[54:55], v[44:47], off offset:64

.LBB0_278:
	v_ashrrev_i32_e32 v53, 31, v52
	v_cvt_pk_bf16_f32 v48, v48, v49
	v_cvt_pk_bf16_f32 v49, v50, v51
	v_cvt_pk_bf16_f32 v50, v44, v45
	v_lshlrev_b64 v[44:45], 7, v[52:53]
	v_lshl_add_u64 v[44:45], s[14:15], 0, v[44:45]
	s_mov_b32 s23, s50
	v_lshl_add_u64 v[44:45], v[44:45], 0, s[22:23]
	v_lshl_add_u64 v[44:45], v[44:45], 0, v[0:1]
	v_mov_b32_e32 v61, v1
	v_cvt_pk_bf16_f32 v51, v46, v47
	v_lshl_add_u64 v[44:45], v[44:45], 0, v[60:61]
	s_nop 1
	v_permlane16_swap_b32 v48, v50
	v_permlane16_swap_b32 v49, v51
	s_nop 1
	global_store_dwordx4 v[44:45], v[48:51], off
	v_or_b32_e32 v44, 48, v2
	s_and_b64 vcc, exec, s[8:9]
	s_mov_b64 s[16:17], -1
	s_cbranch_vccnz .LBB0_280
	s_or_b32 s16, s24, s76
	s_ashr_i32 s17, s16, 31
	s_lshl_b64 s[16:17], s[16:17], 16
	s_add_u32 s16, s20, s16
	v_lshlrev_b32_e32 v45, 8, v44
	s_addc_u32 s17, s21, s17
	v_and_b32_e32 v46, 0xff00, v45
	v_mov_b32_e32 v47, v1
	v_lshl_add_u64 v[46:47], s[16:17], 0, v[46:47]
	s_lshl_b32 s16, s30, 2
	s_mov_b32 s17, s50
	v_lshl_add_u64 v[46:47], v[46:47], 0, s[16:17]
	v_mov_b32_e32 v69, v1
	v_lshl_add_u64 v[46:47], v[46:47], 0, v[68:69]
	s_mov_b64 s[16:17], 0
	global_store_dwordx4 v[46:47], v[40:43], off
	global_store_dwordx4 v[46:47], v[36:39], off offset:64

.LBB0_282:
	v_ashrrev_i32_e32 v45, 31, v44
	v_cvt_pk_bf16_f32 v40, v40, v41
	v_cvt_pk_bf16_f32 v41, v42, v43
	v_cvt_pk_bf16_f32 v42, v36, v37
	v_lshlrev_b64 v[36:37], 7, v[44:45]
	v_lshl_add_u64 v[36:37], s[14:15], 0, v[36:37]
	s_mov_b32 s23, s50
	v_lshl_add_u64 v[36:37], v[36:37], 0, s[22:23]
	v_lshl_add_u64 v[36:37], v[36:37], 0, v[0:1]
	v_mov_b32_e32 v61, v1
	v_cvt_pk_bf16_f32 v43, v38, v39
	v_lshl_add_u64 v[36:37], v[36:37], 0, v[60:61]
	v_add_u32_e32 v38, 0x80, v2
	s_nop 1
	v_permlane16_swap_b32 v40, v42
	v_permlane16_swap_b32 v41, v43
	s_nop 1
	global_store_dwordx4 v[36:37], v[40:43], off
	v_ashrrev_i32_e32 v36, 7, v38
	v_and_b32_e32 v36, -2, v36
	v_or_b32_e32 v36, s76, v36
	s_mov_b64 s[16:17], -1
	s_and_b64 vcc, exec, s[8:9]
	v_ashrrev_i32_e32 v37, 31, v36
	s_cbranch_vccnz .LBB0_284
	v_lshlrev_b64 v[40:41], 16, v[36:37]
	v_lshlrev_b32_e32 v39, 8, v38
	v_lshl_add_u64 v[40:41], s[20:21], 0, v[40:41]
	v_and_b32_e32 v42, 0xcf00, v39
	v_mov_b32_e32 v43, v1
	v_lshl_add_u64 v[40:41], v[40:41], 0, v[42:43]
	s_lshl_b32 s16, s30, 2
	s_mov_b32 s17, s50
	v_lshl_add_u64 v[40:41], v[40:41], 0, s[16:17]
	v_mov_b32_e32 v69, v1
	v_lshl_add_u64 v[40:41], v[40:41], 0, v[68:69]
	s_mov_b64 s[16:17], 0
	global_store_dwordx4 v[40:41], v[32:35], off
	global_store_dwordx4 v[40:41], v[28:31], off offset:64

.LBB0_286:
	v_ashrrev_i32_e32 v39, 31, v38
	v_cvt_pk_bf16_f32 v32, v32, v33
	v_cvt_pk_bf16_f32 v33, v34, v35
	v_cvt_pk_bf16_f32 v34, v28, v29
	v_lshlrev_b64 v[28:29], 7, v[38:39]
	v_lshl_add_u64 v[28:29], s[14:15], 0, v[28:29]
	s_mov_b32 s23, s50
	v_lshl_add_u64 v[28:29], v[28:29], 0, s[22:23]
	v_lshl_add_u64 v[28:29], v[28:29], 0, v[0:1]
	v_mov_b32_e32 v61, v1
	v_cvt_pk_bf16_f32 v35, v30, v31
	v_lshl_add_u64 v[28:29], v[28:29], 0, v[60:61]
	s_nop 1
	v_permlane16_swap_b32 v32, v34
	v_permlane16_swap_b32 v33, v35
	s_nop 1
	global_store_dwordx4 v[28:29], v[32:35], off
	v_add_u32_e32 v28, 0x90, v2
	s_and_b64 vcc, exec, s[8:9]
	s_mov_b64 s[16:17], -1
	s_cbranch_vccnz .LBB0_288
	v_lshlrev_b64 v[30:31], 16, v[36:37]
	v_lshlrev_b32_e32 v29, 8, v28
	v_lshl_add_u64 v[30:31], s[20:21], 0, v[30:31]
	v_and_b32_e32 v32, 0xdf00, v29
	v_mov_b32_e32 v33, v1
	v_lshl_add_u64 v[30:31], v[30:31], 0, v[32:33]
	s_lshl_b32 s16, s30, 2
	s_mov_b32 s17, s50
	v_lshl_add_u64 v[30:31], v[30:31], 0, s[16:17]
	v_mov_b32_e32 v69, v1
	v_lshl_add_u64 v[30:31], v[30:31], 0, v[68:69]
	s_mov_b64 s[16:17], 0
	global_store_dwordx4 v[30:31], v[24:27], off
	global_store_dwordx4 v[30:31], v[20:23], off offset:64

.LBB0_290:
	v_ashrrev_i32_e32 v29, 31, v28
	v_cvt_pk_bf16_f32 v24, v24, v25
	v_cvt_pk_bf16_f32 v25, v26, v27
	v_cvt_pk_bf16_f32 v26, v20, v21
	v_lshlrev_b64 v[20:21], 7, v[28:29]
	v_lshl_add_u64 v[20:21], s[14:15], 0, v[20:21]
	s_mov_b32 s23, s50
	v_lshl_add_u64 v[20:21], v[20:21], 0, s[22:23]
	v_lshl_add_u64 v[20:21], v[20:21], 0, v[0:1]
	v_mov_b32_e32 v61, v1
	v_cvt_pk_bf16_f32 v27, v22, v23
	v_lshl_add_u64 v[20:21], v[20:21], 0, v[60:61]
	s_nop 1
	v_permlane16_swap_b32 v24, v26
	v_permlane16_swap_b32 v25, v27
	s_nop 1
	global_store_dwordx4 v[20:21], v[24:27], off
	v_add_u32_e32 v20, 0xa0, v2
	s_and_b64 vcc, exec, s[8:9]
	s_mov_b64 s[16:17], -1
	s_cbranch_vccnz .LBB0_292
	v_lshlrev_b64 v[22:23], 16, v[36:37]
	v_lshlrev_b32_e32 v3, 8, v20
	v_lshl_add_u64 v[22:23], s[20:21], 0, v[22:23]
	v_and_b32_e32 v24, 0xef00, v3
	v_mov_b32_e32 v25, v1
	v_lshl_add_u64 v[22:23], v[22:23], 0, v[24:25]
	s_lshl_b32 s16, s30, 2
	s_mov_b32 s17, s50
	v_lshl_add_u64 v[22:23], v[22:23], 0, s[16:17]
	v_mov_b32_e32 v69, v1
	v_lshl_add_u64 v[22:23], v[22:23], 0, v[68:69]
	s_mov_b64 s[16:17], 0
	global_store_dwordx4 v[22:23], v[16:19], off
	global_store_dwordx4 v[22:23], v[12:15], off offset:64

.LBB0_294:
	v_ashrrev_i32_e32 v21, 31, v20
	v_cvt_pk_bf16_f32 v16, v16, v17
	v_cvt_pk_bf16_f32 v17, v18, v19
	v_cvt_pk_bf16_f32 v18, v12, v13
	v_lshlrev_b64 v[12:13], 7, v[20:21]
	v_lshl_add_u64 v[12:13], s[14:15], 0, v[12:13]
	s_mov_b32 s23, s50
	v_lshl_add_u64 v[12:13], v[12:13], 0, s[22:23]
	v_lshl_add_u64 v[12:13], v[12:13], 0, v[0:1]
	v_mov_b32_e32 v61, v1
	v_cvt_pk_bf16_f32 v19, v14, v15
	v_lshl_add_u64 v[12:13], v[12:13], 0, v[60:61]
	v_add_u32_e32 v2, 0xb0, v2
	s_and_b64 vcc, exec, s[8:9]
	s_mov_b64 s[8:9], -1
	s_nop 1
	v_permlane16_swap_b32 v16, v18
	v_permlane16_swap_b32 v17, v19
	s_nop 1
	global_store_dwordx4 v[12:13], v[16:19], off
	s_cbranch_vccnz .LBB0_296
	v_lshlrev_b64 v[12:13], 16, v[36:37]
	v_lshlrev_b32_e32 v3, 8, v2
	v_lshl_add_u64 v[12:13], s[20:21], 0, v[12:13]
	v_and_b32_e32 v14, 0xff00, v3
	v_mov_b32_e32 v15, v1
	v_lshl_add_u64 v[12:13], v[12:13], 0, v[14:15]
	s_lshl_b32 s8, s30, 2
	s_mov_b32 s9, s50
	v_lshl_add_u64 v[12:13], v[12:13], 0, s[8:9]
	v_mov_b32_e32 v69, v1
	v_lshl_add_u64 v[12:13], v[12:13], 0, v[68:69]
	s_mov_b64 s[8:9], 0
	global_store_dwordx4 v[12:13], v[8:11], off
	global_store_dwordx4 v[12:13], v[4:7], off offset:64

.LBB0_298:
	v_ashrrev_i32_e32 v3, 31, v2
	v_lshlrev_b64 v[2:3], 7, v[2:3]
	v_lshl_add_u64 v[2:3], s[14:15], 0, v[2:3]
	s_mov_b32 s23, s50
	v_lshl_add_u64 v[2:3], v[2:3], 0, s[22:23]
	v_lshl_add_u64 v[2:3], v[2:3], 0, v[0:1]
	v_mov_b32_e32 v61, v1
	v_cvt_pk_bf16_f32 v8, v8, v9
	v_cvt_pk_bf16_f32 v9, v10, v11
	v_cvt_pk_bf16_f32 v10, v4, v5
	v_cvt_pk_bf16_f32 v11, v6, v7
	v_lshl_add_u64 v[2:3], v[2:3], 0, v[60:61]
	s_nop 1
	v_permlane16_swap_b32 v8, v10
	v_permlane16_swap_b32 v9, v11
	s_nop 1
	global_store_dwordx4 v[2:3], v[8:11], off
.LBB0_299:
	s_abs_i32 s6, s80
	v_cvt_f32_u32_e32 v0, s6
	s_sub_i32 s7, 0, s6
	v_rcp_iflag_f32_e32 v0, v0
	s_nop 0
	v_mul_f32_e32 v0, 0x4f7ffffe, v0
	v_cvt_u32_f32_e32 v0, v0
	s_nop 0
	v_readfirstlane_b32 s8, v0
	s_mul_i32 s7, s7, s8
	s_mul_hi_u32 s7, s8, s7
	s_add_i32 s8, s8, s7
	s_mul_hi_u32 s7, s8, 0xa0
	s_mul_i32 s7, s7, s6
	s_sub_i32 s7, 0xa0, s7
	s_sub_i32 s8, s7, s6
	s_cmp_ge_u32 s7, s6
	s_cselect_b32 s7, s8, s7
	s_sub_i32 s8, s7, s6
	s_cmp_ge_u32 s7, s6
	s_cselect_b32 s6, s8, s7
	s_cmp_lt_i32 s81, s6
	s_cbranch_scc1 .LBB0_360
	s_ashr_i32 s7, s82, 6
	s_mul_i32 s8, s76, 0xab40
	s_sub_i32 s9, s81, s6
	s_add_i32 s18, s8, 0x9540
	s_lshl_b32 s9, s9, 3
	s_add_i32 s8, s8, s7
	s_add_i32 s8, s8, s9
	s_add_i32 s19, s8, 0x6940
	s_cmp_ge_i32 s19, s18
	s_cbranch_scc1 .LBB0_360
	s_sub_i32 s6, s80, s6
	s_lshl_b32 s20, s6, 3
	s_lshl_b32 s6, s7, 14
	s_add_i32 s6, s6, 0
	s_add_u32 s21, s10, 0x10612000
	s_addc_u32 s22, s11, 0
	s_add_u32 s23, s10, 0x5612000
	s_addc_u32 s24, s11, 0
	s_add_u32 s25, s10, 0x4612000
	s_addc_u32 s26, s11, 0
	s_add_u32 s27, s10, 0x3e12000
	s_addc_u32 s28, s11, 0
	s_add_u32 s29, s10, 0x3812000
	s_addc_u32 s30, s11, 0
	s_add_u32 s31, s10, 0x1e12000
	v_bfe_u32 v10, v188, 3, 3
	s_addc_u32 s33, s11, 0
	v_lshlrev_b32_e32 v0, 2, v188
	v_and_b32_e32 v3, 7, v188
	v_lshlrev_b32_e32 v6, 2, v10
	s_add_u32 s34, s10, 0x612000
	v_and_b32_e32 v0, 28, v0
	v_lshl_add_u32 v4, v3, 4, s6
	v_mul_u32_u24_e32 v5, 0x84, v10
	v_lshlrev_b32_e32 v2, 3, v3
	v_mul_u32_u24_e32 v3, 0x420, v3
	v_and_b32_e32 v14, 16, v6
	s_addc_u32 s35, s11, 0
	v_or_b32_e32 v11, 8, v10
	v_or_b32_e32 v12, 16, v10
	v_or_b32_e32 v13, 24, v10
	v_add3_u32 v15, s6, v3, v6
	v_or_b32_e32 v16, 4, v14
	v_or_b32_e32 v17, 8, v14
	v_or_b32_e32 v18, 12, v6
	v_lshlrev_b32_e32 v0, 2, v0
	v_add_u32_e32 v19, v4, v5
	v_lshlrev_b32_e32 v6, 1, v2
	s_mov_b32 s99, 0
	s_branch .LBB0_304
.LBB0_302:
	v_mov_b32_e32 v121, v107
.LBB0_303:
	v_ashrrev_i32_e32 v107, 31, v121
	v_mul_lo_u32 v122, s7, v121
	v_mul_lo_u32 v107, s6, v107
	v_mad_u64_u32 v[120:121], s[6:7], s6, v121, 0
	v_add3_u32 v121, v121, v107, v122
	v_lshl_add_u64 v[108:109], v[120:121], 1, v[108:109]
	global_store_dwordx4 v[108:109], v[102:105], off
	s_waitcnt lgkmcnt(0)
	s_cmp_eq_u32 s99, 2
	s_cbranch_scc1 .LBB0_360
	s_branch .Lcv_mid_G5

.LBB0_336:
	s_lshr_b32 s10, s45, 5
	v_cvt_f32_u32_e32 v2, s10
	s_sub_i32 s17, 0, s10
	s_abs_i32 s16, s39
	s_ashr_i32 s11, s39, 31
	v_rcp_iflag_f32_e32 v2, v2
	s_nop 0
	v_mul_f32_e32 v2, 0x4f7ffffe, v2
	v_cvt_u32_f32_e32 v2, v2
	s_nop 0
	v_readfirstlane_b32 s37, v2
	s_mul_i32 s17, s17, s37
	s_mul_hi_u32 s17, s37, s17
	s_add_i32 s37, s37, s17
	s_mul_hi_u32 s17, s16, s37
	s_mul_i32 s37, s17, s10
	s_sub_i32 s16, s16, s37
	s_add_i32 s37, s17, 1
	s_sub_i32 s38, s16, s10
	s_cmp_ge_u32 s16, s10
	s_cselect_b32 s17, s37, s17
	s_cselect_b32 s16, s38, s16
	s_add_i32 s37, s17, 1
	s_cmp_ge_u32 s16, s10
	s_cselect_b32 s16, s37, s17
	s_xor_b32 s16, s16, s11
	s_sub_i32 s11, s16, s11
	s_lshl_b32 s16, s11, 6
	s_mul_i32 s10, s11, s10
	v_or_b32_e32 v2, s16, v10
	s_ashr_i32 s17, s16, 31
	s_sub_i32 s37, s39, s10
	s_mul_i32 s11, s17, s45
	v_mad_u64_u32 v[2:3], s[38:39], v2, s45, 0
	s_lshl_b32 s10, s37, 5
	v_add_u32_e32 v3, s11, v3
	v_lshl_add_u64 v[2:3], v[2:3], 2, s[14:15]
	s_ashr_i32 s11, s10, 31
	v_lshl_add_u64 v[2:3], s[10:11], 2, v[2:3]
	v_lshl_add_u64 v[8:9], v[2:3], 0, v[0:1]
	s_lshl_b32 s14, s45, 3
	s_mov_b32 s15, s50
	global_load_dwordx4 v[2:5], v[8:9], off nt
	v_lshl_add_u64 v[20:21], s[14:15], 2, v[8:9]
	global_load_dwordx4 v[20:23], v[20:21], off nt
	s_lshl_b32 s14, s45, 4
	v_lshl_add_u64 v[24:25], s[14:15], 2, v[8:9]
	global_load_dwordx4 v[24:27], v[24:25], off nt
	s_mul_i32 s14, s45, 24
	v_lshl_add_u64 v[28:29], s[14:15], 2, v[8:9]
	global_load_dwordx4 v[28:31], v[28:29], off nt
	s_lshl_b32 s14, s45, 5
	v_lshl_add_u64 v[32:33], s[14:15], 2, v[8:9]
	global_load_dwordx4 v[32:35], v[32:33], off nt
	s_mul_i32 s14, s45, 40
	v_lshl_add_u64 v[36:37], s[14:15], 2, v[8:9]
	global_load_dwordx4 v[36:39], v[36:37], off nt
	s_mul_i32 s14, s45, 48
	v_lshl_add_u64 v[40:41], s[14:15], 2, v[8:9]
	global_load_dwordx4 v[40:43], v[40:41], off nt
	s_mul_i32 s14, s45, 56
	v_lshl_add_u64 v[8:9], s[14:15], 2, v[8:9]
	global_load_dwordx4 v[44:47], v[8:9], off nt
	v_writelane_b32 v255, s6, 40
	v_writelane_b32 v255, s7, 41
	v_writelane_b32 v255, s8, 42
	v_writelane_b32 v255, s9, 43
	v_writelane_b32 v255, s10, 44
	v_writelane_b32 v255, s11, 45
	v_writelane_b32 v255, s14, 46
	v_writelane_b32 v255, s15, 47
	v_writelane_b32 v255, s16, 48
	v_writelane_b32 v255, s17, 49
	v_writelane_b32 v255, s36, 50
	v_writelane_b32 v255, s37, 51
	v_writelane_b32 v255, s48, 52
	s_cmp_eq_u32 s99, 1
	s_cbranch_scc1 .Lcv_tail_G5
.Lcv_mid_G5:
	s_waitcnt vmcnt(0)
	ds_write2_b32 v19, v2, v3 offset1:1
	ds_write2_b32 v19, v4, v5 offset0:2 offset1:3
	v_add_u32_e32 v2, 0x420, v19
	ds_write2_b32 v2, v20, v21 offset1:1
	v_add_u32_e32 v2, 0x428, v19
	ds_write2_b32 v2, v22, v23 offset1:1
	v_add_u32_e32 v2, 0x840, v19
	ds_write2_b32 v2, v24, v25 offset1:1
	v_add_u32_e32 v2, 0x848, v19
	ds_write2_b32 v2, v26, v27 offset1:1
	v_add_u32_e32 v2, 0xc60, v19
	ds_write2_b32 v2, v28, v29 offset1:1
	v_add_u32_e32 v2, 0xc68, v19
	ds_write2_b32 v2, v30, v31 offset1:1
	v_add_u32_e32 v2, 0x1080, v19
	ds_write2_b32 v2, v32, v33 offset1:1
	v_add_u32_e32 v2, 0x1088, v19
	ds_write2_b32 v2, v34, v35 offset1:1
	v_add_u32_e32 v2, 0x14a0, v19
	ds_write2_b32 v2, v36, v37 offset1:1
	v_add_u32_e32 v2, 0x14a8, v19
	ds_write2_b32 v2, v38, v39 offset1:1
	v_add_u32_e32 v2, 0x18c0, v19
	ds_write2_b32 v2, v40, v41 offset1:1
	v_add_u32_e32 v2, 0x18c8, v19
	ds_write2_b32 v2, v42, v43 offset1:1
	v_add_u32_e32 v2, 0x1ce0, v19
	ds_write2_b32 v2, v44, v45 offset1:1
	v_add_u32_e32 v2, 0x1ce8, v19
	ds_write2_b32 v2, v46, v47 offset1:1
	s_waitcnt lgkmcnt(0)
	s_nop 1
	v_readlane_b32 s100, v255, 40
	v_readlane_b32 s101, v255, 41
	s_nop 1
	v_writelane_b32 v255, s100, 16
	v_writelane_b32 v255, s101, 17
	s_nop 1
	v_readlane_b32 s100, v255, 42
	v_readlane_b32 s101, v255, 43
	s_nop 1
	v_writelane_b32 v255, s100, 18
	v_writelane_b32 v255, s101, 19
	s_nop 1
	v_readlane_b32 s100, v255, 44
	v_readlane_b32 s101, v255, 45
	s_nop 1
	v_writelane_b32 v255, s100, 20
	v_writelane_b32 v255, s101, 21
	s_nop 1
	v_readlane_b32 s100, v255, 46
	v_readlane_b32 s101, v255, 47
	s_nop 1
	v_writelane_b32 v255, s100, 22
	v_writelane_b32 v255, s101, 23
	s_nop 1
	v_readlane_b32 s100, v255, 48
	v_readlane_b32 s101, v255, 49
	s_nop 1
	v_writelane_b32 v255, s100, 24
	v_writelane_b32 v255, s101, 25
	s_nop 1
	v_readlane_b32 s100, v255, 50
	v_readlane_b32 s101, v255, 51
	s_nop 1
	v_writelane_b32 v255, s100, 26
	v_writelane_b32 v255, s101, 27
	s_nop 1
	v_readlane_b32 s100, v255, 52
	s_nop 1
	v_writelane_b32 v255, s100, 28
	s_nop 1
	s_add_i32 s19, s19, s20
	s_cmp_lt_i32 s19, s18
	s_cbranch_scc0 .Lcv_drain_G5
	s_mov_b32 s99, 1
	s_branch .LBB0_304
.Lcv_drain_G5:
	s_mov_b32 s99, 2
.Lcv_tail_G5:
	s_nop 1
	v_readlane_b32 s6, v255, 16
	v_readlane_b32 s7, v255, 17
	v_readlane_b32 s8, v255, 18
	v_readlane_b32 s9, v255, 19
	v_readlane_b32 s10, v255, 20
	v_readlane_b32 s11, v255, 21
	v_readlane_b32 s14, v255, 22
	v_readlane_b32 s15, v255, 23
	v_readlane_b32 s16, v255, 24
	v_readlane_b32 s17, v255, 25
	v_readlane_b32 s36, v255, 26
	v_readlane_b32 s37, v255, 27
	v_readlane_b32 s48, v255, 28
	s_nop 4
	v_mov_b32_e32 v106, v6
	v_or_b32_e32 v107, s10, v10
	s_cmp_gt_i32 s36, 2
	s_mov_b64 s[14:15], -1
	ds_read2_b32 v[102:103], v15 offset1:33
	s_waitcnt lgkmcnt(0)
	v_cvt_pk_bf16_f32 v102, v102, v103
	ds_read2_b32 v[104:105], v15 offset0:66 offset1:99
	s_waitcnt lgkmcnt(0)
	v_cvt_pk_bf16_f32 v103, v104, v105
	ds_read2_b32 v[104:105], v15 offset0:132 offset1:165
	s_waitcnt lgkmcnt(0)
	v_cvt_pk_bf16_f32 v104, v104, v105
	ds_read2_b32 v[108:109], v15 offset0:198 offset1:231
	s_waitcnt lgkmcnt(0)
	v_cvt_pk_bf16_f32 v105, v108, v109
	s_cbranch_scc0 .LBB0_338
	v_and_or_b32 v121, v107, s91, v14
	s_mov_b64 s[14:15], 0
.LBB0_338:
	s_lshl_b32 s11, s37, 6
	s_and_b32 s11, s11, 0xffffff00
	s_or_b32 s11, s48, s11
	v_or_b32_e32 v120, s11, v14
	s_andn2_b64 vcc, exec, s[14:15]
	s_cbranch_vccnz .LBB0_342
	s_cmp_lg_u32 s36, 0
	s_cbranch_scc0 .LBB0_341
	s_movk_i32 s11, 0x63
	v_and_or_b32 v107, v107, s11, v120

.LBB0_342:
	s_lshl_b64 s[14:15], s[16:17], 1
	s_add_u32 s8, s8, s14
	s_addc_u32 s9, s9, s15
	v_mov_b32_e32 v107, v1
	v_lshl_add_u64 v[108:109], s[8:9], 0, v[106:107]
	v_ashrrev_i32_e32 v107, 31, v121
	v_mul_lo_u32 v124, s7, v121
	v_mul_lo_u32 v107, s6, v107
	v_mad_u64_u32 v[122:123], s[8:9], s6, v121, 0
	v_add3_u32 v123, v123, v107, v124
	v_lshl_add_u64 v[122:123], v[122:123], 1, v[108:109]
	global_store_dwordx4 v[122:123], v[102:105], off
	ds_read2_b32 v[102:103], v15 offset0:8 offset1:41
	v_or_b32_e32 v121, s10, v11
	s_waitcnt lgkmcnt(0)
	v_cvt_pk_bf16_f32 v102, v102, v103
	ds_read2_b32 v[104:105], v15 offset0:74 offset1:107
	s_waitcnt lgkmcnt(0)
	v_cvt_pk_bf16_f32 v103, v104, v105
	ds_read2_b32 v[104:105], v15 offset0:140 offset1:173
	s_cmp_gt_i32 s36, 2
	s_mov_b64 s[8:9], -1
	s_waitcnt lgkmcnt(0)
	v_cvt_pk_bf16_f32 v104, v104, v105
	ds_read2_b32 v[122:123], v15 offset0:206 offset1:239
	s_waitcnt lgkmcnt(0)
	v_cvt_pk_bf16_f32 v105, v122, v123
	s_cbranch_scc0 .LBB0_344
	v_and_or_b32 v107, v121, s91, v16
	s_mov_b64 s[8:9], 0
.LBB0_344:
	s_andn2_b64 vcc, exec, s[8:9]
	s_cbranch_vccnz .LBB0_348
	s_cmp_lg_u32 s36, 0
	s_cbranch_scc0 .LBB0_347
	v_and_b32_e32 v107, 0x63, v121
	v_or3_b32 v121, v107, v120, 4
.LBB0_347:
	v_mov_b32_e32 v107, v121
.LBB0_348:
	v_ashrrev_i32_e32 v121, 31, v107
	v_mul_lo_u32 v126, s7, v107
	v_mul_lo_u32 v121, s6, v121
	v_mad_u64_u32 v[124:125], s[8:9], s6, v107, 0
	v_add3_u32 v125, v125, v121, v126
	v_lshl_add_u64 v[124:125], v[124:125], 1, v[108:109]
	ds_read2_b32 v[122:123], v15 offset0:16 offset1:49
	global_store_dwordx4 v[124:125], v[102:105], off
	v_or_b32_e32 v121, s10, v12
	s_cmp_gt_i32 s36, 2
	s_waitcnt lgkmcnt(0)
	v_cvt_pk_bf16_f32 v102, v122, v123
	ds_read2_b32 v[104:105], v15 offset0:82 offset1:115
	s_waitcnt lgkmcnt(0)
	v_cvt_pk_bf16_f32 v103, v104, v105
	ds_read2_b32 v[104:105], v15 offset0:148 offset1:181
	s_mov_b64 s[8:9], -1
	s_waitcnt lgkmcnt(0)
	v_cvt_pk_bf16_f32 v104, v104, v105
	ds_read2_b32 v[122:123], v15 offset0:214 offset1:247
	s_waitcnt lgkmcnt(0)
	v_cvt_pk_bf16_f32 v105, v122, v123
	s_cbranch_scc0 .LBB0_350
	v_and_or_b32 v107, v121, s91, v17
	s_mov_b64 s[8:9], 0
.LBB0_350:
	s_andn2_b64 vcc, exec, s[8:9]
	s_cbranch_vccnz .LBB0_354
	s_cmp_lg_u32 s36, 0
	s_cbranch_scc0 .LBB0_353
	v_and_b32_e32 v107, 0x63, v121
	v_or3_b32 v121, v107, v120, 8

.LBB0_354:
	v_ashrrev_i32_e32 v121, 31, v107
	v_mul_lo_u32 v126, s7, v107
	v_mul_lo_u32 v121, s6, v121
	v_mad_u64_u32 v[124:125], s[8:9], s6, v107, 0
	v_add3_u32 v125, v125, v121, v126
	v_lshl_add_u64 v[124:125], v[124:125], 1, v[108:109]
	ds_read2_b32 v[122:123], v15 offset0:24 offset1:57
	global_store_dwordx4 v[124:125], v[102:105], off
	v_or_b32_e32 v107, s10, v13
	s_cmp_gt_i32 s36, 2
	s_waitcnt lgkmcnt(0)
	v_cvt_pk_bf16_f32 v102, v122, v123
	ds_read2_b32 v[104:105], v15 offset0:90 offset1:123
	s_waitcnt lgkmcnt(0)
	v_cvt_pk_bf16_f32 v103, v104, v105
	ds_read2_b32 v[104:105], v15 offset0:156 offset1:189
	s_mov_b64 s[8:9], -1
	s_waitcnt lgkmcnt(0)
	v_cvt_pk_bf16_f32 v104, v104, v105
	ds_read2_b32 v[122:123], v15 offset0:222 offset1:255
	s_waitcnt lgkmcnt(0)
	v_cvt_pk_bf16_f32 v105, v122, v123
	s_cbranch_scc0 .LBB0_356
	v_and_or_b32 v121, v107, s91, v18
	s_mov_b64 s[8:9], 0
.LBB0_356:
	s_andn2_b64 vcc, exec, s[8:9]
	s_cbranch_vccnz .LBB0_303
	s_cmp_lg_u32 s36, 0
	s_cbranch_scc0 .LBB0_302
	v_and_b32_e32 v107, 0x63, v107
	v_or3_b32 v107, v107, v120, 12
	s_branch .LBB0_302

.LBB0_433:
	s_lshl_b32 s21, s6, 8
	s_lshl_b32 s36, s8, 8
	s_cmp_eq_u32 s33, 0
	s_cbranch_scc1 .LBB0_436
	v_add_u32_e32 v136, s21, v215
	v_or_b32_e32 v130, s36, v220
	v_ashrrev_i32_e32 v137, 31, v136
	v_ashrrev_i32_e32 v131, 31, v130
	v_lshlrev_b64 v[132:133], 13, v[136:137]
	v_lshl_add_u64 v[132:133], s[16:17], 0, v[132:133]
	v_lshlrev_b64 v[138:139], 1, v[130:131]
	v_lshl_add_u64 v[130:131], v[132:133], 0, v[138:139]
	v_cvt_pk_bf16_f32 v132, v126, v127
	v_cvt_pk_bf16_f32 v133, v128, v129
	v_cvt_pk_bf16_f32 v134, v122, v123
	v_cvt_pk_bf16_f32 v135, v124, v125
	global_store_dwordx4 v[130:131], v[132:135], off
	s_mov_b32 s7, 0x100000
	s_mov_b64 s[8:9], 0x100000
	v_cvt_pk_bf16_f32 v132, v118, v119
	v_cvt_pk_bf16_f32 v133, v120, v121
	v_cvt_pk_bf16_f32 v134, v114, v115
	v_cvt_pk_bf16_f32 v135, v116, v117
	global_store_dwordx4 v[130:131], v[132:135], off offset:256
	s_nop 1
	v_or_b32_e32 v132, 16, v136
	v_ashrrev_i32_e32 v133, 31, v132
	v_lshlrev_b64 v[132:133], 13, v[132:133]
	v_lshl_add_u64 v[132:133], s[16:17], 0, v[132:133]
	v_lshl_add_u64 v[140:141], v[132:133], 0, v[138:139]
	v_cvt_pk_bf16_f32 v132, v110, v111
	v_cvt_pk_bf16_f32 v133, v112, v113
	v_cvt_pk_bf16_f32 v134, v106, v107
	v_cvt_pk_bf16_f32 v135, v108, v109
	global_store_dwordx4 v[140:141], v[132:135], off
	s_nop 1
	v_cvt_pk_bf16_f32 v132, v102, v103
	v_cvt_pk_bf16_f32 v133, v104, v105
	v_cvt_pk_bf16_f32 v134, v98, v99
	v_cvt_pk_bf16_f32 v135, v100, v101
	global_store_dwordx4 v[140:141], v[132:135], off offset:256
	s_nop 1
	v_or_b32_e32 v132, 32, v136
	v_ashrrev_i32_e32 v133, 31, v132
	v_lshlrev_b64 v[132:133], 13, v[132:133]
	v_lshl_add_u64 v[132:133], s[16:17], 0, v[132:133]
	v_lshl_add_u64 v[140:141], v[132:133], 0, v[138:139]
	v_cvt_pk_bf16_f32 v132, v94, v95
	v_cvt_pk_bf16_f32 v133, v96, v97
	v_cvt_pk_bf16_f32 v134, v90, v91
	v_cvt_pk_bf16_f32 v135, v92, v93
	global_store_dwordx4 v[140:141], v[132:135], off
	s_nop 1
	v_cvt_pk_bf16_f32 v132, v86, v87
	v_cvt_pk_bf16_f32 v133, v88, v89
	v_cvt_pk_bf16_f32 v134, v82, v83
	v_cvt_pk_bf16_f32 v135, v84, v85
	global_store_dwordx4 v[140:141], v[132:135], off offset:256
	s_nop 1
	v_or_b32_e32 v132, 48, v136
	v_ashrrev_i32_e32 v133, 31, v132
	v_lshlrev_b64 v[132:133], 13, v[132:133]
	v_lshl_add_u64 v[132:133], s[16:17], 0, v[132:133]
	v_lshl_add_u64 v[136:137], v[132:133], 0, v[138:139]
	v_cvt_pk_bf16_f32 v132, v78, v79
	v_cvt_pk_bf16_f32 v133, v80, v81
	v_cvt_pk_bf16_f32 v134, v74, v75
	v_cvt_pk_bf16_f32 v135, v76, v77
	global_store_dwordx4 v[136:137], v[132:135], off
	v_add_co_u32_e32 v138, vcc, s7, v130
	s_nop 0
	v_cvt_pk_bf16_f32 v132, v70, v71
	v_cvt_pk_bf16_f32 v133, v72, v73
	v_cvt_pk_bf16_f32 v134, v66, v67
	v_cvt_pk_bf16_f32 v135, v68, v69
	global_store_dwordx4 v[136:137], v[132:135], off offset:256
	v_addc_co_u32_e32 v139, vcc, 0, v131, vcc
	s_nop 0
	v_cvt_pk_bf16_f32 v132, v62, v63
	v_cvt_pk_bf16_f32 v133, v64, v65
	s_mov_b32 s7, 0x120000
	v_lshl_add_u64 v[136:137], v[130:131], 0, s[8:9]
	v_cvt_pk_bf16_f32 v134, v58, v59
	v_cvt_pk_bf16_f32 v135, v60, v61
	global_store_dwordx4 v[138:139], v[132:135], off
	v_add_co_u32_e32 v138, vcc, s7, v130
	s_nop 0
	v_cvt_pk_bf16_f32 v132, v54, v55
	v_cvt_pk_bf16_f32 v133, v56, v57
	v_cvt_pk_bf16_f32 v134, v50, v51
	v_cvt_pk_bf16_f32 v135, v52, v53
	global_store_dwordx4 v[136:137], v[132:135], off offset:256
	s_mov_b64 s[8:9], 0x120000
	v_addc_co_u32_e32 v139, vcc, 0, v131, vcc
	v_cvt_pk_bf16_f32 v132, v46, v47
	v_cvt_pk_bf16_f32 v133, v48, v49
	s_mov_b32 s7, 0x140000
	v_lshl_add_u64 v[136:137], v[130:131], 0, s[8:9]
	v_cvt_pk_bf16_f32 v134, v42, v43
	v_cvt_pk_bf16_f32 v135, v44, v45
	global_store_dwordx4 v[138:139], v[132:135], off
	s_mov_b64 s[8:9], 0x140000
	v_add_co_u32_e32 v138, vcc, s7, v130
	v_cvt_pk_bf16_f32 v132, v38, v39
	v_cvt_pk_bf16_f32 v133, v40, v41
	v_cvt_pk_bf16_f32 v134, v34, v35
	v_cvt_pk_bf16_f32 v135, v36, v37
	global_store_dwordx4 v[136:137], v[132:135], off offset:256
	v_lshl_add_u64 v[136:137], v[130:131], 0, s[8:9]
	v_addc_co_u32_e32 v139, vcc, 0, v131, vcc
	v_cvt_pk_bf16_f32 v132, v30, v31
	v_cvt_pk_bf16_f32 v133, v32, v33
	s_mov_b64 s[8:9], 0x160000
	s_mov_b32 s7, 0x160000
	v_cvt_pk_bf16_f32 v134, v26, v27
	v_cvt_pk_bf16_f32 v135, v28, v29
	global_store_dwordx4 v[138:139], v[132:135], off
	v_lshl_add_u64 v[138:139], v[130:131], 0, s[8:9]
	v_add_co_u32_e32 v130, vcc, s7, v130
	v_cvt_pk_bf16_f32 v132, v22, v23
	v_cvt_pk_bf16_f32 v133, v24, v25
	v_cvt_pk_bf16_f32 v134, v18, v19
	v_cvt_pk_bf16_f32 v135, v20, v21
	global_store_dwordx4 v[136:137], v[132:135], off offset:256
	s_nop 0
	v_addc_co_u32_e32 v131, vcc, 0, v131, vcc
	v_cvt_pk_bf16_f32 v132, v14, v15
	v_cvt_pk_bf16_f32 v133, v16, v17
	v_cvt_pk_bf16_f32 v134, v10, v11
	v_cvt_pk_bf16_f32 v135, v12, v13
	global_store_dwordx4 v[130:131], v[132:135], off
	v_cvt_pk_bf16_f32 v130, v6, v7
	v_cvt_pk_bf16_f32 v131, v8, v9
	s_nop 1
	v_cvt_pk_bf16_f32 v132, v2, v3
	v_cvt_pk_bf16_f32 v133, v4, v5
	s_cbranch_execz .LBB0_437
	s_andn2_b64 vcc, exec, s[22:23]
	s_mov_b64 s[6:7], -1
	global_store_dwordx4 v[138:139], v[130:133], off offset:256
	s_cbranch_vccnz .LBB0_423
	s_branch .LBB0_454

.LBB0_453:
	s_waitcnt vmcnt(0)
	v_cndmask_b32_e64 v207, v191, 0, s[34:35]
	v_cndmask_b32_e64 v206, v190, 0, s[34:35]
	v_cndmask_b32_e64 v205, v187, 1.0, s[34:35]
	v_cndmask_b32_e64 v204, v186, 1.0, s[34:35]
	v_cndmask_b32_e64 v223, v193, 0, s[34:35]
	v_cndmask_b32_e64 v222, v192, 0, s[34:35]
	v_pk_mul_f32 v[230:231], v[122:123], v[206:207]
	v_cndmask_b32_e64 v203, v189, 1.0, s[34:35]
	v_cndmask_b32_e64 v202, v188, 1.0, s[34:35]
	v_pk_mul_f32 v[228:229], v[124:125], v[222:223]
	v_pk_fma_f32 v[230:231], v[126:127], v[204:205], v[230:231] neg_lo:[0,0,1] neg_hi:[0,0,1]
	v_pk_mul_f32 v[126:127], v[126:127], v[206:207]
	v_pk_fma_f32 v[228:229], v[128:129], v[202:203], v[228:229] neg_lo:[0,0,1] neg_hi:[0,0,1]
	v_pk_mul_f32 v[128:129], v[128:129], v[222:223]
	v_pk_fma_f32 v[122:123], v[122:123], v[204:205], v[126:127]
	v_pk_fma_f32 v[124:125], v[124:125], v[202:203], v[128:129]
	v_pk_mul_f32 v[122:123], v[122:123], s[62:63] op_sel_hi:[1,0]
	v_or_b32_e32 v226, s21, v214
	v_pk_mul_f32 v[228:229], v[228:229], s[62:63] op_sel_hi:[1,0]
	v_pk_mul_f32 v[230:231], v[230:231], s[62:63] op_sel_hi:[1,0]
	v_pk_mul_f32 v[128:129], v[124:125], s[62:63] op_sel_hi:[1,0]
	v_cvt_pk_bf16_f32 v124, v230, v231
	v_cvt_pk_bf16_f32 v125, v228, v229
	v_cvt_pk_bf16_f32 v126, v122, v123
	v_mov_b64_e32 v[122:123], s[14:15]
	s_ashr_i32 s37, s36, 31
	v_cvt_pk_bf16_f32 v127, v128, v129
	v_mad_i64_i32 v[128:129], s[6:7], v226, s96, v[122:123]
	s_lshl_b64 s[6:7], s[36:37], 1
	s_nop 0
	v_lshl_add_u64 v[128:129], v[128:129], 0, s[6:7]
	s_mov_b32 s21, s50
	v_lshl_add_u64 v[128:129], v[128:129], 0, s[20:21]
	v_lshl_add_u64 v[128:129], v[128:129], 0, v[0:1]
	v_mov_b32_e32 v213, v1
	s_cmp_eq_u32 s25, 0
	s_nop 1
	v_permlane16_swap_b32 v124, v126
	v_permlane16_swap_b32 v125, v127
	s_nop 1
	v_lshl_add_u64 v[128:129], v[128:129], 0, v[212:213]
	s_cselect_b64 s[8:9], -1, 0
	global_store_dwordx4 v[128:129], v[124:127], off
	v_mov_b64_e32 v[230:231], v[234:235]
	s_nop 0
	v_cndmask_b32_e64 v125, v189, 1.0, s[8:9]
	v_cndmask_b32_e64 v124, v188, 1.0, s[8:9]
	v_cndmask_b32_e64 v127, v187, 1.0, s[8:9]
	v_cndmask_b32_e64 v126, v186, 1.0, s[8:9]
	v_cndmask_b32_e64 v187, v191, 0, s[8:9]
	v_cndmask_b32_e64 v186, v190, 0, s[8:9]
	v_cndmask_b32_e64 v189, v193, 0, s[8:9]
	v_cndmask_b32_e64 v188, v192, 0, s[8:9]
	v_pk_mul_f32 v[190:191], v[116:117], v[188:189]
	v_pk_mul_f32 v[192:193], v[114:115], v[186:187]
	v_pk_fma_f32 v[190:191], v[120:121], v[124:125], v[190:191] neg_lo:[0,0,1] neg_hi:[0,0,1]
	v_pk_fma_f32 v[192:193], v[118:119], v[126:127], v[192:193] neg_lo:[0,0,1] neg_hi:[0,0,1]
	v_pk_mul_f32 v[120:121], v[120:121], v[188:189]
	v_pk_mul_f32 v[118:119], v[118:119], v[186:187]
	v_pk_fma_f32 v[116:117], v[116:117], v[124:125], v[120:121]
	v_pk_fma_f32 v[114:115], v[114:115], v[126:127], v[118:119]
	v_pk_mul_f32 v[118:119], v[116:117], s[62:63] op_sel_hi:[1,0]
	v_pk_mul_f32 v[116:117], v[114:115], s[62:63] op_sel_hi:[1,0]
	v_pk_mul_f32 v[190:191], v[190:191], s[62:63] op_sel_hi:[1,0]
	v_pk_mul_f32 v[192:193], v[192:193], s[62:63] op_sel_hi:[1,0]
	v_cndmask_b32_e64 v121, v181, 0, s[34:35]
	v_cvt_pk_bf16_f32 v114, v192, v193
	v_cvt_pk_bf16_f32 v115, v190, v191
	v_cvt_pk_bf16_f32 v116, v116, v117
	v_cvt_pk_bf16_f32 v117, v118, v119
	v_cndmask_b32_e64 v119, v179, 0, s[34:35]
	s_nop 1
	v_permlane16_swap_b32 v114, v116
	v_permlane16_swap_b32 v115, v117
	s_nop 1
	v_cndmask_b32_e64 v118, v178, 0, s[34:35]
	v_cndmask_b32_e64 v120, v180, 0, s[34:35]
	global_store_dwordx4 v[128:129], v[114:117], off offset:256
	v_pk_mul_f32 v[124:125], v[108:109], v[120:121]
	v_pk_mul_f32 v[126:127], v[106:107], v[118:119]
	v_cndmask_b32_e64 v115, v185, 1.0, s[34:35]
	v_cndmask_b32_e64 v114, v184, 1.0, s[34:35]
	v_cndmask_b32_e64 v117, v183, 1.0, s[34:35]
	v_cndmask_b32_e64 v116, v182, 1.0, s[34:35]
	v_pk_fma_f32 v[126:127], v[110:111], v[116:117], v[126:127] neg_lo:[0,0,1] neg_hi:[0,0,1]
	v_pk_fma_f32 v[124:125], v[112:113], v[114:115], v[124:125] neg_lo:[0,0,1] neg_hi:[0,0,1]
	v_pk_mul_f32 v[112:113], v[112:113], v[120:121]
	v_pk_mul_f32 v[110:111], v[110:111], v[118:119]
	v_pk_fma_f32 v[108:109], v[108:109], v[114:115], v[112:113]
	v_pk_fma_f32 v[106:107], v[106:107], v[116:117], v[110:111]
	v_or_b32_e32 v128, 16, v226
	v_pk_mul_f32 v[110:111], v[108:109], s[62:63] op_sel_hi:[1,0]
	v_pk_mul_f32 v[108:109], v[106:107], s[62:63] op_sel_hi:[1,0]
	v_pk_mul_f32 v[124:125], v[124:125], s[62:63] op_sel_hi:[1,0]
	v_pk_mul_f32 v[126:127], v[126:127], s[62:63] op_sel_hi:[1,0]
	v_cndmask_b32_e64 v113, v179, 0, s[8:9]
	v_cvt_pk_bf16_f32 v106, v126, v127
	v_cvt_pk_bf16_f32 v107, v124, v125
	v_cvt_pk_bf16_f32 v108, v108, v109
	v_cvt_pk_bf16_f32 v109, v110, v111
	v_mad_i64_i32 v[110:111], s[36:37], v128, s96, v[122:123]
	v_lshl_add_u64 v[110:111], v[110:111], 0, s[6:7]
	v_lshl_add_u64 v[110:111], v[110:111], 0, s[20:21]
	v_lshl_add_u64 v[110:111], v[110:111], 0, v[0:1]
	s_nop 1
	v_permlane16_swap_b32 v106, v108
	v_permlane16_swap_b32 v107, v109
	s_nop 1
	v_lshl_add_u64 v[110:111], v[110:111], 0, v[212:213]
	v_cndmask_b32_e64 v112, v178, 0, s[8:9]
	v_cndmask_b32_e64 v115, v181, 0, s[8:9]
	v_cndmask_b32_e64 v114, v180, 0, s[8:9]
	global_store_dwordx4 v[110:111], v[106:109], off
	v_pk_mul_f32 v[116:117], v[100:101], v[114:115]
	v_pk_mul_f32 v[118:119], v[98:99], v[112:113]
	v_cndmask_b32_e64 v107, v185, 1.0, s[8:9]
	v_cndmask_b32_e64 v106, v184, 1.0, s[8:9]
	v_cndmask_b32_e64 v109, v183, 1.0, s[8:9]
	v_cndmask_b32_e64 v108, v182, 1.0, s[8:9]
	v_pk_fma_f32 v[118:119], v[102:103], v[108:109], v[118:119] neg_lo:[0,0,1] neg_hi:[0,0,1]
	v_pk_fma_f32 v[116:117], v[104:105], v[106:107], v[116:117] neg_lo:[0,0,1] neg_hi:[0,0,1]
	v_pk_mul_f32 v[104:105], v[104:105], v[114:115]
	v_pk_mul_f32 v[102:103], v[102:103], v[112:113]
	v_pk_fma_f32 v[100:101], v[100:101], v[106:107], v[104:105]
	v_pk_fma_f32 v[98:99], v[98:99], v[108:109], v[102:103]
	v_pk_mul_f32 v[102:103], v[100:101], s[62:63] op_sel_hi:[1,0]
	v_pk_mul_f32 v[100:101], v[98:99], s[62:63] op_sel_hi:[1,0]
	v_pk_mul_f32 v[116:117], v[116:117], s[62:63] op_sel_hi:[1,0]
	v_pk_mul_f32 v[118:119], v[118:119], s[62:63] op_sel_hi:[1,0]
	v_cndmask_b32_e64 v105, v177, 0, s[34:35]
	v_cvt_pk_bf16_f32 v98, v118, v119
	v_cvt_pk_bf16_f32 v99, v116, v117
	v_cvt_pk_bf16_f32 v100, v100, v101
	v_cvt_pk_bf16_f32 v101, v102, v103
	v_cndmask_b32_e64 v103, v175, 0, s[34:35]
	s_nop 1
	v_permlane16_swap_b32 v98, v100
	v_permlane16_swap_b32 v99, v101
	s_nop 1
	v_cndmask_b32_e64 v102, v174, 0, s[34:35]
	v_cndmask_b32_e64 v104, v176, 0, s[34:35]
	global_store_dwordx4 v[110:111], v[98:101], off offset:256
	v_pk_mul_f32 v[106:107], v[92:93], v[104:105]
	v_pk_mul_f32 v[108:109], v[90:91], v[102:103]
	v_cndmask_b32_e64 v99, v173, 1.0, s[34:35]
	v_cndmask_b32_e64 v98, v172, 1.0, s[34:35]
	v_cndmask_b32_e64 v101, v171, 1.0, s[34:35]
	v_cndmask_b32_e64 v100, v170, 1.0, s[34:35]
	v_pk_fma_f32 v[108:109], v[94:95], v[100:101], v[108:109] neg_lo:[0,0,1] neg_hi:[0,0,1]
	v_pk_fma_f32 v[106:107], v[96:97], v[98:99], v[106:107] neg_lo:[0,0,1] neg_hi:[0,0,1]
	v_pk_mul_f32 v[96:97], v[96:97], v[104:105]
	v_pk_mul_f32 v[94:95], v[94:95], v[102:103]
	v_pk_fma_f32 v[92:93], v[92:93], v[98:99], v[96:97]
	v_pk_fma_f32 v[90:91], v[90:91], v[100:101], v[94:95]
	v_or_b32_e32 v110, 32, v226
	v_pk_mul_f32 v[94:95], v[92:93], s[62:63] op_sel_hi:[1,0]
	v_pk_mul_f32 v[92:93], v[90:91], s[62:63] op_sel_hi:[1,0]
	v_pk_mul_f32 v[106:107], v[106:107], s[62:63] op_sel_hi:[1,0]
	v_pk_mul_f32 v[108:109], v[108:109], s[62:63] op_sel_hi:[1,0]
	v_cndmask_b32_e64 v97, v175, 0, s[8:9]
	v_cvt_pk_bf16_f32 v90, v108, v109
	v_cvt_pk_bf16_f32 v91, v106, v107
	v_cvt_pk_bf16_f32 v92, v92, v93
	v_cvt_pk_bf16_f32 v93, v94, v95
	v_mad_i64_i32 v[94:95], s[36:37], v110, s96, v[122:123]
	v_lshl_add_u64 v[94:95], v[94:95], 0, s[6:7]
	v_lshl_add_u64 v[94:95], v[94:95], 0, s[20:21]
	v_lshl_add_u64 v[94:95], v[94:95], 0, v[0:1]
	s_nop 1
	v_permlane16_swap_b32 v90, v92
	v_permlane16_swap_b32 v91, v93
	s_nop 1
	v_lshl_add_u64 v[94:95], v[94:95], 0, v[212:213]
	v_cndmask_b32_e64 v96, v174, 0, s[8:9]
	v_cndmask_b32_e64 v99, v177, 0, s[8:9]
	v_cndmask_b32_e64 v98, v176, 0, s[8:9]
	global_store_dwordx4 v[94:95], v[90:93], off
	v_pk_mul_f32 v[100:101], v[84:85], v[98:99]
	v_pk_mul_f32 v[102:103], v[82:83], v[96:97]
	v_cndmask_b32_e64 v91, v173, 1.0, s[8:9]
	v_cndmask_b32_e64 v90, v172, 1.0, s[8:9]
	v_cndmask_b32_e64 v93, v171, 1.0, s[8:9]
	v_cndmask_b32_e64 v92, v170, 1.0, s[8:9]
	v_pk_fma_f32 v[102:103], v[86:87], v[92:93], v[102:103] neg_lo:[0,0,1] neg_hi:[0,0,1]
	v_pk_fma_f32 v[100:101], v[88:89], v[90:91], v[100:101] neg_lo:[0,0,1] neg_hi:[0,0,1]
	v_pk_mul_f32 v[88:89], v[88:89], v[98:99]
	v_pk_mul_f32 v[86:87], v[86:87], v[96:97]
	v_pk_fma_f32 v[84:85], v[84:85], v[90:91], v[88:89]
	v_pk_fma_f32 v[82:83], v[82:83], v[92:93], v[86:87]
	v_pk_mul_f32 v[86:87], v[84:85], s[62:63] op_sel_hi:[1,0]
	v_pk_mul_f32 v[84:85], v[82:83], s[62:63] op_sel_hi:[1,0]
	v_pk_mul_f32 v[100:101], v[100:101], s[62:63] op_sel_hi:[1,0]
	v_pk_mul_f32 v[102:103], v[102:103], s[62:63] op_sel_hi:[1,0]
	v_cndmask_b32_e64 v89, v165, 0, s[34:35]
	v_cvt_pk_bf16_f32 v82, v102, v103
	v_cvt_pk_bf16_f32 v83, v100, v101
	v_cvt_pk_bf16_f32 v84, v84, v85
	v_cvt_pk_bf16_f32 v85, v86, v87
	v_cndmask_b32_e64 v87, v163, 0, s[34:35]
	s_nop 1
	v_permlane16_swap_b32 v82, v84
	v_permlane16_swap_b32 v83, v85
	s_nop 1
	v_cndmask_b32_e64 v86, v162, 0, s[34:35]
	v_cndmask_b32_e64 v88, v164, 0, s[34:35]
	global_store_dwordx4 v[94:95], v[82:85], off offset:256
	v_pk_mul_f32 v[90:91], v[76:77], v[88:89]
	v_pk_mul_f32 v[92:93], v[74:75], v[86:87]
	v_cndmask_b32_e64 v83, v169, 1.0, s[34:35]
	v_cndmask_b32_e64 v82, v168, 1.0, s[34:35]
	v_cndmask_b32_e64 v85, v167, 1.0, s[34:35]
	v_cndmask_b32_e64 v84, v166, 1.0, s[34:35]
	v_pk_fma_f32 v[92:93], v[78:79], v[84:85], v[92:93] neg_lo:[0,0,1] neg_hi:[0,0,1]
	v_pk_fma_f32 v[90:91], v[80:81], v[82:83], v[90:91] neg_lo:[0,0,1] neg_hi:[0,0,1]
	v_pk_mul_f32 v[80:81], v[80:81], v[88:89]
	v_pk_mul_f32 v[78:79], v[78:79], v[86:87]
	v_pk_fma_f32 v[76:77], v[76:77], v[82:83], v[80:81]
	v_pk_fma_f32 v[74:75], v[74:75], v[84:85], v[78:79]
	v_or_b32_e32 v94, 48, v226
	v_pk_mul_f32 v[78:79], v[76:77], s[62:63] op_sel_hi:[1,0]
	v_pk_mul_f32 v[76:77], v[74:75], s[62:63] op_sel_hi:[1,0]
	v_pk_mul_f32 v[90:91], v[90:91], s[62:63] op_sel_hi:[1,0]
	v_pk_mul_f32 v[92:93], v[92:93], s[62:63] op_sel_hi:[1,0]
	v_cndmask_b32_e64 v81, v163, 0, s[8:9]
	v_cvt_pk_bf16_f32 v74, v92, v93
	v_cvt_pk_bf16_f32 v75, v90, v91
	v_cvt_pk_bf16_f32 v76, v76, v77
	v_cvt_pk_bf16_f32 v77, v78, v79
	v_mad_i64_i32 v[78:79], s[36:37], v94, s96, v[122:123]
	v_lshl_add_u64 v[78:79], v[78:79], 0, s[6:7]
	v_lshl_add_u64 v[78:79], v[78:79], 0, s[20:21]
	v_lshl_add_u64 v[78:79], v[78:79], 0, v[0:1]
	s_nop 1
	v_permlane16_swap_b32 v74, v76
	v_permlane16_swap_b32 v75, v77
	s_nop 1
	v_lshl_add_u64 v[78:79], v[78:79], 0, v[212:213]
	v_cndmask_b32_e64 v80, v162, 0, s[8:9]
	v_cndmask_b32_e64 v83, v165, 0, s[8:9]
	v_cndmask_b32_e64 v82, v164, 0, s[8:9]
	global_store_dwordx4 v[78:79], v[74:77], off
	v_pk_mul_f32 v[84:85], v[68:69], v[82:83]
	v_pk_mul_f32 v[86:87], v[66:67], v[80:81]
	v_cndmask_b32_e64 v75, v169, 1.0, s[8:9]
	v_cndmask_b32_e64 v74, v168, 1.0, s[8:9]
	v_cndmask_b32_e64 v77, v167, 1.0, s[8:9]
	v_cndmask_b32_e64 v76, v166, 1.0, s[8:9]
	v_pk_fma_f32 v[86:87], v[70:71], v[76:77], v[86:87] neg_lo:[0,0,1] neg_hi:[0,0,1]
	v_pk_fma_f32 v[84:85], v[72:73], v[74:75], v[84:85] neg_lo:[0,0,1] neg_hi:[0,0,1]
	v_pk_mul_f32 v[72:73], v[72:73], v[82:83]
	v_pk_mul_f32 v[70:71], v[70:71], v[80:81]
	v_pk_fma_f32 v[68:69], v[68:69], v[74:75], v[72:73]
	v_pk_fma_f32 v[66:67], v[66:67], v[76:77], v[70:71]
	v_pk_mul_f32 v[70:71], v[68:69], s[62:63] op_sel_hi:[1,0]
	v_pk_mul_f32 v[68:69], v[66:67], s[62:63] op_sel_hi:[1,0]
	v_pk_mul_f32 v[84:85], v[84:85], s[62:63] op_sel_hi:[1,0]
	v_pk_mul_f32 v[86:87], v[86:87], s[62:63] op_sel_hi:[1,0]
	v_cndmask_b32_e64 v73, v161, 0, s[34:35]
	v_cvt_pk_bf16_f32 v66, v86, v87
	v_cvt_pk_bf16_f32 v67, v84, v85
	v_cvt_pk_bf16_f32 v68, v68, v69
	v_cvt_pk_bf16_f32 v69, v70, v71
	v_cndmask_b32_e64 v71, v159, 0, s[34:35]
	s_nop 1
	v_permlane16_swap_b32 v66, v68
	v_permlane16_swap_b32 v67, v69
	s_nop 1
	v_cndmask_b32_e64 v70, v158, 0, s[34:35]
	v_cndmask_b32_e64 v72, v160, 0, s[34:35]
	global_store_dwordx4 v[78:79], v[66:69], off offset:256
	v_pk_mul_f32 v[74:75], v[60:61], v[72:73]
	v_pk_mul_f32 v[76:77], v[58:59], v[70:71]
	v_cndmask_b32_e64 v67, v157, 1.0, s[34:35]
	v_cndmask_b32_e64 v66, v156, 1.0, s[34:35]
	v_cndmask_b32_e64 v69, v155, 1.0, s[34:35]
	v_cndmask_b32_e64 v68, v154, 1.0, s[34:35]
	v_pk_fma_f32 v[76:77], v[62:63], v[68:69], v[76:77] neg_lo:[0,0,1] neg_hi:[0,0,1]
	v_pk_fma_f32 v[74:75], v[64:65], v[66:67], v[74:75] neg_lo:[0,0,1] neg_hi:[0,0,1]
	v_pk_mul_f32 v[64:65], v[64:65], v[72:73]
	v_pk_mul_f32 v[62:63], v[62:63], v[70:71]
	v_pk_fma_f32 v[60:61], v[60:61], v[66:67], v[64:65]
	v_pk_fma_f32 v[58:59], v[58:59], v[68:69], v[62:63]
	v_add_u32_e32 v78, 0x80, v226
	v_pk_mul_f32 v[62:63], v[60:61], s[62:63] op_sel_hi:[1,0]
	v_pk_mul_f32 v[60:61], v[58:59], s[62:63] op_sel_hi:[1,0]
	v_pk_mul_f32 v[74:75], v[74:75], s[62:63] op_sel_hi:[1,0]
	v_pk_mul_f32 v[76:77], v[76:77], s[62:63] op_sel_hi:[1,0]
	v_cndmask_b32_e64 v65, v159, 0, s[8:9]
	v_cvt_pk_bf16_f32 v58, v76, v77
	v_cvt_pk_bf16_f32 v59, v74, v75
	v_cvt_pk_bf16_f32 v60, v60, v61
	v_cvt_pk_bf16_f32 v61, v62, v63
	v_mad_i64_i32 v[62:63], s[36:37], v78, s96, v[122:123]
	v_lshl_add_u64 v[62:63], v[62:63], 0, s[6:7]
	v_lshl_add_u64 v[62:63], v[62:63], 0, s[20:21]
	v_lshl_add_u64 v[62:63], v[62:63], 0, v[0:1]
	s_nop 1
	v_permlane16_swap_b32 v58, v60
	v_permlane16_swap_b32 v59, v61
	s_nop 1
	v_lshl_add_u64 v[62:63], v[62:63], 0, v[212:213]
	v_cndmask_b32_e64 v64, v158, 0, s[8:9]
	v_cndmask_b32_e64 v67, v161, 0, s[8:9]
	v_cndmask_b32_e64 v66, v160, 0, s[8:9]
	global_store_dwordx4 v[62:63], v[58:61], off
	v_pk_mul_f32 v[68:69], v[52:53], v[66:67]
	v_pk_mul_f32 v[70:71], v[50:51], v[64:65]
	v_cndmask_b32_e64 v59, v157, 1.0, s[8:9]
	v_cndmask_b32_e64 v58, v156, 1.0, s[8:9]
	v_cndmask_b32_e64 v61, v155, 1.0, s[8:9]
	v_cndmask_b32_e64 v60, v154, 1.0, s[8:9]
	v_pk_fma_f32 v[70:71], v[54:55], v[60:61], v[70:71] neg_lo:[0,0,1] neg_hi:[0,0,1]
	v_pk_fma_f32 v[68:69], v[56:57], v[58:59], v[68:69] neg_lo:[0,0,1] neg_hi:[0,0,1]
	v_pk_mul_f32 v[56:57], v[56:57], v[66:67]
	v_pk_mul_f32 v[54:55], v[54:55], v[64:65]
	v_pk_fma_f32 v[52:53], v[52:53], v[58:59], v[56:57]
	v_pk_fma_f32 v[50:51], v[50:51], v[60:61], v[54:55]
	v_pk_mul_f32 v[54:55], v[52:53], s[62:63] op_sel_hi:[1,0]
	v_pk_mul_f32 v[52:53], v[50:51], s[62:63] op_sel_hi:[1,0]
	v_pk_mul_f32 v[68:69], v[68:69], s[62:63] op_sel_hi:[1,0]
	v_pk_mul_f32 v[70:71], v[70:71], s[62:63] op_sel_hi:[1,0]
	v_cndmask_b32_e64 v57, v149, 0, s[34:35]
	v_cvt_pk_bf16_f32 v50, v70, v71
	v_cvt_pk_bf16_f32 v51, v68, v69
	v_cvt_pk_bf16_f32 v52, v52, v53
	v_cvt_pk_bf16_f32 v53, v54, v55
	v_cndmask_b32_e64 v55, v147, 0, s[34:35]
	s_nop 1
	v_permlane16_swap_b32 v50, v52
	v_permlane16_swap_b32 v51, v53
	s_nop 1
	v_cndmask_b32_e64 v54, v146, 0, s[34:35]
	v_cndmask_b32_e64 v56, v148, 0, s[34:35]
	global_store_dwordx4 v[62:63], v[50:53], off offset:256
	v_pk_mul_f32 v[58:59], v[44:45], v[56:57]
	v_pk_mul_f32 v[60:61], v[42:43], v[54:55]
	v_cndmask_b32_e64 v51, v153, 1.0, s[34:35]
	v_cndmask_b32_e64 v50, v152, 1.0, s[34:35]
	v_cndmask_b32_e64 v53, v151, 1.0, s[34:35]
	v_cndmask_b32_e64 v52, v150, 1.0, s[34:35]
	v_pk_fma_f32 v[60:61], v[46:47], v[52:53], v[60:61] neg_lo:[0,0,1] neg_hi:[0,0,1]
	v_pk_fma_f32 v[58:59], v[48:49], v[50:51], v[58:59] neg_lo:[0,0,1] neg_hi:[0,0,1]
	v_pk_mul_f32 v[48:49], v[48:49], v[56:57]
	v_pk_mul_f32 v[46:47], v[46:47], v[54:55]
	v_pk_fma_f32 v[44:45], v[44:45], v[50:51], v[48:49]
	v_pk_fma_f32 v[42:43], v[42:43], v[52:53], v[46:47]
	v_add_u32_e32 v62, 0x90, v226
	v_pk_mul_f32 v[46:47], v[44:45], s[62:63] op_sel_hi:[1,0]
	v_pk_mul_f32 v[44:45], v[42:43], s[62:63] op_sel_hi:[1,0]
	v_pk_mul_f32 v[58:59], v[58:59], s[62:63] op_sel_hi:[1,0]
	v_pk_mul_f32 v[60:61], v[60:61], s[62:63] op_sel_hi:[1,0]
	v_cndmask_b32_e64 v49, v147, 0, s[8:9]
	v_cvt_pk_bf16_f32 v42, v60, v61
	v_cvt_pk_bf16_f32 v43, v58, v59
	v_cvt_pk_bf16_f32 v44, v44, v45
	v_cvt_pk_bf16_f32 v45, v46, v47
	v_mad_i64_i32 v[46:47], s[36:37], v62, s96, v[122:123]
	v_lshl_add_u64 v[46:47], v[46:47], 0, s[6:7]
	v_lshl_add_u64 v[46:47], v[46:47], 0, s[20:21]
	v_lshl_add_u64 v[46:47], v[46:47], 0, v[0:1]
	s_nop 1
	v_permlane16_swap_b32 v42, v44
	v_permlane16_swap_b32 v43, v45
	s_nop 1
	v_lshl_add_u64 v[46:47], v[46:47], 0, v[212:213]
	v_cndmask_b32_e64 v48, v146, 0, s[8:9]
	v_cndmask_b32_e64 v51, v149, 0, s[8:9]
	v_cndmask_b32_e64 v50, v148, 0, s[8:9]
	global_store_dwordx4 v[46:47], v[42:45], off
	v_pk_mul_f32 v[52:53], v[36:37], v[50:51]
	v_pk_mul_f32 v[54:55], v[34:35], v[48:49]
	v_cndmask_b32_e64 v43, v153, 1.0, s[8:9]
	v_cndmask_b32_e64 v42, v152, 1.0, s[8:9]
	v_cndmask_b32_e64 v45, v151, 1.0, s[8:9]
	v_cndmask_b32_e64 v44, v150, 1.0, s[8:9]
	v_pk_fma_f32 v[54:55], v[38:39], v[44:45], v[54:55] neg_lo:[0,0,1] neg_hi:[0,0,1]
	v_pk_fma_f32 v[52:53], v[40:41], v[42:43], v[52:53] neg_lo:[0,0,1] neg_hi:[0,0,1]
	v_pk_mul_f32 v[40:41], v[40:41], v[50:51]
	v_pk_mul_f32 v[38:39], v[38:39], v[48:49]
	v_pk_fma_f32 v[36:37], v[36:37], v[42:43], v[40:41]
	v_pk_fma_f32 v[34:35], v[34:35], v[44:45], v[38:39]
	v_pk_mul_f32 v[38:39], v[36:37], s[62:63] op_sel_hi:[1,0]
	v_pk_mul_f32 v[36:37], v[34:35], s[62:63] op_sel_hi:[1,0]
	v_pk_mul_f32 v[52:53], v[52:53], s[62:63] op_sel_hi:[1,0]
	v_pk_mul_f32 v[54:55], v[54:55], s[62:63] op_sel_hi:[1,0]
	v_cndmask_b32_e64 v41, v145, 0, s[34:35]
	v_cvt_pk_bf16_f32 v34, v54, v55
	v_cvt_pk_bf16_f32 v35, v52, v53
	v_cvt_pk_bf16_f32 v36, v36, v37
	v_cvt_pk_bf16_f32 v37, v38, v39
	v_cndmask_b32_e64 v39, v143, 0, s[34:35]
	s_nop 1
	v_permlane16_swap_b32 v34, v36
	v_permlane16_swap_b32 v35, v37
	s_nop 1
	v_cndmask_b32_e64 v38, v142, 0, s[34:35]
	v_cndmask_b32_e64 v40, v144, 0, s[34:35]
	global_store_dwordx4 v[46:47], v[34:37], off offset:256
	v_pk_mul_f32 v[42:43], v[28:29], v[40:41]
	v_pk_mul_f32 v[44:45], v[26:27], v[38:39]
	v_cndmask_b32_e64 v35, v141, 1.0, s[34:35]
	v_cndmask_b32_e64 v34, v140, 1.0, s[34:35]
	v_cndmask_b32_e64 v37, v139, 1.0, s[34:35]
	v_cndmask_b32_e64 v36, v138, 1.0, s[34:35]
	v_pk_fma_f32 v[44:45], v[30:31], v[36:37], v[44:45] neg_lo:[0,0,1] neg_hi:[0,0,1]
	v_pk_fma_f32 v[42:43], v[32:33], v[34:35], v[42:43] neg_lo:[0,0,1] neg_hi:[0,0,1]
	v_pk_mul_f32 v[32:33], v[32:33], v[40:41]
	v_pk_mul_f32 v[30:31], v[30:31], v[38:39]
	v_pk_fma_f32 v[28:29], v[28:29], v[34:35], v[32:33]
	v_pk_fma_f32 v[26:27], v[26:27], v[36:37], v[30:31]
	v_add_u32_e32 v46, 0xa0, v226
	v_pk_mul_f32 v[30:31], v[28:29], s[62:63] op_sel_hi:[1,0]
	v_pk_mul_f32 v[28:29], v[26:27], s[62:63] op_sel_hi:[1,0]
	v_pk_mul_f32 v[42:43], v[42:43], s[62:63] op_sel_hi:[1,0]
	v_pk_mul_f32 v[44:45], v[44:45], s[62:63] op_sel_hi:[1,0]
	v_cndmask_b32_e64 v33, v143, 0, s[8:9]
	v_cvt_pk_bf16_f32 v26, v44, v45
	v_cvt_pk_bf16_f32 v27, v42, v43
	v_cvt_pk_bf16_f32 v28, v28, v29
	v_cvt_pk_bf16_f32 v29, v30, v31
	v_mad_i64_i32 v[30:31], s[36:37], v46, s96, v[122:123]
	v_lshl_add_u64 v[30:31], v[30:31], 0, s[6:7]
	v_lshl_add_u64 v[30:31], v[30:31], 0, s[20:21]
	v_lshl_add_u64 v[30:31], v[30:31], 0, v[0:1]
	s_nop 1
	v_permlane16_swap_b32 v26, v28
	v_permlane16_swap_b32 v27, v29
	s_nop 1
	v_lshl_add_u64 v[30:31], v[30:31], 0, v[212:213]
	v_cndmask_b32_e64 v32, v142, 0, s[8:9]
	v_cndmask_b32_e64 v35, v145, 0, s[8:9]
	v_cndmask_b32_e64 v34, v144, 0, s[8:9]
	global_store_dwordx4 v[30:31], v[26:29], off
	v_pk_mul_f32 v[36:37], v[20:21], v[34:35]
	v_pk_mul_f32 v[38:39], v[18:19], v[32:33]
	v_cndmask_b32_e64 v27, v141, 1.0, s[8:9]
	v_cndmask_b32_e64 v26, v140, 1.0, s[8:9]
	v_cndmask_b32_e64 v29, v139, 1.0, s[8:9]
	v_cndmask_b32_e64 v28, v138, 1.0, s[8:9]
	v_pk_fma_f32 v[38:39], v[22:23], v[28:29], v[38:39] neg_lo:[0,0,1] neg_hi:[0,0,1]
	v_pk_fma_f32 v[36:37], v[24:25], v[26:27], v[36:37] neg_lo:[0,0,1] neg_hi:[0,0,1]
	v_pk_mul_f32 v[24:25], v[24:25], v[34:35]
	v_pk_mul_f32 v[22:23], v[22:23], v[32:33]
	v_pk_fma_f32 v[20:21], v[20:21], v[26:27], v[24:25]
	v_pk_fma_f32 v[18:19], v[18:19], v[28:29], v[22:23]
	v_pk_mul_f32 v[22:23], v[20:21], s[62:63] op_sel_hi:[1,0]
	v_pk_mul_f32 v[20:21], v[18:19], s[62:63] op_sel_hi:[1,0]
	v_pk_mul_f32 v[36:37], v[36:37], s[62:63] op_sel_hi:[1,0]
	v_pk_mul_f32 v[38:39], v[38:39], s[62:63] op_sel_hi:[1,0]
	v_cndmask_b32_e64 v25, v133, 0, s[34:35]
	v_cvt_pk_bf16_f32 v18, v38, v39
	v_cvt_pk_bf16_f32 v19, v36, v37
	v_cvt_pk_bf16_f32 v20, v20, v21
	v_cvt_pk_bf16_f32 v21, v22, v23
	v_cndmask_b32_e64 v23, v131, 0, s[34:35]
	s_nop 1
	v_permlane16_swap_b32 v18, v20
	v_permlane16_swap_b32 v19, v21
	s_nop 1
	v_cndmask_b32_e64 v22, v130, 0, s[34:35]
	v_cndmask_b32_e64 v24, v132, 0, s[34:35]
	global_store_dwordx4 v[30:31], v[18:21], off offset:256
	v_pk_mul_f32 v[26:27], v[12:13], v[24:25]
	v_pk_mul_f32 v[28:29], v[10:11], v[22:23]
	v_cndmask_b32_e64 v19, v137, 1.0, s[34:35]
	v_cndmask_b32_e64 v18, v136, 1.0, s[34:35]
	v_cndmask_b32_e64 v21, v135, 1.0, s[34:35]
	v_cndmask_b32_e64 v20, v134, 1.0, s[34:35]
	v_pk_fma_f32 v[28:29], v[14:15], v[20:21], v[28:29] neg_lo:[0,0,1] neg_hi:[0,0,1]
	v_pk_fma_f32 v[26:27], v[16:17], v[18:19], v[26:27] neg_lo:[0,0,1] neg_hi:[0,0,1]
	v_pk_mul_f32 v[16:17], v[16:17], v[24:25]
	v_pk_mul_f32 v[14:15], v[14:15], v[22:23]
	v_pk_fma_f32 v[12:13], v[12:13], v[18:19], v[16:17]
	v_pk_fma_f32 v[10:11], v[10:11], v[20:21], v[14:15]
	v_add_u32_e32 v30, 0xb0, v226
	v_pk_mul_f32 v[14:15], v[12:13], s[62:63] op_sel_hi:[1,0]
	v_pk_mul_f32 v[12:13], v[10:11], s[62:63] op_sel_hi:[1,0]
	v_pk_mul_f32 v[26:27], v[26:27], s[62:63] op_sel_hi:[1,0]
	v_pk_mul_f32 v[28:29], v[28:29], s[62:63] op_sel_hi:[1,0]
	v_cndmask_b32_e64 v17, v133, 0, s[8:9]
	v_cvt_pk_bf16_f32 v10, v28, v29
	v_cvt_pk_bf16_f32 v11, v26, v27
	v_cvt_pk_bf16_f32 v12, v12, v13
	v_cvt_pk_bf16_f32 v13, v14, v15
	v_mad_i64_i32 v[14:15], s[34:35], v30, s96, v[122:123]
	v_lshl_add_u64 v[14:15], v[14:15], 0, s[6:7]
	v_lshl_add_u64 v[14:15], v[14:15], 0, s[20:21]
	v_lshl_add_u64 v[14:15], v[14:15], 0, v[0:1]
	s_nop 1
	v_permlane16_swap_b32 v10, v12
	v_permlane16_swap_b32 v11, v13
	s_nop 1
	v_lshl_add_u64 v[138:139], v[14:15], 0, v[212:213]
	v_cndmask_b32_e64 v15, v131, 0, s[8:9]
	v_cndmask_b32_e64 v14, v130, 0, s[8:9]
	v_cndmask_b32_e64 v16, v132, 0, s[8:9]
	global_store_dwordx4 v[138:139], v[10:13], off
	v_pk_mul_f32 v[18:19], v[4:5], v[16:17]
	v_pk_mul_f32 v[20:21], v[2:3], v[14:15]
	v_cndmask_b32_e64 v11, v137, 1.0, s[8:9]
	v_cndmask_b32_e64 v10, v136, 1.0, s[8:9]
	v_cndmask_b32_e64 v13, v135, 1.0, s[8:9]
	v_cndmask_b32_e64 v12, v134, 1.0, s[8:9]
	v_pk_fma_f32 v[20:21], v[6:7], v[12:13], v[20:21] neg_lo:[0,0,1] neg_hi:[0,0,1]
	v_pk_fma_f32 v[18:19], v[8:9], v[10:11], v[18:19] neg_lo:[0,0,1] neg_hi:[0,0,1]
	v_pk_mul_f32 v[8:9], v[8:9], v[16:17]
	v_pk_mul_f32 v[6:7], v[6:7], v[14:15]
	v_pk_fma_f32 v[4:5], v[4:5], v[10:11], v[8:9]
	v_pk_fma_f32 v[2:3], v[2:3], v[12:13], v[6:7]
	v_pk_mul_f32 v[18:19], v[18:19], s[62:63] op_sel_hi:[1,0]
	v_pk_mul_f32 v[20:21], v[20:21], s[62:63] op_sel_hi:[1,0]
	v_pk_mul_f32 v[4:5], v[4:5], s[62:63] op_sel_hi:[1,0]
	v_pk_mul_f32 v[2:3], v[2:3], s[62:63] op_sel_hi:[1,0]
	v_cvt_pk_bf16_f32 v130, v20, v21
	v_cvt_pk_bf16_f32 v131, v18, v19
	s_nop 0
	v_cvt_pk_bf16_f32 v132, v2, v3
	v_cvt_pk_bf16_f32 v133, v4, v5
	s_nop 0
	s_nop 1
	v_permlane16_swap_b32 v130, v132
	v_permlane16_swap_b32 v131, v133
	s_nop 1
	s_andn2_b64 vcc, exec, s[22:23]
	s_mov_b64 s[6:7], -1
	global_store_dwordx4 v[138:139], v[130:133], off offset:256
	s_cbranch_vccnz .LBB0_423

.LBB0_540:
	ds_bpermute_b32 v0, v231, v239
	s_mulk_i32 s69, 0x1300
	s_add_i32 s10, s69, 0
	s_add_i32 s10, s10, 0x16800
	v_mov_b32_e32 v217, v1
	s_waitcnt lgkmcnt(0)
	v_add_f32_e32 v0, v239, v0
	v_div_scale_f32 v66, s[8:9], v0, v0, 1.0
	v_rcp_f32_e32 v67, v66
	v_div_scale_f32 v68, vcc, 1.0, v0, 1.0
	s_ashr_i32 s8, s67, 2
	v_fma_f32 v69, -v66, v67, 1.0
	v_fmac_f32_e32 v67, v69, v67
	v_mul_f32_e32 v69, v68, v67
	v_fma_f32 v70, -v66, v69, v68
	v_fmac_f32_e32 v69, v70, v67
	v_fma_f32 v66, -v66, v69, v68
	v_div_fmas_f32 v66, v66, v67, v69
	v_div_fixup_f32 v66, v66, v0, 1.0
	v_mul_f32_e32 v0, v50, v66
	v_mul_f32_e32 v50, v51, v66
	v_mul_f32_e32 v51, v52, v66
	v_mul_f32_e32 v52, v53, v66
	v_cvt_pk_bf16_f32 v50, v0, v50
	v_mul_u32_u24_e32 v0, 0x90, v203
	v_cvt_pk_bf16_f32 v51, v51, v52
	v_add3_u32 v52, s10, v0, v182
	ds_write_b64 v52, v[50:51]
	v_mul_f32_e32 v50, v55, v66
	v_mul_f32_e32 v0, v54, v66
	v_mul_f32_e32 v51, v56, v66
	v_cvt_pk_bf16_f32 v50, v0, v50
	v_mul_f32_e32 v53, v57, v66
	v_cvt_pk_bf16_f32 v51, v51, v53
	ds_write_b64 v52, v[50:51] offset:16
	v_mul_f32_e32 v50, v59, v66
	v_mul_f32_e32 v0, v58, v66
	v_mul_f32_e32 v51, v60, v66
	v_cvt_pk_bf16_f32 v50, v0, v50
	v_mul_f32_e32 v53, v61, v66
	v_cvt_pk_bf16_f32 v51, v51, v53
	ds_write_b64 v52, v[50:51] offset:32
	v_mul_f32_e32 v0, v62, v66
	v_mul_f32_e32 v50, v63, v66
	v_mul_f32_e32 v51, v64, v66
	v_cvt_pk_bf16_f32 v50, v0, v50
	v_mul_f32_e32 v0, v34, v66
	v_mul_f32_e32 v34, v35, v66
	v_mul_f32_e32 v53, v65, v66
	v_cvt_pk_bf16_f32 v51, v51, v53
	ds_write_b64 v52, v[50:51] offset:48
	v_mul_f32_e32 v35, v36, v66
	v_cvt_pk_bf16_f32 v34, v0, v34
	v_mul_f32_e32 v36, v37, v66
	v_cvt_pk_bf16_f32 v35, v35, v36
	ds_write_b64 v52, v[34:35] offset:64
	v_mul_f32_e32 v34, v39, v66
	v_mul_f32_e32 v0, v38, v66
	v_mul_f32_e32 v35, v40, v66
	v_cvt_pk_bf16_f32 v34, v0, v34
	v_mul_f32_e32 v36, v41, v66
	v_cvt_pk_bf16_f32 v35, v35, v36
	ds_write_b64 v52, v[34:35] offset:80
	v_mul_f32_e32 v34, v43, v66
	v_mul_f32_e32 v0, v42, v66
	v_mul_f32_e32 v35, v44, v66
	v_cvt_pk_bf16_f32 v34, v0, v34
	v_mul_f32_e32 v36, v45, v66
	v_cvt_pk_bf16_f32 v35, v35, v36
	ds_write_b64 v52, v[34:35] offset:96
	v_mul_f32_e32 v0, v46, v66
	v_mul_f32_e32 v34, v47, v66
	v_cvt_pk_bf16_f32 v34, v0, v34
	v_mul_u32_u24_e32 v0, 0x90, v232
	v_mul_f32_e32 v35, v48, v66
	v_add3_u32 v53, s10, v226, v0
	v_or_b32_e32 v0, s65, v232
	s_and_b32 s8, s8, 0xffffff80
	v_mul_f32_e32 v36, v49, v66
	v_cvt_pk_bf16_f32 v35, v35, v36
	ds_write_b64 v52, v[34:35] offset:112
	v_lshlrev_b32_e32 v0, 12, v0
	s_ashr_i32 s9, s8, 31
	s_waitcnt lgkmcnt(0)
	v_lshl_add_u64 v[50:51], s[6:7], 0, v[0:1]
	s_lshl_b64 s[8:9], s[8:9], 1
	v_or_b32_e32 v0, 8, v232
	ds_read_b128 v[34:37], v53
	ds_read_b128 v[38:41], v53 offset:1152
	ds_read_b128 v[42:45], v53 offset:2304
	ds_read_b128 v[46:49], v53 offset:3456
	v_lshl_add_u64 v[50:51], v[50:51], 0, s[8:9]
	v_or_b32_e32 v0, s65, v0
	v_lshl_add_u64 v[50:51], v[50:51], 0, v[216:217]
	v_lshlrev_b32_e32 v0, 12, v0
	s_waitcnt lgkmcnt(0)
	s_waitcnt lgkmcnt(3)
	global_store_dwordx4 v[50:51], v[34:37], off
	s_andn2_b64 vcc, exec, s[22:23]
	v_mov_b64_e32 v[240:241], v[236:237]
	v_lshl_add_u64 v[34:35], s[6:7], 0, v[0:1]
	v_or_b32_e32 v0, 16, v232
	v_or_b32_e32 v0, s65, v0
	v_lshlrev_b32_e32 v0, 12, v0
	v_lshl_add_u64 v[36:37], s[6:7], 0, v[0:1]
	v_or_b32_e32 v0, 24, v232
	v_lshl_add_u64 v[34:35], v[34:35], 0, s[8:9]
	v_or_b32_e32 v0, s65, v0
	v_lshl_add_u64 v[34:35], v[34:35], 0, v[216:217]
	v_lshlrev_b32_e32 v0, 12, v0
	s_waitcnt lgkmcnt(2)
	global_store_dwordx4 v[34:35], v[38:41], off
	v_lshl_add_u64 v[36:37], v[36:37], 0, s[8:9]
	v_lshl_add_u64 v[36:37], v[36:37], 0, v[216:217]
	v_lshl_add_u64 v[38:39], s[6:7], 0, v[0:1]
	v_lshl_add_u64 v[38:39], v[38:39], 0, s[8:9]
	v_lshl_add_u64 v[38:39], v[38:39], 0, v[216:217]
	v_mul_f32_e32 v0, v18, v66
	v_mul_f32_e32 v18, v19, v66
	s_waitcnt lgkmcnt(1)
	global_store_dwordx4 v[36:37], v[42:45], off
	s_waitcnt lgkmcnt(0)
	global_store_dwordx4 v[38:39], v[46:49], off
	v_mul_f32_e32 v19, v20, v66
	v_cvt_pk_bf16_f32 v18, v0, v18
	v_mul_f32_e32 v20, v21, v66
	v_cvt_pk_bf16_f32 v19, v19, v20
	ds_write_b64 v52, v[18:19]
	v_mul_f32_e32 v18, v23, v66
	v_mul_f32_e32 v0, v22, v66
	v_mul_f32_e32 v19, v24, v66
	v_cvt_pk_bf16_f32 v18, v0, v18
	v_mul_f32_e32 v20, v25, v66
	v_cvt_pk_bf16_f32 v19, v19, v20
	ds_write_b64 v52, v[18:19] offset:16
	v_mul_f32_e32 v18, v27, v66
	v_mul_f32_e32 v0, v26, v66
	v_mul_f32_e32 v19, v28, v66
	v_cvt_pk_bf16_f32 v18, v0, v18
	v_mul_f32_e32 v20, v29, v66
	v_cvt_pk_bf16_f32 v19, v19, v20
	ds_write_b64 v52, v[18:19] offset:32
	v_mul_f32_e32 v0, v30, v66
	v_mul_f32_e32 v18, v31, v66
	v_mul_f32_e32 v19, v32, v66
	v_cvt_pk_bf16_f32 v18, v0, v18
	v_mul_f32_e32 v0, v2, v66
	v_mul_f32_e32 v2, v3, v66
	v_mul_f32_e32 v3, v4, v66
	v_mul_f32_e32 v20, v33, v66
	v_cvt_pk_bf16_f32 v19, v19, v20
	ds_write_b64 v52, v[18:19] offset:48
	v_mul_f32_e32 v4, v5, v66
	v_cvt_pk_bf16_f32 v2, v0, v2
	v_cvt_pk_bf16_f32 v3, v3, v4
	ds_write_b64 v52, v[2:3] offset:64
	v_mul_f32_e32 v2, v7, v66
	v_mul_f32_e32 v3, v8, v66
	v_mul_f32_e32 v0, v6, v66
	v_mul_f32_e32 v4, v9, v66
	v_cvt_pk_bf16_f32 v2, v0, v2
	v_cvt_pk_bf16_f32 v3, v3, v4
	ds_write_b64 v52, v[2:3] offset:80
	v_mul_f32_e32 v2, v11, v66
	v_mul_f32_e32 v3, v12, v66
	v_mul_f32_e32 v0, v10, v66
	v_mul_f32_e32 v4, v13, v66
	v_cvt_pk_bf16_f32 v2, v0, v2
	v_cvt_pk_bf16_f32 v3, v3, v4
	ds_write_b64 v52, v[2:3] offset:96
	v_mul_f32_e32 v2, v15, v66
	v_mul_f32_e32 v3, v16, v66
	v_mul_f32_e32 v0, v14, v66
	v_mul_f32_e32 v4, v17, v66
	v_cvt_pk_bf16_f32 v2, v0, v2
	v_cvt_pk_bf16_f32 v3, v3, v4
	ds_write_b64 v52, v[2:3] offset:112
	s_waitcnt lgkmcnt(0)
	ds_read_b128 v[2:5], v53
	ds_read_b128 v[6:9], v53 offset:1152
	ds_read_b128 v[10:13], v53 offset:2304
	ds_read_b128 v[14:17], v53 offset:3456
	s_waitcnt lgkmcnt(0)
	s_waitcnt lgkmcnt(3)
	global_store_dwordx4 v[50:51], v[2:5], off offset:128
	s_waitcnt lgkmcnt(2)
	global_store_dwordx4 v[34:35], v[6:9], off offset:128
	s_waitcnt lgkmcnt(1)
	global_store_dwordx4 v[36:37], v[10:13], off offset:128
	s_waitcnt lgkmcnt(0)
	global_store_dwordx4 v[38:39], v[14:17], off offset:128
	s_cbranch_vccnz .LBB0_508
	s_barrier
	s_branch .LBB0_508

.LBB0_631:
	s_ashr_i32 s83, s82, 31
	s_lshl_b64 s[10:11], s[82:83], 1
	s_add_u32 s10, s86, s10
	s_addc_u32 s11, s87, s11
	s_add_u32 s10, s10, s94
	s_addc_u32 s11, s11, 0
	v_add_u32_e32 v202, s82, v229
	s_cmp_eq_u64 s[84:85], 0
	v_or_b32_e32 v234, s31, v227
	v_lshl_add_u64 v[204:205], s[10:11], 0, v[0:1]
	v_mov_b32_e32 v213, v1
	s_cselect_b64 s[10:11], -1, 0
	v_ashrrev_i32_e32 v203, 31, v202
	v_lshl_add_u64 v[214:215], v[204:205], 0, v[212:213]
	s_or_b64 s[10:11], s[78:79], s[10:11]
	v_lshl_add_u64 v[216:217], v[202:203], 2, s[84:85]
	v_mad_i64_i32 v[202:203], s[78:79], s80, v234, 0
	v_lshl_add_u64 v[220:221], v[202:203], 1, v[214:215]
	v_lshlrev_b32_e32 v202, 11, v234
	v_and_b32_e32 v202, 0x67800, v202
	v_mov_b32_e32 v203, v1
	v_lshl_add_u64 v[218:219], v[216:217], 0, v[202:203]
	s_waitcnt vmcnt(0)
	v_pk_mul_f32 v[202:203], v[124:125], v[192:193]
	v_pk_mul_f32 v[204:205], v[122:123], v[190:191]
	v_pk_fma_f32 v[202:203], v[132:133], v[188:189], v[202:203] neg_lo:[0,0,1] neg_hi:[0,0,1]
	v_pk_fma_f32 v[204:205], v[130:131], v[186:187], v[204:205] neg_lo:[0,0,1] neg_hi:[0,0,1]
	v_pk_mul_f32 v[132:133], v[132:133], v[192:193]
	v_pk_mul_f32 v[130:131], v[130:131], v[190:191]
	v_pk_fma_f32 v[132:133], v[124:125], v[188:189], v[132:133]
	v_pk_fma_f32 v[130:131], v[122:123], v[186:187], v[130:131]
	s_ashr_i32 s31, s31, 7
	v_pk_mul_f32 v[124:125], v[202:203], s[64:65] op_sel_hi:[1,0]
	v_pk_mul_f32 v[122:123], v[204:205], s[64:65] op_sel_hi:[1,0]
	v_pk_mul_f32 v[206:207], v[132:133], s[64:65] op_sel_hi:[1,0]
	v_pk_mul_f32 v[222:223], v[130:131], s[64:65] op_sel_hi:[1,0]
	s_and_b32 s31, s31, -2
	v_cndmask_b32_e64 v123, v205, v123, s[8:9]
	v_cndmask_b32_e64 v122, v204, v122, s[8:9]
	v_cndmask_b32_e64 v125, v203, v125, s[8:9]
	v_cndmask_b32_e64 v124, v202, v124, s[8:9]
	v_cndmask_b32_e64 v131, v131, v223, s[8:9]
	v_cndmask_b32_e64 v130, v130, v222, s[8:9]
	v_cndmask_b32_e64 v133, v133, v207, s[8:9]
	v_cndmask_b32_e64 v132, v132, v206, s[8:9]
	v_cvt_pk_bf16_f32 v236, v122, v123
	v_cvt_pk_bf16_f32 v237, v124, v125
	v_cvt_pk_bf16_f32 v238, v130, v131
	v_cvt_pk_bf16_f32 v239, v132, v133
	s_and_b64 vcc, exec, s[10:11]
	s_nop 1
	v_permlane16_swap_b32 v236, v238
	v_permlane16_swap_b32 v237, v239
	s_nop 1
	global_store_dwordx4 v[220:221], v[236:239], off
	s_cbranch_vccnz .LBB0_633
	s_or_b32 s78, s31, s76
	s_ashr_i32 s79, s78, 31
	s_lshl_b64 s[78:79], s[78:79], 19
	v_lshl_add_u64 v[202:203], v[218:219], 0, s[78:79]
	global_store_dwordx4 v[202:203], v[122:125], off
	global_store_dwordx4 v[202:203], v[130:133], off offset:64
.LBB0_633:
	s_nop 0
	v_pk_mul_f32 v[124:125], v[114:115], v[190:191]
	v_pk_mul_f32 v[122:123], v[116:117], v[192:193]
	v_pk_fma_f32 v[124:125], v[118:119], v[186:187], v[124:125] neg_lo:[0,0,1] neg_hi:[0,0,1]
	v_pk_mul_f32 v[118:119], v[118:119], v[190:191]
	v_pk_fma_f32 v[122:123], v[120:121], v[188:189], v[122:123] neg_lo:[0,0,1] neg_hi:[0,0,1]
	v_pk_mul_f32 v[120:121], v[120:121], v[192:193]
	v_pk_fma_f32 v[118:119], v[114:115], v[186:187], v[118:119]
	v_pk_fma_f32 v[120:121], v[116:117], v[188:189], v[120:121]
	v_pk_mul_f32 v[130:131], v[118:119], s[64:65] op_sel_hi:[1,0]
	s_xor_b64 s[78:79], s[10:11], -1
	v_pk_mul_f32 v[114:115], v[124:125], s[64:65] op_sel_hi:[1,0]
	v_pk_mul_f32 v[116:117], v[122:123], s[64:65] op_sel_hi:[1,0]
	v_pk_mul_f32 v[132:133], v[120:121], s[64:65] op_sel_hi:[1,0]
	v_cndmask_b32_e64 v118, v118, v130, s[8:9]
	v_cndmask_b32_e64 v130, 0, 1, s[78:79]
	v_cndmask_b32_e64 v117, v123, v117, s[8:9]
	v_cndmask_b32_e64 v116, v122, v116, s[8:9]
	v_cndmask_b32_e64 v115, v125, v115, s[8:9]
	v_cndmask_b32_e64 v114, v124, v114, s[8:9]
	v_cndmask_b32_e64 v121, v121, v133, s[8:9]
	v_cndmask_b32_e64 v120, v120, v132, s[8:9]
	v_cndmask_b32_e64 v119, v119, v131, s[8:9]
	v_cvt_pk_bf16_f32 v122, v114, v115
	v_cvt_pk_bf16_f32 v123, v116, v117
	v_cvt_pk_bf16_f32 v124, v118, v119
	v_cvt_pk_bf16_f32 v125, v120, v121
	v_cmp_ne_u32_e64 s[10:11], 1, v130
	s_andn2_b64 vcc, exec, s[78:79]
	s_nop 1
	v_permlane16_swap_b32 v122, v124
	v_permlane16_swap_b32 v123, v125
	s_nop 1
	global_store_dwordx4 v[220:221], v[122:125], off offset:256
	s_cbranch_vccnz .LBB0_635
	s_or_b32 s78, s31, s76
	s_ashr_i32 s79, s78, 31
	s_lshl_b64 s[78:79], s[78:79], 19
	v_lshl_add_u64 v[122:123], v[218:219], 0, s[78:79]
	global_store_dwordx4 v[122:123], v[114:117], off offset:512
	global_store_dwordx4 v[122:123], v[118:121], off offset:576
.LBB0_635:
	s_nop 1
	v_or_b32_e32 v118, 16, v234
	v_mad_i64_i32 v[114:115], s[78:79], s80, v118, 0
	v_lshl_add_u64 v[116:117], v[114:115], 1, v[214:215]
	v_lshlrev_b32_e32 v114, 11, v118
	v_pk_mul_f32 v[118:119], v[108:109], v[184:185]
	v_pk_mul_f32 v[120:121], v[106:107], v[182:183]
	v_pk_fma_f32 v[118:119], v[112:113], v[180:181], v[118:119] neg_lo:[0,0,1] neg_hi:[0,0,1]
	v_pk_fma_f32 v[120:121], v[110:111], v[178:179], v[120:121] neg_lo:[0,0,1] neg_hi:[0,0,1]
	v_pk_mul_f32 v[112:113], v[112:113], v[184:185]
	v_pk_mul_f32 v[110:111], v[110:111], v[182:183]
	v_pk_fma_f32 v[112:113], v[108:109], v[180:181], v[112:113]
	v_pk_fma_f32 v[110:111], v[106:107], v[178:179], v[110:111]
	v_and_b32_e32 v114, 0x6f800, v114
	v_mov_b32_e32 v115, v1
	v_pk_mul_f32 v[108:109], v[118:119], s[64:65] op_sel_hi:[1,0]
	v_pk_mul_f32 v[106:107], v[120:121], s[64:65] op_sel_hi:[1,0]
	v_pk_mul_f32 v[122:123], v[112:113], s[64:65] op_sel_hi:[1,0]
	v_pk_mul_f32 v[124:125], v[110:111], s[64:65] op_sel_hi:[1,0]
	v_lshl_add_u64 v[114:115], v[216:217], 0, v[114:115]
	v_cndmask_b32_e64 v107, v121, v107, s[8:9]
	v_cndmask_b32_e64 v106, v120, v106, s[8:9]
	v_cndmask_b32_e64 v109, v119, v109, s[8:9]
	v_cndmask_b32_e64 v108, v118, v108, s[8:9]
	v_cndmask_b32_e64 v111, v111, v125, s[8:9]
	v_cndmask_b32_e64 v110, v110, v124, s[8:9]
	v_cndmask_b32_e64 v113, v113, v123, s[8:9]
	v_cndmask_b32_e64 v112, v112, v122, s[8:9]
	v_cvt_pk_bf16_f32 v118, v106, v107
	v_cvt_pk_bf16_f32 v119, v108, v109
	v_cvt_pk_bf16_f32 v120, v110, v111
	v_cvt_pk_bf16_f32 v121, v112, v113
	s_and_b64 vcc, exec, s[10:11]
	s_nop 1
	v_permlane16_swap_b32 v118, v120
	v_permlane16_swap_b32 v119, v121
	s_nop 1
	global_store_dwordx4 v[116:117], v[118:121], off
	s_cbranch_vccnz .LBB0_637
	s_or_b32 s78, s31, s76
	s_ashr_i32 s79, s78, 31
	s_lshl_b64 s[78:79], s[78:79], 19
	v_lshl_add_u64 v[118:119], v[114:115], 0, s[78:79]
	global_store_dwordx4 v[118:119], v[106:109], off
	global_store_dwordx4 v[118:119], v[110:113], off offset:64
.LBB0_637:
	s_nop 0
	v_pk_mul_f32 v[106:107], v[100:101], v[184:185]
	v_pk_mul_f32 v[108:109], v[98:99], v[182:183]
	v_pk_fma_f32 v[106:107], v[104:105], v[180:181], v[106:107] neg_lo:[0,0,1] neg_hi:[0,0,1]
	v_pk_fma_f32 v[108:109], v[102:103], v[178:179], v[108:109] neg_lo:[0,0,1] neg_hi:[0,0,1]
	v_pk_mul_f32 v[104:105], v[104:105], v[184:185]
	v_pk_mul_f32 v[102:103], v[102:103], v[182:183]
	v_pk_fma_f32 v[104:105], v[100:101], v[180:181], v[104:105]
	v_pk_fma_f32 v[102:103], v[98:99], v[178:179], v[102:103]
	v_pk_mul_f32 v[98:99], v[108:109], s[64:65] op_sel_hi:[1,0]
	v_pk_mul_f32 v[100:101], v[106:107], s[64:65] op_sel_hi:[1,0]
	v_pk_mul_f32 v[110:111], v[102:103], s[64:65] op_sel_hi:[1,0]
	v_pk_mul_f32 v[112:113], v[104:105], s[64:65] op_sel_hi:[1,0]
	v_cndmask_b32_e64 v101, v107, v101, s[8:9]
	v_cndmask_b32_e64 v100, v106, v100, s[8:9]
	v_cndmask_b32_e64 v99, v109, v99, s[8:9]
	v_cndmask_b32_e64 v98, v108, v98, s[8:9]
	v_cndmask_b32_e64 v105, v105, v113, s[8:9]
	v_cndmask_b32_e64 v104, v104, v112, s[8:9]
	v_cndmask_b32_e64 v103, v103, v111, s[8:9]
	v_cndmask_b32_e64 v102, v102, v110, s[8:9]
	v_cvt_pk_bf16_f32 v106, v98, v99
	v_cvt_pk_bf16_f32 v107, v100, v101
	v_cvt_pk_bf16_f32 v108, v102, v103
	v_cvt_pk_bf16_f32 v109, v104, v105
	s_and_b64 vcc, exec, s[10:11]
	s_nop 1
	v_permlane16_swap_b32 v106, v108
	v_permlane16_swap_b32 v107, v109
	s_nop 1
	global_store_dwordx4 v[116:117], v[106:109], off offset:256
	s_cbranch_vccnz .LBB0_639
	s_or_b32 s78, s31, s76
	s_ashr_i32 s79, s78, 31
	s_lshl_b64 s[78:79], s[78:79], 19
	v_lshl_add_u64 v[106:107], v[114:115], 0, s[78:79]
	global_store_dwordx4 v[106:107], v[98:101], off offset:512
	global_store_dwordx4 v[106:107], v[102:105], off offset:576
.LBB0_639:
	s_nop 1
	v_or_b32_e32 v102, 32, v234
	v_mad_i64_i32 v[98:99], s[78:79], s80, v102, 0
	v_lshl_add_u64 v[100:101], v[98:99], 1, v[214:215]
	v_lshlrev_b32_e32 v98, 11, v102
	v_pk_mul_f32 v[102:103], v[92:93], v[176:177]
	v_pk_mul_f32 v[104:105], v[90:91], v[174:175]
	v_pk_fma_f32 v[102:103], v[96:97], v[172:173], v[102:103] neg_lo:[0,0,1] neg_hi:[0,0,1]
	v_pk_fma_f32 v[104:105], v[94:95], v[170:171], v[104:105] neg_lo:[0,0,1] neg_hi:[0,0,1]
	v_pk_mul_f32 v[96:97], v[96:97], v[176:177]
	v_pk_mul_f32 v[94:95], v[94:95], v[174:175]
	v_pk_fma_f32 v[96:97], v[92:93], v[172:173], v[96:97]
	v_pk_fma_f32 v[94:95], v[90:91], v[170:171], v[94:95]
	v_and_b32_e32 v98, 0x77800, v98
	v_mov_b32_e32 v99, v1
	v_pk_mul_f32 v[92:93], v[102:103], s[64:65] op_sel_hi:[1,0]
	v_pk_mul_f32 v[90:91], v[104:105], s[64:65] op_sel_hi:[1,0]
	v_pk_mul_f32 v[106:107], v[96:97], s[64:65] op_sel_hi:[1,0]
	v_pk_mul_f32 v[108:109], v[94:95], s[64:65] op_sel_hi:[1,0]
	v_lshl_add_u64 v[98:99], v[216:217], 0, v[98:99]
	v_cndmask_b32_e64 v91, v105, v91, s[8:9]
	v_cndmask_b32_e64 v90, v104, v90, s[8:9]
	v_cndmask_b32_e64 v93, v103, v93, s[8:9]
	v_cndmask_b32_e64 v92, v102, v92, s[8:9]
	v_cndmask_b32_e64 v95, v95, v109, s[8:9]
	v_cndmask_b32_e64 v94, v94, v108, s[8:9]
	v_cndmask_b32_e64 v97, v97, v107, s[8:9]
	v_cndmask_b32_e64 v96, v96, v106, s[8:9]
	v_cvt_pk_bf16_f32 v102, v90, v91
	v_cvt_pk_bf16_f32 v103, v92, v93
	v_cvt_pk_bf16_f32 v104, v94, v95
	v_cvt_pk_bf16_f32 v105, v96, v97
	s_and_b64 vcc, exec, s[10:11]
	s_nop 1
	v_permlane16_swap_b32 v102, v104
	v_permlane16_swap_b32 v103, v105
	s_nop 1
	global_store_dwordx4 v[100:101], v[102:105], off
	s_cbranch_vccnz .LBB0_641
	s_or_b32 s78, s31, s76
	s_ashr_i32 s79, s78, 31
	s_lshl_b64 s[78:79], s[78:79], 19
	v_lshl_add_u64 v[102:103], v[98:99], 0, s[78:79]
	global_store_dwordx4 v[102:103], v[90:93], off
	global_store_dwordx4 v[102:103], v[94:97], off offset:64
.LBB0_641:
	s_nop 0
	v_pk_mul_f32 v[90:91], v[84:85], v[176:177]
	v_pk_mul_f32 v[92:93], v[82:83], v[174:175]
	v_pk_fma_f32 v[90:91], v[88:89], v[172:173], v[90:91] neg_lo:[0,0,1] neg_hi:[0,0,1]
	v_pk_fma_f32 v[92:93], v[86:87], v[170:171], v[92:93] neg_lo:[0,0,1] neg_hi:[0,0,1]
	v_pk_mul_f32 v[88:89], v[88:89], v[176:177]
	v_pk_mul_f32 v[86:87], v[86:87], v[174:175]
	v_pk_fma_f32 v[88:89], v[84:85], v[172:173], v[88:89]
	v_pk_fma_f32 v[86:87], v[82:83], v[170:171], v[86:87]
	v_pk_mul_f32 v[82:83], v[92:93], s[64:65] op_sel_hi:[1,0]
	v_pk_mul_f32 v[84:85], v[90:91], s[64:65] op_sel_hi:[1,0]
	v_pk_mul_f32 v[94:95], v[86:87], s[64:65] op_sel_hi:[1,0]
	v_pk_mul_f32 v[96:97], v[88:89], s[64:65] op_sel_hi:[1,0]
	v_cndmask_b32_e64 v85, v91, v85, s[8:9]
	v_cndmask_b32_e64 v84, v90, v84, s[8:9]
	v_cndmask_b32_e64 v83, v93, v83, s[8:9]
	v_cndmask_b32_e64 v82, v92, v82, s[8:9]
	v_cndmask_b32_e64 v89, v89, v97, s[8:9]
	v_cndmask_b32_e64 v88, v88, v96, s[8:9]
	v_cndmask_b32_e64 v87, v87, v95, s[8:9]
	v_cndmask_b32_e64 v86, v86, v94, s[8:9]
	v_cvt_pk_bf16_f32 v90, v82, v83
	v_cvt_pk_bf16_f32 v91, v84, v85
	v_cvt_pk_bf16_f32 v92, v86, v87
	v_cvt_pk_bf16_f32 v93, v88, v89
	s_and_b64 vcc, exec, s[10:11]
	s_nop 1
	v_permlane16_swap_b32 v90, v92
	v_permlane16_swap_b32 v91, v93
	s_nop 1
	global_store_dwordx4 v[100:101], v[90:93], off offset:256
	s_cbranch_vccnz .LBB0_643
	s_or_b32 s78, s31, s76
	s_ashr_i32 s79, s78, 31
	s_lshl_b64 s[78:79], s[78:79], 19
	v_lshl_add_u64 v[90:91], v[98:99], 0, s[78:79]
	global_store_dwordx4 v[90:91], v[82:85], off offset:512
	global_store_dwordx4 v[90:91], v[86:89], off offset:576
.LBB0_643:
	s_nop 1
	v_or_b32_e32 v86, 48, v234
	v_mad_i64_i32 v[82:83], s[78:79], s80, v86, 0
	v_lshl_add_u64 v[84:85], v[82:83], 1, v[214:215]
	v_lshlrev_b32_e32 v82, 11, v86
	v_pk_mul_f32 v[86:87], v[76:77], v[168:169]
	v_pk_mul_f32 v[88:89], v[74:75], v[166:167]
	v_pk_fma_f32 v[86:87], v[80:81], v[164:165], v[86:87] neg_lo:[0,0,1] neg_hi:[0,0,1]
	v_pk_fma_f32 v[88:89], v[78:79], v[162:163], v[88:89] neg_lo:[0,0,1] neg_hi:[0,0,1]
	v_pk_mul_f32 v[80:81], v[80:81], v[168:169]
	v_pk_mul_f32 v[78:79], v[78:79], v[166:167]
	v_pk_fma_f32 v[80:81], v[76:77], v[164:165], v[80:81]
	v_pk_fma_f32 v[78:79], v[74:75], v[162:163], v[78:79]
	v_and_b32_e32 v82, 0x7f800, v82
	v_mov_b32_e32 v83, v1
	v_pk_mul_f32 v[76:77], v[86:87], s[64:65] op_sel_hi:[1,0]
	v_pk_mul_f32 v[74:75], v[88:89], s[64:65] op_sel_hi:[1,0]
	v_pk_mul_f32 v[90:91], v[80:81], s[64:65] op_sel_hi:[1,0]
	v_pk_mul_f32 v[92:93], v[78:79], s[64:65] op_sel_hi:[1,0]
	v_lshl_add_u64 v[82:83], v[216:217], 0, v[82:83]
	v_cndmask_b32_e64 v75, v89, v75, s[8:9]
	v_cndmask_b32_e64 v74, v88, v74, s[8:9]
	v_cndmask_b32_e64 v77, v87, v77, s[8:9]
	v_cndmask_b32_e64 v76, v86, v76, s[8:9]
	v_cndmask_b32_e64 v79, v79, v93, s[8:9]
	v_cndmask_b32_e64 v78, v78, v92, s[8:9]
	v_cndmask_b32_e64 v81, v81, v91, s[8:9]
	v_cndmask_b32_e64 v80, v80, v90, s[8:9]
	v_cvt_pk_bf16_f32 v86, v74, v75
	v_cvt_pk_bf16_f32 v87, v76, v77
	v_cvt_pk_bf16_f32 v88, v78, v79
	v_cvt_pk_bf16_f32 v89, v80, v81
	s_and_b64 vcc, exec, s[10:11]
	s_nop 1
	v_permlane16_swap_b32 v86, v88
	v_permlane16_swap_b32 v87, v89
	s_nop 1
	global_store_dwordx4 v[84:85], v[86:89], off
	s_cbranch_vccnz .LBB0_645
	s_or_b32 s78, s31, s76
	s_ashr_i32 s79, s78, 31
	s_lshl_b64 s[78:79], s[78:79], 19
	v_lshl_add_u64 v[86:87], v[82:83], 0, s[78:79]
	global_store_dwordx4 v[86:87], v[74:77], off
	global_store_dwordx4 v[86:87], v[78:81], off offset:64
.LBB0_645:
	s_nop 0
	v_pk_mul_f32 v[74:75], v[68:69], v[168:169]
	v_pk_mul_f32 v[76:77], v[66:67], v[166:167]
	v_pk_fma_f32 v[74:75], v[72:73], v[164:165], v[74:75] neg_lo:[0,0,1] neg_hi:[0,0,1]
	v_pk_fma_f32 v[76:77], v[70:71], v[162:163], v[76:77] neg_lo:[0,0,1] neg_hi:[0,0,1]
	v_pk_mul_f32 v[72:73], v[72:73], v[168:169]
	v_pk_mul_f32 v[70:71], v[70:71], v[166:167]
	v_pk_fma_f32 v[72:73], v[68:69], v[164:165], v[72:73]
	v_pk_fma_f32 v[70:71], v[66:67], v[162:163], v[70:71]
	v_pk_mul_f32 v[66:67], v[76:77], s[64:65] op_sel_hi:[1,0]
	v_pk_mul_f32 v[68:69], v[74:75], s[64:65] op_sel_hi:[1,0]
	v_pk_mul_f32 v[78:79], v[70:71], s[64:65] op_sel_hi:[1,0]
	v_pk_mul_f32 v[80:81], v[72:73], s[64:65] op_sel_hi:[1,0]
	v_cndmask_b32_e64 v69, v75, v69, s[8:9]
	v_cndmask_b32_e64 v68, v74, v68, s[8:9]
	v_cndmask_b32_e64 v67, v77, v67, s[8:9]
	v_cndmask_b32_e64 v66, v76, v66, s[8:9]
	v_cndmask_b32_e64 v73, v73, v81, s[8:9]
	v_cndmask_b32_e64 v72, v72, v80, s[8:9]
	v_cndmask_b32_e64 v71, v71, v79, s[8:9]
	v_cndmask_b32_e64 v70, v70, v78, s[8:9]
	v_cvt_pk_bf16_f32 v74, v66, v67
	v_cvt_pk_bf16_f32 v75, v68, v69
	v_cvt_pk_bf16_f32 v76, v70, v71
	v_cvt_pk_bf16_f32 v77, v72, v73
	s_and_b64 vcc, exec, s[10:11]
	s_nop 1
	v_permlane16_swap_b32 v74, v76
	v_permlane16_swap_b32 v75, v77
	s_nop 1
	global_store_dwordx4 v[84:85], v[74:77], off offset:256
	s_cbranch_vccnz .LBB0_647
	s_or_b32 s78, s31, s76
	s_ashr_i32 s79, s78, 31
	s_lshl_b64 s[78:79], s[78:79], 19
	v_lshl_add_u64 v[74:75], v[82:83], 0, s[78:79]
	global_store_dwordx4 v[74:75], v[66:69], off offset:512
	global_store_dwordx4 v[74:75], v[70:73], off offset:576
.LBB0_647:
	s_nop 0
	v_add_u32_e32 v68, 0x80, v234
	v_ashrrev_i32_e32 v66, 7, v68
	v_and_b32_e32 v78, -2, v66
	v_mad_i64_i32 v[66:67], s[78:79], s80, v68, 0
	v_lshl_add_u64 v[70:71], v[66:67], 1, v[214:215]
	v_lshlrev_b32_e32 v66, 11, v68
	v_and_b32_e32 v66, 0x67800, v66
	v_mov_b32_e32 v67, v1
	v_lshl_add_u64 v[68:69], v[216:217], 0, v[66:67]
	v_pk_mul_f32 v[66:67], v[60:61], v[160:161]
	v_pk_mul_f32 v[72:73], v[58:59], v[158:159]
	v_pk_fma_f32 v[66:67], v[64:65], v[156:157], v[66:67] neg_lo:[0,0,1] neg_hi:[0,0,1]
	v_pk_fma_f32 v[72:73], v[62:63], v[154:155], v[72:73] neg_lo:[0,0,1] neg_hi:[0,0,1]
	v_pk_mul_f32 v[64:65], v[64:65], v[160:161]
	v_pk_mul_f32 v[62:63], v[62:63], v[158:159]
	v_pk_fma_f32 v[64:65], v[60:61], v[156:157], v[64:65]
	v_pk_fma_f32 v[62:63], v[58:59], v[154:155], v[62:63]
	v_pk_mul_f32 v[60:61], v[66:67], s[64:65] op_sel_hi:[1,0]
	v_pk_mul_f32 v[58:59], v[72:73], s[64:65] op_sel_hi:[1,0]
	v_pk_mul_f32 v[74:75], v[64:65], s[64:65] op_sel_hi:[1,0]
	v_pk_mul_f32 v[76:77], v[62:63], s[64:65] op_sel_hi:[1,0]
	v_cndmask_b32_e64 v60, v66, v60, s[8:9]
	v_or_b32_e32 v66, s76, v78
	v_cndmask_b32_e64 v59, v73, v59, s[8:9]
	v_cndmask_b32_e64 v58, v72, v58, s[8:9]
	v_cndmask_b32_e64 v61, v67, v61, s[8:9]
	v_cndmask_b32_e64 v63, v63, v77, s[8:9]
	v_cndmask_b32_e64 v62, v62, v76, s[8:9]
	v_cndmask_b32_e64 v65, v65, v75, s[8:9]
	v_cndmask_b32_e64 v64, v64, v74, s[8:9]
	v_cvt_pk_bf16_f32 v72, v58, v59
	v_cvt_pk_bf16_f32 v73, v60, v61
	v_cvt_pk_bf16_f32 v74, v62, v63
	v_cvt_pk_bf16_f32 v75, v64, v65
	s_and_b64 vcc, exec, s[10:11]
	v_ashrrev_i32_e32 v67, 31, v66
	s_nop 1
	v_permlane16_swap_b32 v72, v74
	v_permlane16_swap_b32 v73, v75
	s_nop 1
	global_store_dwordx4 v[70:71], v[72:75], off
	s_cbranch_vccnz .LBB0_649
	s_nop 0
	v_lshlrev_b64 v[72:73], 19, v[66:67]
	v_lshl_add_u64 v[72:73], v[68:69], 0, v[72:73]
	global_store_dwordx4 v[72:73], v[58:61], off
	global_store_dwordx4 v[72:73], v[62:65], off offset:64
.LBB0_649:
	s_nop 0
	v_pk_mul_f32 v[58:59], v[52:53], v[160:161]
	v_pk_mul_f32 v[60:61], v[50:51], v[158:159]
	v_pk_fma_f32 v[58:59], v[56:57], v[156:157], v[58:59] neg_lo:[0,0,1] neg_hi:[0,0,1]
	v_pk_fma_f32 v[60:61], v[54:55], v[154:155], v[60:61] neg_lo:[0,0,1] neg_hi:[0,0,1]
	v_pk_mul_f32 v[56:57], v[56:57], v[160:161]
	v_pk_mul_f32 v[54:55], v[54:55], v[158:159]
	v_pk_fma_f32 v[56:57], v[52:53], v[156:157], v[56:57]
	v_pk_fma_f32 v[54:55], v[50:51], v[154:155], v[54:55]
	v_pk_mul_f32 v[50:51], v[60:61], s[64:65] op_sel_hi:[1,0]
	v_pk_mul_f32 v[52:53], v[58:59], s[64:65] op_sel_hi:[1,0]
	v_pk_mul_f32 v[62:63], v[54:55], s[64:65] op_sel_hi:[1,0]
	v_pk_mul_f32 v[64:65], v[56:57], s[64:65] op_sel_hi:[1,0]
	v_cndmask_b32_e64 v53, v59, v53, s[8:9]
	v_cndmask_b32_e64 v52, v58, v52, s[8:9]
	v_cndmask_b32_e64 v51, v61, v51, s[8:9]
	v_cndmask_b32_e64 v50, v60, v50, s[8:9]
	v_cndmask_b32_e64 v57, v57, v65, s[8:9]
	v_cndmask_b32_e64 v56, v56, v64, s[8:9]
	v_cndmask_b32_e64 v55, v55, v63, s[8:9]
	v_cndmask_b32_e64 v54, v54, v62, s[8:9]
	v_cvt_pk_bf16_f32 v58, v50, v51
	v_cvt_pk_bf16_f32 v59, v52, v53
	v_cvt_pk_bf16_f32 v60, v54, v55
	v_cvt_pk_bf16_f32 v61, v56, v57
	s_and_b64 vcc, exec, s[10:11]
	s_nop 1
	v_permlane16_swap_b32 v58, v60
	v_permlane16_swap_b32 v59, v61
	s_nop 1
	global_store_dwordx4 v[70:71], v[58:61], off offset:256
	s_cbranch_vccnz .LBB0_651
	s_nop 0
	v_lshlrev_b64 v[58:59], 19, v[66:67]
	v_lshl_add_u64 v[58:59], v[68:69], 0, v[58:59]
	global_store_dwordx4 v[58:59], v[50:53], off offset:512
	global_store_dwordx4 v[58:59], v[54:57], off offset:576
.LBB0_651:
	s_nop 1
	v_add_u32_e32 v54, 0x90, v234
	v_mad_i64_i32 v[50:51], s[78:79], s80, v54, 0
	v_lshl_add_u64 v[52:53], v[50:51], 1, v[214:215]
	v_lshlrev_b32_e32 v50, 11, v54
	v_pk_mul_f32 v[54:55], v[44:45], v[152:153]
	v_pk_mul_f32 v[56:57], v[42:43], v[150:151]
	v_pk_fma_f32 v[54:55], v[48:49], v[148:149], v[54:55] neg_lo:[0,0,1] neg_hi:[0,0,1]
	v_pk_fma_f32 v[56:57], v[46:47], v[146:147], v[56:57] neg_lo:[0,0,1] neg_hi:[0,0,1]
	v_pk_mul_f32 v[48:49], v[48:49], v[152:153]
	v_pk_mul_f32 v[46:47], v[46:47], v[150:151]
	v_pk_fma_f32 v[48:49], v[44:45], v[148:149], v[48:49]
	v_pk_fma_f32 v[46:47], v[42:43], v[146:147], v[46:47]
	v_and_b32_e32 v50, 0x6f800, v50
	v_mov_b32_e32 v51, v1
	v_pk_mul_f32 v[44:45], v[54:55], s[64:65] op_sel_hi:[1,0]
	v_pk_mul_f32 v[42:43], v[56:57], s[64:65] op_sel_hi:[1,0]
	v_pk_mul_f32 v[58:59], v[48:49], s[64:65] op_sel_hi:[1,0]
	v_pk_mul_f32 v[60:61], v[46:47], s[64:65] op_sel_hi:[1,0]
	v_lshl_add_u64 v[50:51], v[216:217], 0, v[50:51]
	v_cndmask_b32_e64 v43, v57, v43, s[8:9]
	v_cndmask_b32_e64 v42, v56, v42, s[8:9]
	v_cndmask_b32_e64 v45, v55, v45, s[8:9]
	v_cndmask_b32_e64 v44, v54, v44, s[8:9]
	v_cndmask_b32_e64 v47, v47, v61, s[8:9]
	v_cndmask_b32_e64 v46, v46, v60, s[8:9]
	v_cndmask_b32_e64 v49, v49, v59, s[8:9]
	v_cndmask_b32_e64 v48, v48, v58, s[8:9]
	v_cvt_pk_bf16_f32 v54, v42, v43
	v_cvt_pk_bf16_f32 v55, v44, v45
	v_cvt_pk_bf16_f32 v56, v46, v47
	v_cvt_pk_bf16_f32 v57, v48, v49
	s_and_b64 vcc, exec, s[10:11]
	s_nop 1
	v_permlane16_swap_b32 v54, v56
	v_permlane16_swap_b32 v55, v57
	s_nop 1
	global_store_dwordx4 v[52:53], v[54:57], off
	s_cbranch_vccnz .LBB0_653
	s_nop 0
	v_lshlrev_b64 v[54:55], 19, v[66:67]
	v_lshl_add_u64 v[54:55], v[50:51], 0, v[54:55]
	global_store_dwordx4 v[54:55], v[42:45], off
	global_store_dwordx4 v[54:55], v[46:49], off offset:64
.LBB0_653:
	s_nop 0
	v_pk_mul_f32 v[42:43], v[36:37], v[152:153]
	v_pk_mul_f32 v[44:45], v[34:35], v[150:151]
	v_pk_fma_f32 v[42:43], v[40:41], v[148:149], v[42:43] neg_lo:[0,0,1] neg_hi:[0,0,1]
	v_pk_fma_f32 v[44:45], v[38:39], v[146:147], v[44:45] neg_lo:[0,0,1] neg_hi:[0,0,1]
	v_pk_mul_f32 v[40:41], v[40:41], v[152:153]
	v_pk_mul_f32 v[38:39], v[38:39], v[150:151]
	v_pk_fma_f32 v[40:41], v[36:37], v[148:149], v[40:41]
	v_pk_fma_f32 v[38:39], v[34:35], v[146:147], v[38:39]
	v_pk_mul_f32 v[34:35], v[44:45], s[64:65] op_sel_hi:[1,0]
	v_pk_mul_f32 v[36:37], v[42:43], s[64:65] op_sel_hi:[1,0]
	v_pk_mul_f32 v[46:47], v[38:39], s[64:65] op_sel_hi:[1,0]
	v_pk_mul_f32 v[48:49], v[40:41], s[64:65] op_sel_hi:[1,0]
	v_cndmask_b32_e64 v37, v43, v37, s[8:9]
	v_cndmask_b32_e64 v36, v42, v36, s[8:9]
	v_cndmask_b32_e64 v35, v45, v35, s[8:9]
	v_cndmask_b32_e64 v34, v44, v34, s[8:9]
	v_cndmask_b32_e64 v41, v41, v49, s[8:9]
	v_cndmask_b32_e64 v40, v40, v48, s[8:9]
	v_cndmask_b32_e64 v39, v39, v47, s[8:9]
	v_cndmask_b32_e64 v38, v38, v46, s[8:9]
	v_cvt_pk_bf16_f32 v42, v34, v35
	v_cvt_pk_bf16_f32 v43, v36, v37
	v_cvt_pk_bf16_f32 v44, v38, v39
	v_cvt_pk_bf16_f32 v45, v40, v41
	s_and_b64 vcc, exec, s[10:11]
	s_nop 1
	v_permlane16_swap_b32 v42, v44
	v_permlane16_swap_b32 v43, v45
	s_nop 1
	global_store_dwordx4 v[52:53], v[42:45], off offset:256
	s_cbranch_vccnz .LBB0_655
	s_nop 0
	v_lshlrev_b64 v[42:43], 19, v[66:67]
	v_lshl_add_u64 v[42:43], v[50:51], 0, v[42:43]
	global_store_dwordx4 v[42:43], v[34:37], off offset:512
	global_store_dwordx4 v[42:43], v[38:41], off offset:576
.LBB0_655:
	s_nop 1
	v_add_u32_e32 v38, 0xa0, v234
	v_mad_i64_i32 v[34:35], s[78:79], s80, v38, 0
	v_lshl_add_u64 v[36:37], v[34:35], 1, v[214:215]
	v_lshlrev_b32_e32 v34, 11, v38
	v_pk_mul_f32 v[38:39], v[28:29], v[144:145]
	v_pk_mul_f32 v[40:41], v[26:27], v[142:143]
	v_pk_fma_f32 v[38:39], v[32:33], v[140:141], v[38:39] neg_lo:[0,0,1] neg_hi:[0,0,1]
	v_pk_fma_f32 v[40:41], v[30:31], v[138:139], v[40:41] neg_lo:[0,0,1] neg_hi:[0,0,1]
	v_pk_mul_f32 v[32:33], v[32:33], v[144:145]
	v_pk_mul_f32 v[30:31], v[30:31], v[142:143]
	v_pk_fma_f32 v[32:33], v[28:29], v[140:141], v[32:33]
	v_pk_fma_f32 v[30:31], v[26:27], v[138:139], v[30:31]
	v_and_b32_e32 v34, 0x77800, v34
	v_mov_b32_e32 v35, v1
	v_pk_mul_f32 v[28:29], v[38:39], s[64:65] op_sel_hi:[1,0]
	v_pk_mul_f32 v[26:27], v[40:41], s[64:65] op_sel_hi:[1,0]
	v_pk_mul_f32 v[42:43], v[32:33], s[64:65] op_sel_hi:[1,0]
	v_pk_mul_f32 v[44:45], v[30:31], s[64:65] op_sel_hi:[1,0]
	v_lshl_add_u64 v[34:35], v[216:217], 0, v[34:35]
	v_cndmask_b32_e64 v27, v41, v27, s[8:9]
	v_cndmask_b32_e64 v26, v40, v26, s[8:9]
	v_cndmask_b32_e64 v29, v39, v29, s[8:9]
	v_cndmask_b32_e64 v28, v38, v28, s[8:9]
	v_cndmask_b32_e64 v31, v31, v45, s[8:9]
	v_cndmask_b32_e64 v30, v30, v44, s[8:9]
	v_cndmask_b32_e64 v33, v33, v43, s[8:9]
	v_cndmask_b32_e64 v32, v32, v42, s[8:9]
	v_cvt_pk_bf16_f32 v38, v26, v27
	v_cvt_pk_bf16_f32 v39, v28, v29
	v_cvt_pk_bf16_f32 v40, v30, v31
	v_cvt_pk_bf16_f32 v41, v32, v33
	s_and_b64 vcc, exec, s[10:11]
	s_nop 1
	v_permlane16_swap_b32 v38, v40
	v_permlane16_swap_b32 v39, v41
	s_nop 1
	global_store_dwordx4 v[36:37], v[38:41], off
	s_cbranch_vccnz .LBB0_657
	s_nop 0
	v_lshlrev_b64 v[38:39], 19, v[66:67]
	v_lshl_add_u64 v[38:39], v[34:35], 0, v[38:39]
	global_store_dwordx4 v[38:39], v[26:29], off
	global_store_dwordx4 v[38:39], v[30:33], off offset:64
.LBB0_657:
	s_nop 0
	v_pk_mul_f32 v[26:27], v[20:21], v[144:145]
	v_pk_mul_f32 v[28:29], v[18:19], v[142:143]
	v_pk_fma_f32 v[26:27], v[24:25], v[140:141], v[26:27] neg_lo:[0,0,1] neg_hi:[0,0,1]
	v_pk_fma_f32 v[28:29], v[22:23], v[138:139], v[28:29] neg_lo:[0,0,1] neg_hi:[0,0,1]
	v_pk_mul_f32 v[24:25], v[24:25], v[144:145]
	v_pk_mul_f32 v[22:23], v[22:23], v[142:143]
	v_pk_fma_f32 v[24:25], v[20:21], v[140:141], v[24:25]
	v_pk_fma_f32 v[22:23], v[18:19], v[138:139], v[22:23]
	v_pk_mul_f32 v[18:19], v[28:29], s[64:65] op_sel_hi:[1,0]
	v_pk_mul_f32 v[20:21], v[26:27], s[64:65] op_sel_hi:[1,0]
	v_pk_mul_f32 v[30:31], v[22:23], s[64:65] op_sel_hi:[1,0]
	v_pk_mul_f32 v[32:33], v[24:25], s[64:65] op_sel_hi:[1,0]
	v_cndmask_b32_e64 v21, v27, v21, s[8:9]
	v_cndmask_b32_e64 v20, v26, v20, s[8:9]
	v_cndmask_b32_e64 v19, v29, v19, s[8:9]
	v_cndmask_b32_e64 v18, v28, v18, s[8:9]
	v_cndmask_b32_e64 v25, v25, v33, s[8:9]
	v_cndmask_b32_e64 v24, v24, v32, s[8:9]
	v_cndmask_b32_e64 v23, v23, v31, s[8:9]
	v_cndmask_b32_e64 v22, v22, v30, s[8:9]
	v_cvt_pk_bf16_f32 v26, v18, v19
	v_cvt_pk_bf16_f32 v27, v20, v21
	v_cvt_pk_bf16_f32 v28, v22, v23
	v_cvt_pk_bf16_f32 v29, v24, v25
	s_and_b64 vcc, exec, s[10:11]
	s_nop 1
	v_permlane16_swap_b32 v26, v28
	v_permlane16_swap_b32 v27, v29
	s_nop 1
	global_store_dwordx4 v[36:37], v[26:29], off offset:256
	s_cbranch_vccnz .LBB0_659
	s_nop 0
	v_lshlrev_b64 v[26:27], 19, v[66:67]
	v_lshl_add_u64 v[26:27], v[34:35], 0, v[26:27]
	global_store_dwordx4 v[26:27], v[18:21], off offset:512
	global_store_dwordx4 v[26:27], v[22:25], off offset:576
.LBB0_659:
	s_nop 1
	v_add_u32_e32 v22, 0xb0, v234
	v_mad_i64_i32 v[18:19], s[78:79], s80, v22, 0
	v_lshl_add_u64 v[20:21], v[18:19], 1, v[214:215]
	v_lshlrev_b32_e32 v18, 11, v22
	v_pk_mul_f32 v[22:23], v[12:13], v[136:137]
	v_pk_mul_f32 v[24:25], v[10:11], v[134:135]
	v_pk_fma_f32 v[22:23], v[16:17], v[128:129], v[22:23] neg_lo:[0,0,1] neg_hi:[0,0,1]
	v_pk_fma_f32 v[24:25], v[14:15], v[126:127], v[24:25] neg_lo:[0,0,1] neg_hi:[0,0,1]
	v_pk_mul_f32 v[16:17], v[16:17], v[136:137]
	v_pk_mul_f32 v[14:15], v[14:15], v[134:135]
	v_pk_fma_f32 v[16:17], v[12:13], v[128:129], v[16:17]
	v_pk_fma_f32 v[14:15], v[10:11], v[126:127], v[14:15]
	v_and_b32_e32 v18, 0x7f800, v18
	v_mov_b32_e32 v19, v1
	v_pk_mul_f32 v[12:13], v[22:23], s[64:65] op_sel_hi:[1,0]
	v_pk_mul_f32 v[10:11], v[24:25], s[64:65] op_sel_hi:[1,0]
	v_pk_mul_f32 v[26:27], v[16:17], s[64:65] op_sel_hi:[1,0]
	v_pk_mul_f32 v[28:29], v[14:15], s[64:65] op_sel_hi:[1,0]
	v_lshl_add_u64 v[18:19], v[216:217], 0, v[18:19]
	v_cndmask_b32_e64 v11, v25, v11, s[8:9]
	v_cndmask_b32_e64 v10, v24, v10, s[8:9]
	v_cndmask_b32_e64 v13, v23, v13, s[8:9]
	v_cndmask_b32_e64 v12, v22, v12, s[8:9]
	v_cndmask_b32_e64 v15, v15, v29, s[8:9]
	v_cndmask_b32_e64 v14, v14, v28, s[8:9]
	v_cndmask_b32_e64 v17, v17, v27, s[8:9]
	v_cndmask_b32_e64 v16, v16, v26, s[8:9]
	v_cvt_pk_bf16_f32 v22, v10, v11
	v_cvt_pk_bf16_f32 v23, v12, v13
	v_cvt_pk_bf16_f32 v24, v14, v15
	v_cvt_pk_bf16_f32 v25, v16, v17
	s_and_b64 vcc, exec, s[10:11]
	s_nop 1
	v_permlane16_swap_b32 v22, v24
	v_permlane16_swap_b32 v23, v25
	s_nop 1
	global_store_dwordx4 v[20:21], v[22:25], off
	s_cbranch_vccnz .LBB0_661
	s_nop 0
	v_lshlrev_b64 v[22:23], 19, v[66:67]
	v_lshl_add_u64 v[22:23], v[18:19], 0, v[22:23]
	global_store_dwordx4 v[22:23], v[10:13], off
	global_store_dwordx4 v[22:23], v[14:17], off offset:64
.LBB0_661:
	s_nop 0
	v_pk_mul_f32 v[10:11], v[4:5], v[136:137]
	v_pk_mul_f32 v[12:13], v[2:3], v[134:135]
	v_pk_fma_f32 v[10:11], v[8:9], v[128:129], v[10:11] neg_lo:[0,0,1] neg_hi:[0,0,1]
	v_pk_fma_f32 v[12:13], v[6:7], v[126:127], v[12:13] neg_lo:[0,0,1] neg_hi:[0,0,1]
	v_pk_mul_f32 v[8:9], v[8:9], v[136:137]
	v_pk_mul_f32 v[6:7], v[6:7], v[134:135]
	v_pk_fma_f32 v[8:9], v[4:5], v[128:129], v[8:9]
	v_pk_fma_f32 v[6:7], v[2:3], v[126:127], v[6:7]
	v_pk_mul_f32 v[2:3], v[12:13], s[64:65] op_sel_hi:[1,0]
	v_pk_mul_f32 v[4:5], v[10:11], s[64:65] op_sel_hi:[1,0]
	v_pk_mul_f32 v[14:15], v[6:7], s[64:65] op_sel_hi:[1,0]
	v_pk_mul_f32 v[16:17], v[8:9], s[64:65] op_sel_hi:[1,0]
	v_cndmask_b32_e64 v5, v11, v5, s[8:9]
	v_cndmask_b32_e64 v4, v10, v4, s[8:9]
	v_cndmask_b32_e64 v3, v13, v3, s[8:9]
	v_cndmask_b32_e64 v2, v12, v2, s[8:9]
	v_cndmask_b32_e64 v9, v9, v17, s[8:9]
	v_cndmask_b32_e64 v8, v8, v16, s[8:9]
	v_cndmask_b32_e64 v7, v7, v15, s[8:9]
	v_cndmask_b32_e64 v6, v6, v14, s[8:9]
	v_cvt_pk_bf16_f32 v10, v2, v3
	v_cvt_pk_bf16_f32 v11, v4, v5
	v_cvt_pk_bf16_f32 v12, v6, v7
	v_cvt_pk_bf16_f32 v13, v8, v9
	s_and_b64 vcc, exec, s[10:11]
	s_nop 1
	v_permlane16_swap_b32 v10, v12
	v_permlane16_swap_b32 v11, v13
	s_nop 1
	global_store_dwordx4 v[20:21], v[10:13], off offset:256
	s_cbranch_vccnz .LBB0_663
	s_nop 0
	v_lshlrev_b64 v[10:11], 19, v[66:67]
	v_lshl_add_u64 v[10:11], v[18:19], 0, v[10:11]
	global_store_dwordx4 v[10:11], v[2:5], off offset:512
	global_store_dwordx4 v[10:11], v[6:9], off offset:576

.LBB0_667:
	s_abs_i32 s4, s68
	v_cvt_f32_u32_e32 v0, s4
	s_sub_i32 s5, 0, s4
	v_rcp_iflag_f32_e32 v0, v0
	s_nop 0
	v_mul_f32_e32 v0, 0x4f7ffffe, v0
	v_cvt_u32_f32_e32 v0, v0
	s_nop 0
	v_readfirstlane_b32 s6, v0
	s_mul_i32 s5, s5, s6
	s_mul_hi_u32 s5, s6, s5
	s_add_i32 s6, s6, s5
	s_mul_hi_u32 s5, s6, 0x180
	s_mul_i32 s5, s5, s4
	s_sub_i32 s5, 0x180, s5
	s_sub_i32 s6, s5, s4
	s_cmp_ge_u32 s5, s4
	s_cselect_b32 s5, s6, s5
	s_sub_i32 s6, s5, s4
	s_cmp_ge_u32 s5, s4
	s_cselect_b32 s4, s6, s5
	s_cmp_lt_i32 s69, s4
	s_cbranch_scc1 .LBB0_728
	s_ashr_i32 s5, s70, 6
	s_mul_i32 s16, s76, 0xab40
	s_sub_i32 s7, s69, s4
	s_add_i32 s6, s5, s16
	s_lshl_b32 s7, s7, 3
	s_add_i32 s6, s6, s7
	s_addk_i32 s16, 0x4000
	s_add_i32 s17, s6, 0x1400
	s_cmp_ge_i32 s17, s16
	s_cbranch_scc1 .LBB0_728
	s_sub_i32 s4, s68, s4
	s_lshl_b32 s18, s4, 3
	s_lshl_b32 s4, s5, 14
	s_add_i32 s4, s4, 0
	s_add_u32 s19, s14, 0x10612000
	s_addc_u32 s20, s15, 0
	s_add_u32 s21, s14, 0x5612000
	s_addc_u32 s22, s15, 0
	s_add_u32 s23, s14, 0x4612000
	s_addc_u32 s24, s15, 0
	s_add_u32 s25, s14, 0x3e12000
	s_addc_u32 s26, s15, 0
	s_add_u32 s27, s14, 0x3812000
	s_addc_u32 s28, s15, 0
	s_add_u32 s29, s14, 0x2e12000
	v_bfe_u32 v10, v226, 3, 3
	s_addc_u32 s30, s15, 0
	v_lshlrev_b32_e32 v0, 2, v226
	v_and_b32_e32 v3, 7, v226
	v_lshlrev_b32_e32 v6, 2, v10
	s_add_u32 s31, s14, 0x1e12000
	v_and_b32_e32 v0, 28, v0
	v_lshl_add_u32 v4, v3, 4, s4
	v_mul_u32_u24_e32 v5, 0x84, v10
	v_lshlrev_b32_e32 v2, 3, v3
	v_mul_u32_u24_e32 v3, 0x420, v3
	v_and_b32_e32 v14, 16, v6
	s_addc_u32 s33, s15, 0
	v_or_b32_e32 v11, 8, v10
	v_or_b32_e32 v12, 16, v10
	v_or_b32_e32 v13, 24, v10
	v_add3_u32 v15, s4, v3, v6
	v_or_b32_e32 v16, 4, v14
	v_or_b32_e32 v17, 8, v14
	v_or_b32_e32 v18, 12, v6
	v_lshlrev_b32_e32 v0, 2, v0
	v_add_u32_e32 v19, v4, v5
	v_lshlrev_b32_e32 v6, 1, v2
	s_mov_b32 s99, 0
	s_branch .LBB0_672

.LBB0_671:
	v_ashrrev_i32_e32 v107, 31, v121
	v_mul_lo_u32 v122, s5, v121
	v_mul_lo_u32 v107, s4, v107
	v_mad_u64_u32 v[120:121], s[4:5], s4, v121, 0
	v_add3_u32 v121, v121, v107, v122
	v_lshl_add_u64 v[108:109], v[120:121], 1, v[108:109]
	global_store_dwordx4 v[108:109], v[102:105], off
	s_waitcnt lgkmcnt(0)
	s_cmp_eq_u32 s99, 2
	s_cbranch_scc1 .LBB0_728
	s_branch .Lcv_mid_G1

.LBB0_704:
	s_lshr_b32 s8, s39, 5
	v_cvt_f32_u32_e32 v2, s8
	s_sub_i32 s15, 0, s8
	s_abs_i32 s14, s37
	s_ashr_i32 s9, s37, 31
	v_rcp_iflag_f32_e32 v2, v2
	s_nop 0
	v_mul_f32_e32 v2, 0x4f7ffffe, v2
	v_cvt_u32_f32_e32 v2, v2
	s_nop 0
	v_readfirstlane_b32 s35, v2
	s_mul_i32 s15, s15, s35
	s_mul_hi_u32 s15, s35, s15
	s_add_i32 s35, s35, s15
	s_mul_hi_u32 s15, s14, s35
	s_mul_i32 s35, s15, s8
	s_sub_i32 s14, s14, s35
	s_add_i32 s35, s15, 1
	s_sub_i32 s36, s14, s8
	s_cmp_ge_u32 s14, s8
	s_cselect_b32 s15, s35, s15
	s_cselect_b32 s14, s36, s14
	s_add_i32 s35, s15, 1
	s_cmp_ge_u32 s14, s8
	s_cselect_b32 s14, s35, s15
	s_xor_b32 s14, s14, s9
	s_sub_i32 s9, s14, s9
	s_lshl_b32 s14, s9, 6
	s_mul_i32 s8, s9, s8
	v_or_b32_e32 v2, s14, v10
	s_ashr_i32 s15, s14, 31
	s_sub_i32 s35, s37, s8
	s_mul_i32 s9, s15, s39
	v_mad_u64_u32 v[2:3], s[36:37], v2, s39, 0
	s_lshl_b32 s8, s35, 5
	v_add_u32_e32 v3, s9, v3
	s_waitcnt lgkmcnt(0)
	v_lshl_add_u64 v[2:3], v[2:3], 2, s[10:11]
	s_ashr_i32 s9, s8, 31
	v_lshl_add_u64 v[2:3], s[8:9], 2, v[2:3]
	v_lshl_add_u64 v[8:9], v[2:3], 0, v[0:1]
	s_lshl_b32 s10, s39, 3
	s_mov_b32 s11, s50
	global_load_dwordx4 v[2:5], v[8:9], off nt
	v_lshl_add_u64 v[20:21], s[10:11], 2, v[8:9]
	global_load_dwordx4 v[20:23], v[20:21], off nt
	s_lshl_b32 s10, s39, 4
	v_lshl_add_u64 v[24:25], s[10:11], 2, v[8:9]
	global_load_dwordx4 v[24:27], v[24:25], off nt
	s_mul_i32 s10, s39, 24
	v_lshl_add_u64 v[28:29], s[10:11], 2, v[8:9]
	global_load_dwordx4 v[28:31], v[28:29], off nt
	s_lshl_b32 s10, s39, 5
	v_lshl_add_u64 v[32:33], s[10:11], 2, v[8:9]
	global_load_dwordx4 v[32:35], v[32:33], off nt
	s_mul_i32 s10, s39, 40
	v_lshl_add_u64 v[36:37], s[10:11], 2, v[8:9]
	global_load_dwordx4 v[36:39], v[36:37], off nt
	s_mul_i32 s10, s39, 48
	v_lshl_add_u64 v[40:41], s[10:11], 2, v[8:9]
	global_load_dwordx4 v[40:43], v[40:41], off nt
	s_mul_i32 s10, s39, 56
	v_lshl_add_u64 v[8:9], s[10:11], 2, v[8:9]
	global_load_dwordx4 v[44:47], v[8:9], off nt
	v_writelane_b32 v255, s4, 40
	v_writelane_b32 v255, s5, 41
	v_writelane_b32 v255, s6, 42
	v_writelane_b32 v255, s7, 43
	v_writelane_b32 v255, s8, 44
	v_writelane_b32 v255, s9, 45
	v_writelane_b32 v255, s10, 46
	v_writelane_b32 v255, s11, 47
	v_writelane_b32 v255, s14, 48
	v_writelane_b32 v255, s15, 49
	v_writelane_b32 v255, s34, 50
	v_writelane_b32 v255, s35, 51
	v_writelane_b32 v255, s44, 52
	s_cmp_eq_u32 s99, 1
	s_cbranch_scc1 .Lcv_tail_G1
.Lcv_mid_G1:
	s_waitcnt vmcnt(0)
	ds_write2_b32 v19, v2, v3 offset1:1
	ds_write2_b32 v19, v4, v5 offset0:2 offset1:3
	v_add_u32_e32 v2, 0x420, v19
	ds_write2_b32 v2, v20, v21 offset1:1
	v_add_u32_e32 v2, 0x428, v19
	ds_write2_b32 v2, v22, v23 offset1:1
	v_add_u32_e32 v2, 0x840, v19
	ds_write2_b32 v2, v24, v25 offset1:1
	v_add_u32_e32 v2, 0x848, v19
	ds_write2_b32 v2, v26, v27 offset1:1
	v_add_u32_e32 v2, 0xc60, v19
	ds_write2_b32 v2, v28, v29 offset1:1
	v_add_u32_e32 v2, 0xc68, v19
	ds_write2_b32 v2, v30, v31 offset1:1
	v_add_u32_e32 v2, 0x1080, v19
	ds_write2_b32 v2, v32, v33 offset1:1
	v_add_u32_e32 v2, 0x1088, v19
	ds_write2_b32 v2, v34, v35 offset1:1
	v_add_u32_e32 v2, 0x14a0, v19
	ds_write2_b32 v2, v36, v37 offset1:1
	v_add_u32_e32 v2, 0x14a8, v19
	ds_write2_b32 v2, v38, v39 offset1:1
	v_add_u32_e32 v2, 0x18c0, v19
	ds_write2_b32 v2, v40, v41 offset1:1
	v_add_u32_e32 v2, 0x18c8, v19
	ds_write2_b32 v2, v42, v43 offset1:1
	v_add_u32_e32 v2, 0x1ce0, v19
	ds_write2_b32 v2, v44, v45 offset1:1
	v_add_u32_e32 v2, 0x1ce8, v19
	ds_write2_b32 v2, v46, v47 offset1:1
	s_waitcnt lgkmcnt(0)
	s_nop 1
	v_readlane_b32 s100, v255, 40
	v_readlane_b32 s101, v255, 41
	s_nop 1
	v_writelane_b32 v255, s100, 16
	v_writelane_b32 v255, s101, 17
	s_nop 1
	v_readlane_b32 s100, v255, 42
	v_readlane_b32 s101, v255, 43
	s_nop 1
	v_writelane_b32 v255, s100, 18
	v_writelane_b32 v255, s101, 19
	s_nop 1
	v_readlane_b32 s100, v255, 44
	v_readlane_b32 s101, v255, 45
	s_nop 1
	v_writelane_b32 v255, s100, 20
	v_writelane_b32 v255, s101, 21
	s_nop 1
	v_readlane_b32 s100, v255, 46
	v_readlane_b32 s101, v255, 47
	s_nop 1
	v_writelane_b32 v255, s100, 22
	v_writelane_b32 v255, s101, 23
	s_nop 1
	v_readlane_b32 s100, v255, 48
	v_readlane_b32 s101, v255, 49
	s_nop 1
	v_writelane_b32 v255, s100, 24
	v_writelane_b32 v255, s101, 25
	s_nop 1
	v_readlane_b32 s100, v255, 50
	v_readlane_b32 s101, v255, 51
	s_nop 1
	v_writelane_b32 v255, s100, 26
	v_writelane_b32 v255, s101, 27
	s_nop 1
	v_readlane_b32 s100, v255, 52
	s_nop 1
	v_writelane_b32 v255, s100, 28
	s_nop 1
	s_add_i32 s17, s17, s18
	s_cmp_lt_i32 s17, s16
	s_cbranch_scc0 .Lcv_drain_G1
	s_mov_b32 s99, 1
	s_branch .LBB0_672

.Lcv_tail_G1:
	s_nop 1
	v_readlane_b32 s4, v255, 16
	v_readlane_b32 s5, v255, 17
	v_readlane_b32 s6, v255, 18
	v_readlane_b32 s7, v255, 19
	v_readlane_b32 s8, v255, 20
	v_readlane_b32 s9, v255, 21
	v_readlane_b32 s10, v255, 22
	v_readlane_b32 s11, v255, 23
	v_readlane_b32 s14, v255, 24
	v_readlane_b32 s15, v255, 25
	v_readlane_b32 s34, v255, 26
	v_readlane_b32 s35, v255, 27
	v_readlane_b32 s44, v255, 28
	s_nop 4
	v_mov_b32_e32 v106, v6
	v_or_b32_e32 v107, s8, v10
	s_cmp_gt_i32 s34, 2
	s_mov_b64 s[10:11], -1
	ds_read2_b32 v[102:103], v15 offset1:33
	s_waitcnt lgkmcnt(0)
	v_cvt_pk_bf16_f32 v102, v102, v103
	ds_read2_b32 v[104:105], v15 offset0:66 offset1:99
	s_waitcnt lgkmcnt(0)
	v_cvt_pk_bf16_f32 v103, v104, v105
	ds_read2_b32 v[104:105], v15 offset0:132 offset1:165
	s_waitcnt lgkmcnt(0)
	v_cvt_pk_bf16_f32 v104, v104, v105
	ds_read2_b32 v[108:109], v15 offset0:198 offset1:231
	s_waitcnt lgkmcnt(0)
	v_cvt_pk_bf16_f32 v105, v108, v109
	s_cbranch_scc0 .LBB0_706
	v_and_or_b32 v121, v107, s91, v14
	s_mov_b64 s[10:11], 0
.LBB0_706:
	s_lshl_b32 s9, s35, 6
	s_and_b32 s9, s9, 0xffffff00
	s_or_b32 s9, s44, s9
	s_andn2_b64 vcc, exec, s[10:11]
	v_or_b32_e32 v120, s9, v14
	s_cbranch_vccnz .LBB0_710
	s_cmp_lg_u32 s34, 0
	s_cbranch_scc0 .LBB0_709
	s_movk_i32 s9, 0x63
	v_and_or_b32 v107, v107, s9, v120

.LBB0_710:
	s_lshl_b64 s[10:11], s[14:15], 1
	s_add_u32 s6, s6, s10
	s_addc_u32 s7, s7, s11
	v_mov_b32_e32 v107, v1
	v_lshl_add_u64 v[108:109], s[6:7], 0, v[106:107]
	v_ashrrev_i32_e32 v107, 31, v121
	v_mul_lo_u32 v126, s5, v121
	v_mul_lo_u32 v107, s4, v107
	v_mad_u64_u32 v[124:125], s[6:7], s4, v121, 0
	v_add3_u32 v125, v125, v107, v126
	v_lshl_add_u64 v[124:125], v[124:125], 1, v[108:109]
	ds_read2_b32 v[122:123], v15 offset0:8 offset1:41
	global_store_dwordx4 v[124:125], v[102:105], off
	v_or_b32_e32 v121, s8, v11
	s_cmp_gt_i32 s34, 2
	s_waitcnt lgkmcnt(0)
	v_cvt_pk_bf16_f32 v102, v122, v123
	ds_read2_b32 v[104:105], v15 offset0:74 offset1:107
	s_waitcnt lgkmcnt(0)
	v_cvt_pk_bf16_f32 v103, v104, v105
	ds_read2_b32 v[104:105], v15 offset0:140 offset1:173
	s_mov_b64 s[6:7], -1
	s_waitcnt lgkmcnt(0)
	v_cvt_pk_bf16_f32 v104, v104, v105
	ds_read2_b32 v[122:123], v15 offset0:206 offset1:239
	s_waitcnt lgkmcnt(0)
	v_cvt_pk_bf16_f32 v105, v122, v123
	s_cbranch_scc0 .LBB0_712
	v_and_or_b32 v107, v121, s91, v16
	s_mov_b64 s[6:7], 0
.LBB0_712:
	s_andn2_b64 vcc, exec, s[6:7]
	s_cbranch_vccnz .LBB0_716
	s_cmp_lg_u32 s34, 0
	s_cbranch_scc0 .LBB0_715
	v_and_b32_e32 v107, 0x63, v121
	v_or3_b32 v121, v107, v120, 4

.LBB0_716:
	v_ashrrev_i32_e32 v121, 31, v107
	v_mul_lo_u32 v126, s5, v107
	v_mul_lo_u32 v121, s4, v121
	v_mad_u64_u32 v[124:125], s[6:7], s4, v107, 0
	v_add3_u32 v125, v125, v121, v126
	v_lshl_add_u64 v[124:125], v[124:125], 1, v[108:109]
	ds_read2_b32 v[122:123], v15 offset0:16 offset1:49
	global_store_dwordx4 v[124:125], v[102:105], off
	v_or_b32_e32 v121, s8, v12
	s_cmp_gt_i32 s34, 2
	s_waitcnt lgkmcnt(0)
	v_cvt_pk_bf16_f32 v102, v122, v123
	ds_read2_b32 v[104:105], v15 offset0:82 offset1:115
	s_waitcnt lgkmcnt(0)
	v_cvt_pk_bf16_f32 v103, v104, v105
	ds_read2_b32 v[104:105], v15 offset0:148 offset1:181
	s_mov_b64 s[6:7], -1
	s_waitcnt lgkmcnt(0)
	v_cvt_pk_bf16_f32 v104, v104, v105
	ds_read2_b32 v[122:123], v15 offset0:214 offset1:247
	s_waitcnt lgkmcnt(0)
	v_cvt_pk_bf16_f32 v105, v122, v123
	s_cbranch_scc0 .LBB0_718
	v_and_or_b32 v107, v121, s91, v17
	s_mov_b64 s[6:7], 0
.LBB0_718:
	s_andn2_b64 vcc, exec, s[6:7]
	s_cbranch_vccnz .LBB0_722
	s_cmp_lg_u32 s34, 0
	s_cbranch_scc0 .LBB0_721
	v_and_b32_e32 v107, 0x63, v121
	v_or3_b32 v121, v107, v120, 8

.LBB0_722:
	v_ashrrev_i32_e32 v121, 31, v107
	v_mul_lo_u32 v126, s5, v107
	v_mul_lo_u32 v121, s4, v121
	v_mad_u64_u32 v[124:125], s[6:7], s4, v107, 0
	v_add3_u32 v125, v125, v121, v126
	v_lshl_add_u64 v[124:125], v[124:125], 1, v[108:109]
	ds_read2_b32 v[122:123], v15 offset0:24 offset1:57
	global_store_dwordx4 v[124:125], v[102:105], off
	v_or_b32_e32 v107, s8, v13
	s_cmp_gt_i32 s34, 2
	s_waitcnt lgkmcnt(0)
	v_cvt_pk_bf16_f32 v102, v122, v123
	ds_read2_b32 v[104:105], v15 offset0:90 offset1:123
	s_waitcnt lgkmcnt(0)
	v_cvt_pk_bf16_f32 v103, v104, v105
	ds_read2_b32 v[104:105], v15 offset0:156 offset1:189
	s_mov_b64 s[6:7], -1
	s_waitcnt lgkmcnt(0)
	v_cvt_pk_bf16_f32 v104, v104, v105
	ds_read2_b32 v[122:123], v15 offset0:222 offset1:255
	s_waitcnt lgkmcnt(0)
	v_cvt_pk_bf16_f32 v105, v122, v123
	s_cbranch_scc0 .LBB0_724
	v_and_or_b32 v121, v107, s91, v18
	s_mov_b64 s[6:7], 0
.LBB0_724:
	s_andn2_b64 vcc, exec, s[6:7]
	s_cbranch_vccnz .LBB0_671
	s_cmp_lg_u32 s34, 0
	s_cbranch_scc0 .LBB0_670
	v_and_b32_e32 v107, 0x63, v107
	v_or3_b32 v107, v107, v120, 12
	s_branch .LBB0_670

.LBB0_818:
	ds_bpermute_b32 v0, v125, v117
	s_mulk_i32 s71, 0x1300
	s_waitcnt lgkmcnt(0)
	v_add_f32_e32 v0, v117, v0
	v_div_scale_f32 v2, s[8:9], v0, v0, 1.0
	v_rcp_f32_e32 v3, v2
	v_div_scale_f32 v4, vcc, 1.0, v0, 1.0
	s_add_i32 s8, s71, 0
	v_fma_f32 v5, -v2, v3, 1.0
	v_fmac_f32_e32 v3, v5, v3
	v_mul_f32_e32 v5, v4, v3
	v_fma_f32 v6, -v2, v5, v4
	v_fmac_f32_e32 v5, v6, v3
	v_fma_f32 v2, -v2, v5, v4
	v_div_fmas_f32 v2, v2, v3, v5
	v_div_fixup_f32 v0, v2, v0, 1.0
	v_mul_f32_e32 v2, v32, v0
	v_mul_f32_e32 v3, v33, v0
	v_mul_f32_e32 v4, v34, v0
	v_mul_f32_e32 v5, v35, v0
	v_cvt_pk_bf16_f32 v2, v2, v3
	v_cvt_pk_bf16_f32 v3, v4, v5
	v_add3_u32 v4, s8, v119, v104
	ds_write_b64 v4, v[2:3] offset:43008
	v_mul_f32_e32 v2, v36, v0
	v_mul_f32_e32 v3, v37, v0
	v_mul_f32_e32 v5, v38, v0
	v_mul_f32_e32 v6, v39, v0
	v_cvt_pk_bf16_f32 v2, v2, v3
	v_cvt_pk_bf16_f32 v3, v5, v6
	ds_write_b64 v4, v[2:3] offset:43024
	v_mul_f32_e32 v2, v40, v0
	v_mul_f32_e32 v3, v41, v0
	v_mul_f32_e32 v5, v42, v0
	v_mul_f32_e32 v6, v43, v0
	v_cvt_pk_bf16_f32 v2, v2, v3
	v_cvt_pk_bf16_f32 v3, v5, v6
	ds_write_b64 v4, v[2:3] offset:43040
	v_mul_f32_e32 v2, v44, v0
	v_mul_f32_e32 v3, v45, v0
	v_mul_f32_e32 v5, v46, v0
	v_mul_f32_e32 v6, v47, v0
	v_cvt_pk_bf16_f32 v2, v2, v3
	v_cvt_pk_bf16_f32 v3, v5, v6
	ds_write_b64 v4, v[2:3] offset:43056
	v_mul_f32_e32 v2, v16, v0
	v_mul_f32_e32 v3, v17, v0
	v_mul_f32_e32 v5, v18, v0
	v_mul_f32_e32 v6, v19, v0
	v_cvt_pk_bf16_f32 v2, v2, v3
	v_cvt_pk_bf16_f32 v3, v5, v6
	ds_write_b64 v4, v[2:3] offset:43072
	v_mul_f32_e32 v2, v20, v0
	v_mul_f32_e32 v3, v21, v0
	v_mul_f32_e32 v5, v22, v0
	v_mul_f32_e32 v6, v23, v0
	v_cvt_pk_bf16_f32 v2, v2, v3
	v_cvt_pk_bf16_f32 v3, v5, v6
	ds_write_b64 v4, v[2:3] offset:43088
	v_mul_f32_e32 v2, v24, v0
	v_mul_f32_e32 v3, v25, v0
	v_mul_f32_e32 v5, v26, v0
	v_mul_f32_e32 v6, v27, v0
	v_cvt_pk_bf16_f32 v2, v2, v3
	v_cvt_pk_bf16_f32 v3, v5, v6
	ds_write_b64 v4, v[2:3] offset:43104
	v_mul_f32_e32 v2, v28, v0
	v_mul_f32_e32 v3, v29, v0
	v_mul_f32_e32 v5, v30, v0
	v_mul_f32_e32 v0, v31, v0
	v_cvt_pk_bf16_f32 v2, v2, v3
	v_cvt_pk_bf16_f32 v3, v5, v0
	ds_write_b64 v4, v[2:3] offset:43120
	s_waitcnt lgkmcnt(0)
	v_add3_u32 v0, s8, v126, v128
	s_ashr_i32 s8, s69, 1
	ds_read_b128 v[2:5], v0 offset:43008
	ds_read_b128 v[6:9], v0 offset:44160
	ds_read_b128 v[10:13], v0 offset:45312
	ds_read_b128 v[14:17], v0 offset:46464
	v_or_b32_e32 v0, s68, v127
	s_andn2_b32 s8, s8, 63
	v_lshlrev_b32_e32 v0, 12, v0
	s_ashr_i32 s9, s8, 31
	v_lshl_add_u64 v[18:19], s[6:7], 0, v[0:1]
	s_lshl_b64 s[8:9], s[8:9], 1
	v_lshl_add_u64 v[18:19], v[18:19], 0, s[8:9]
	v_mov_b32_e32 v117, v1
	v_or_b32_e32 v0, s68, v129
	v_lshl_add_u64 v[18:19], v[18:19], 0, v[116:117]
	v_lshlrev_b32_e32 v0, 12, v0
	s_waitcnt lgkmcnt(0)
	s_waitcnt lgkmcnt(3)
	global_store_dwordx4 v[18:19], v[2:5], off
	s_andn2_b64 vcc, exec, s[18:19]
	s_nop 0
	v_lshl_add_u64 v[2:3], s[6:7], 0, v[0:1]
	v_lshl_add_u64 v[2:3], v[2:3], 0, s[8:9]
	v_or_b32_e32 v0, s68, v130
	v_lshl_add_u64 v[2:3], v[2:3], 0, v[116:117]
	v_lshlrev_b32_e32 v0, 12, v0
	s_waitcnt lgkmcnt(2)
	global_store_dwordx4 v[2:3], v[6:9], off
	v_lshl_add_u64 v[2:3], s[6:7], 0, v[0:1]
	v_lshl_add_u64 v[2:3], v[2:3], 0, s[8:9]
	v_or_b32_e32 v0, s68, v131
	v_lshl_add_u64 v[2:3], v[2:3], 0, v[116:117]
	v_lshlrev_b32_e32 v0, 12, v0
	s_waitcnt lgkmcnt(1)
	global_store_dwordx4 v[2:3], v[10:13], off
	v_lshl_add_u64 v[2:3], s[6:7], 0, v[0:1]
	v_lshl_add_u64 v[2:3], v[2:3], 0, s[8:9]
	v_lshl_add_u64 v[2:3], v[2:3], 0, v[116:117]
	s_waitcnt lgkmcnt(0)
	global_store_dwordx4 v[2:3], v[14:17], off
	s_cbranch_vccnz .LBB0_779
	s_barrier
	s_branch .LBB0_779

.LBB0_914:
	s_or_b64 exec, exec, s[24:25]
	v_ashrrev_i32_e32 v211, 31, v210
	v_lshlrev_b64 v[148:149], 12, v[210:211]
	v_lshl_add_u64 v[2:3], s[6:7], 0, v[148:149]
	v_lshlrev_b64 v[146:147], 1, v[208:209]
	v_lshl_add_u64 v[6:7], v[2:3], 0, v[146:147]
	v_cvt_pk_bf16_f32 v2, v126, v127
	v_cvt_pk_bf16_f32 v3, v128, v129
	v_cvt_pk_bf16_f32 v4, v122, v123
	v_cvt_pk_bf16_f32 v5, v124, v125
	global_store_dwordx4 v[6:7], v[2:5], off
	s_lshl_b32 s18, s56, 11
	s_mov_b32 s19, s50
	v_cvt_pk_bf16_f32 v2, v118, v119
	v_cvt_pk_bf16_f32 v3, v120, v121
	v_cvt_pk_bf16_f32 v4, v114, v115
	v_cvt_pk_bf16_f32 v5, v116, v117
	global_store_dwordx4 v[6:7], v[2:5], off offset:256
	s_lshl_b64 s[18:19], s[18:19], 2
	s_add_u32 s16, s16, s18
	v_or_b32_e32 v2, 16, v210
	v_ashrrev_i32_e32 v3, 31, v2
	v_lshlrev_b64 v[150:151], 12, v[2:3]
	v_lshl_add_u64 v[2:3], s[6:7], 0, v[150:151]
	v_lshl_add_u64 v[6:7], v[2:3], 0, v[146:147]
	v_cvt_pk_bf16_f32 v2, v110, v111
	v_cvt_pk_bf16_f32 v3, v112, v113
	v_cvt_pk_bf16_f32 v4, v106, v107
	v_cvt_pk_bf16_f32 v5, v108, v109
	global_store_dwordx4 v[6:7], v[2:5], off
	s_addc_u32 s17, s17, s19
	s_mov_b64 s[18:19], 0x80000
	v_cvt_pk_bf16_f32 v2, v102, v103
	v_cvt_pk_bf16_f32 v3, v104, v105
	v_cvt_pk_bf16_f32 v4, v94, v95
	v_cvt_pk_bf16_f32 v5, v96, v97
	global_store_dwordx4 v[6:7], v[2:5], off offset:256
	v_lshl_add_u64 v[188:189], v[148:149], 0, s[18:19]
	s_mov_b64 s[18:19], 0x90000
	v_or_b32_e32 v2, 32, v210
	v_ashrrev_i32_e32 v3, 31, v2
	v_lshlrev_b64 v[152:153], 12, v[2:3]
	v_lshl_add_u64 v[2:3], s[6:7], 0, v[152:153]
	v_lshl_add_u64 v[6:7], v[2:3], 0, v[146:147]
	v_cvt_pk_bf16_f32 v2, v98, v99
	v_cvt_pk_bf16_f32 v3, v100, v101
	v_cvt_pk_bf16_f32 v4, v90, v91
	v_cvt_pk_bf16_f32 v5, v92, v93
	global_store_dwordx4 v[6:7], v[2:5], off
	v_lshl_add_u64 v[190:191], v[148:149], 0, s[18:19]
	s_mov_b64 s[18:19], 0xa0000
	v_cvt_pk_bf16_f32 v2, v86, v87
	v_cvt_pk_bf16_f32 v3, v88, v89
	v_cvt_pk_bf16_f32 v4, v78, v79
	v_cvt_pk_bf16_f32 v5, v80, v81
	global_store_dwordx4 v[6:7], v[2:5], off offset:256
	v_lshl_add_u64 v[192:193], v[148:149], 0, s[18:19]
	s_mov_b64 s[18:19], 0xb0000
	v_or_b32_e32 v2, 48, v210
	v_ashrrev_i32_e32 v3, 31, v2
	v_lshlrev_b64 v[186:187], 12, v[2:3]
	v_lshl_add_u64 v[2:3], s[6:7], 0, v[186:187]
	v_lshl_add_u64 v[6:7], v[2:3], 0, v[146:147]
	v_cvt_pk_bf16_f32 v2, v82, v83
	v_cvt_pk_bf16_f32 v3, v84, v85
	v_cvt_pk_bf16_f32 v4, v74, v75
	v_cvt_pk_bf16_f32 v5, v76, v77
	global_store_dwordx4 v[6:7], v[2:5], off
	v_lshl_add_u64 v[194:195], v[148:149], 0, s[18:19]
	v_and_b32_e32 v0, 7, v212
	v_cvt_pk_bf16_f32 v2, v70, v71
	v_cvt_pk_bf16_f32 v3, v72, v73
	v_cvt_pk_bf16_f32 v4, v66, v67
	v_cvt_pk_bf16_f32 v5, v68, v69
	global_store_dwordx4 v[6:7], v[2:5], off offset:256
	v_lshlrev_b32_e32 v0, 3, v0
	s_nop 0
	v_lshl_add_u64 v[2:3], s[6:7], 0, v[188:189]
	v_lshl_add_u64 v[6:7], v[2:3], 0, v[146:147]
	v_cvt_pk_bf16_f32 v2, v176, v177
	v_cvt_pk_bf16_f32 v3, v174, v175
	v_cvt_pk_bf16_f32 v4, v180, v181
	v_cvt_pk_bf16_f32 v5, v178, v179
	global_store_dwordx4 v[6:7], v[2:5], off
	s_nop 1
	v_cvt_pk_bf16_f32 v2, v54, v55
	v_cvt_pk_bf16_f32 v3, v56, v57
	v_cvt_pk_bf16_f32 v4, v60, v61
	v_cvt_pk_bf16_f32 v5, v58, v59
	global_store_dwordx4 v[6:7], v[2:5], off offset:256
	s_nop 1
	v_lshl_add_u64 v[2:3], s[6:7], 0, v[190:191]
	v_lshl_add_u64 v[6:7], v[2:3], 0, v[146:147]
	v_cvt_pk_bf16_f32 v2, v170, v171
	v_cvt_pk_bf16_f32 v3, v166, v167
	v_cvt_pk_bf16_f32 v4, v172, v173
	v_cvt_pk_bf16_f32 v5, v168, v169
	global_store_dwordx4 v[6:7], v[2:5], off
	s_nop 1
	v_cvt_pk_bf16_f32 v2, v62, v63
	v_cvt_pk_bf16_f32 v3, v50, v51
	v_cvt_pk_bf16_f32 v4, v64, v65
	v_cvt_pk_bf16_f32 v5, v52, v53
	global_store_dwordx4 v[6:7], v[2:5], off offset:256
	s_nop 1
	v_lshl_add_u64 v[2:3], s[6:7], 0, v[192:193]
	v_lshl_add_u64 v[6:7], v[2:3], 0, v[146:147]
	v_cvt_pk_bf16_f32 v2, v164, v165
	v_cvt_pk_bf16_f32 v3, v162, v163
	v_cvt_pk_bf16_f32 v4, v184, v185
	v_cvt_pk_bf16_f32 v5, v182, v183
	global_store_dwordx4 v[6:7], v[2:5], off
	s_nop 1
	v_cvt_pk_bf16_f32 v2, v156, v157
	v_cvt_pk_bf16_f32 v3, v154, v155
	v_cvt_pk_bf16_f32 v4, v160, v161
	v_cvt_pk_bf16_f32 v5, v158, v159
	global_store_dwordx4 v[6:7], v[2:5], off offset:256
	s_nop 1
	v_lshl_add_u64 v[2:3], s[6:7], 0, v[194:195]
	s_add_u32 s6, s20, 0x8000
	v_lshl_add_u64 v[6:7], v[2:3], 0, v[146:147]
	v_cvt_pk_bf16_f32 v2, v142, v143
	v_cvt_pk_bf16_f32 v3, v144, v145
	s_addc_u32 s7, s21, 0
	v_cvt_pk_bf16_f32 v4, v138, v139
	v_cvt_pk_bf16_f32 v5, v140, v141
	global_store_dwordx4 v[6:7], v[2:5], off
	s_add_u32 s18, s20, 0x6000
	s_addc_u32 s19, s21, 0
	v_cvt_pk_bf16_f32 v2, v134, v135
	v_cvt_pk_bf16_f32 v3, v136, v137
	v_cvt_pk_bf16_f32 v4, v130, v131
	v_cvt_pk_bf16_f32 v5, v132, v133
	global_store_dwordx4 v[6:7], v[2:5], off offset:256
	s_nop 1
	v_lshlrev_b64 v[2:3], 2, v[208:209]
	v_lshl_add_u64 v[4:5], s[16:17], 0, v[2:3]
	v_lshl_add_u64 v[6:7], s[6:7], 0, v[2:3]
	v_lshl_add_u64 v[2:3], s[18:19], 0, v[2:3]
	global_load_dwordx4 v[18:21], v[4:5], off offset:16
	global_load_dwordx4 v[26:29], v[4:5], off
	global_load_dwordx4 v[30:33], v[6:7], off offset:16
	global_load_dwordx4 v[34:37], v[6:7], off
	global_load_dwordx4 v[10:13], v[2:3], off offset:16
	global_load_dwordx4 v[14:17], v[2:3], off
	v_or_b32_e32 v2, 0x80, v208
	v_ashrrev_i32_e32 v3, 31, v2
	v_lshlrev_b64 v[2:3], 2, v[2:3]
	global_load_dwordx4 v[22:25], v[4:5], off offset:528
	global_load_dwordx4 v[38:41], v[4:5], off offset:512
	v_lshl_add_u64 v[4:5], s[6:7], 0, v[2:3]
	v_lshl_add_u64 v[6:7], s[18:19], 0, v[2:3]
	global_load_dwordx4 v[42:45], v[4:5], off offset:16
	global_load_dwordx4 v[46:49], v[4:5], off
	s_nop 0
	global_load_dwordx4 v[2:5], v[6:7], off offset:16
	s_nop 0
	global_load_dwordx4 v[6:9], v[6:7], off
	s_add_i32 s6, s26, s28
	s_memrealtime s[16:17]
	s_ashr_i32 s7, s6, 31
	s_lshl_b64 s[6:7], s[6:7], 6
	s_add_u32 s6, s8, s6
	s_addc_u32 s7, s9, s7
	v_lshl_add_u64 v[198:199], s[6:7], 0, v[0:1]
	v_cmp_gt_u32_e64 s[6:7], 8, v226
	s_branch .LBB0_916

.LBB0_931:
	s_or_b64 exec, exec, s[6:7]
	s_lshl_b32 s4, s80, 2
	v_pk_add_f32 v[36:37], v[36:37], 1.0 op_sel_hi:[1,0]
	v_pk_add_f32 v[196:197], v[34:35], 1.0 op_sel_hi:[1,0]
	s_add_i32 s4, s4, 0
	v_pk_mul_f32 v[34:35], v[28:29], v[36:37]
	v_pk_mul_f32 v[36:37], v[26:27], v[196:197]
	v_pk_add_f32 v[26:27], v[32:33], 1.0 op_sel_hi:[1,0]
	v_lshl_add_u32 v0, v221, 2, s4
	v_pk_mul_f32 v[196:197], v[20:21], v[26:27]
	v_pk_add_f32 v[20:21], v[46:47], 1.0 op_sel_hi:[1,0]
	s_waitcnt lgkmcnt(0)
	s_barrier
	v_add_u32_e32 v0, 0x2000, v0
	v_pk_mul_f32 v[20:21], v[38:39], v[20:21]
	ds_read2_b32 v[38:39], v0 offset1:16
	v_pk_add_f32 v[28:29], v[30:31], 1.0 op_sel_hi:[1,0]
	v_pk_add_f32 v[26:27], v[44:45], 1.0 op_sel_hi:[1,0]
	v_pk_mul_f32 v[32:33], v[18:19], v[28:29]
	v_pk_add_f32 v[18:19], v[48:49], 1.0 op_sel_hi:[1,0]
	v_pk_add_f32 v[28:29], v[42:43], 1.0 op_sel_hi:[1,0]
	v_pk_mul_f32 v[18:19], v[40:41], v[18:19]
	s_waitcnt lgkmcnt(0)
	v_pk_mul_f32 v[40:41], v[128:129], v[38:39] op_sel_hi:[1,0]
	v_pk_mul_f32 v[42:43], v[126:127], v[38:39] op_sel_hi:[1,0]
	v_pk_fma_f32 v[40:41], v[34:35], v[40:41], v[16:17]
	v_pk_fma_f32 v[42:43], v[36:37], v[42:43], v[14:15]
	v_pk_mul_f32 v[22:23], v[22:23], v[28:29]
	v_pk_mul_f32 v[24:25], v[24:25], v[26:27]
	ds_read2_b32 v[30:31], v0 offset0:32 offset1:48
	ds_read2_b32 v[28:29], v0 offset0:128 offset1:144
	ds_read2_b32 v[26:27], v0 offset0:160 offset1:176
	v_pk_mul_f32 v[44:45], v[124:125], v[38:39] op_sel_hi:[1,0]
	v_pk_mul_f32 v[46:47], v[122:123], v[38:39] op_sel_hi:[1,0]
	v_cvt_pk_bf16_f32 v42, v42, v43
	v_cvt_pk_bf16_f32 v43, v40, v41
	v_lshl_add_u64 v[40:41], s[22:23], 0, v[148:149]
	v_pk_fma_f32 v[48:49], v[196:197], v[44:45], v[12:13]
	v_pk_fma_f32 v[44:45], v[32:33], v[46:47], v[10:11]
	v_lshl_add_u64 v[40:41], v[40:41], 0, v[146:147]
	v_mov_b32_e32 v0, v39
	v_cvt_pk_bf16_f32 v44, v44, v45
	v_cvt_pk_bf16_f32 v45, v48, v49
	global_store_dwordx4 v[40:41], v[42:45], off
	v_pk_mul_f32 v[46:47], v[108:109], v[0:1] op_sel_hi:[1,0]
	v_pk_mul_f32 v[48:49], v[106:107], v[0:1] op_sel_hi:[1,0]
	v_pk_mul_f32 v[42:43], v[112:113], v[0:1] op_sel_hi:[1,0]
	v_pk_mul_f32 v[44:45], v[110:111], v[0:1] op_sel_hi:[1,0]
	v_pk_fma_f32 v[42:43], v[34:35], v[42:43], v[16:17]
	v_pk_fma_f32 v[44:45], v[36:37], v[44:45], v[14:15]
	v_pk_fma_f32 v[106:107], v[196:197], v[46:47], v[12:13]
	v_cvt_pk_bf16_f32 v46, v44, v45
	v_cvt_pk_bf16_f32 v47, v42, v43
	v_lshl_add_u64 v[42:43], s[22:23], 0, v[150:151]
	v_pk_fma_f32 v[48:49], v[32:33], v[48:49], v[10:11]
	v_lshl_add_u64 v[44:45], v[42:43], 0, v[146:147]
	v_cvt_pk_bf16_f32 v48, v48, v49
	v_cvt_pk_bf16_f32 v49, v106, v107
	global_store_dwordx4 v[44:45], v[46:49], off
	s_waitcnt lgkmcnt(2)
	v_pk_mul_f32 v[42:43], v[100:101], v[30:31] op_sel_hi:[1,0]
	v_pk_mul_f32 v[90:91], v[90:91], v[30:31] op_sel_hi:[1,0]
	v_pk_mul_f32 v[46:47], v[98:99], v[30:31] op_sel_hi:[1,0]
	v_pk_fma_f32 v[42:43], v[34:35], v[42:43], v[16:17]
	v_pk_fma_f32 v[46:47], v[36:37], v[46:47], v[14:15]
	v_pk_mul_f32 v[48:49], v[92:93], v[30:31] op_sel_hi:[1,0]
	v_cvt_pk_bf16_f32 v46, v46, v47
	v_cvt_pk_bf16_f32 v47, v42, v43
	v_lshl_add_u64 v[42:43], s[22:23], 0, v[152:153]
	v_pk_fma_f32 v[92:93], v[196:197], v[48:49], v[12:13]
	v_pk_fma_f32 v[48:49], v[32:33], v[90:91], v[10:11]
	v_lshl_add_u64 v[90:91], v[42:43], 0, v[146:147]
	v_cvt_pk_bf16_f32 v48, v48, v49
	v_cvt_pk_bf16_f32 v49, v92, v93
	v_mov_b32_e32 v42, v31
	global_store_dwordx4 v[90:91], v[46:49], off
	v_pk_mul_f32 v[74:75], v[74:75], v[42:43] op_sel_hi:[1,0]
	s_mov_b64 s[4:5], 0x100
	v_pk_mul_f32 v[46:47], v[84:85], v[42:43] op_sel_hi:[1,0]
	v_pk_mul_f32 v[48:49], v[82:83], v[42:43] op_sel_hi:[1,0]
	v_pk_fma_f32 v[82:83], v[34:35], v[46:47], v[16:17]
	v_pk_fma_f32 v[46:47], v[36:37], v[48:49], v[14:15]
	v_pk_mul_f32 v[48:49], v[76:77], v[42:43] op_sel_hi:[1,0]
	v_cvt_pk_bf16_f32 v46, v46, v47
	v_cvt_pk_bf16_f32 v47, v82, v83
	s_waitcnt lgkmcnt(1)
	v_pk_mul_f32 v[82:83], v[180:181], v[28:29] op_sel_hi:[1,0]
	v_pk_fma_f32 v[76:77], v[196:197], v[48:49], v[12:13]
	v_pk_fma_f32 v[48:49], v[32:33], v[74:75], v[10:11]
	v_lshl_add_u64 v[74:75], s[22:23], 0, v[186:187]
	v_cvt_pk_bf16_f32 v48, v48, v49
	v_cvt_pk_bf16_f32 v49, v76, v77
	v_lshl_add_u64 v[74:75], v[74:75], 0, v[146:147]
	global_store_dwordx4 v[74:75], v[46:49], off
	s_mov_b64 s[16:17], -1
	s_nop 0
	v_pk_mul_f32 v[46:47], v[174:175], v[28:29] op_sel_hi:[1,0]
	v_pk_mul_f32 v[48:49], v[176:177], v[28:29] op_sel_hi:[1,0]
	v_pk_fma_f32 v[76:77], v[34:35], v[46:47], v[16:17]
	v_pk_fma_f32 v[46:47], v[36:37], v[48:49], v[14:15]
	v_pk_mul_f32 v[48:49], v[178:179], v[28:29] op_sel_hi:[1,0]
	v_cvt_pk_bf16_f32 v46, v46, v47
	v_cvt_pk_bf16_f32 v47, v76, v77
	v_lshl_add_u64 v[76:77], s[22:23], 0, v[188:189]
	v_pk_fma_f32 v[84:85], v[196:197], v[48:49], v[12:13]
	v_pk_fma_f32 v[48:49], v[32:33], v[82:83], v[10:11]
	v_lshl_add_u64 v[76:77], v[76:77], 0, v[146:147]
	v_cvt_pk_bf16_f32 v48, v48, v49
	v_cvt_pk_bf16_f32 v49, v84, v85
	v_mov_b32_e32 v82, v29
	global_store_dwordx4 v[76:77], v[46:49], off
	v_pk_mul_f32 v[92:93], v[172:173], v[82:83] op_sel_hi:[1,0]
	s_nop 0
	v_pk_mul_f32 v[46:47], v[166:167], v[82:83] op_sel_hi:[1,0]
	v_pk_mul_f32 v[48:49], v[170:171], v[82:83] op_sel_hi:[1,0]
	v_pk_fma_f32 v[84:85], v[34:35], v[46:47], v[16:17]
	v_pk_fma_f32 v[46:47], v[36:37], v[48:49], v[14:15]
	v_pk_mul_f32 v[48:49], v[168:169], v[82:83] op_sel_hi:[1,0]
	v_cvt_pk_bf16_f32 v46, v46, v47
	v_cvt_pk_bf16_f32 v47, v84, v85
	v_lshl_add_u64 v[84:85], s[22:23], 0, v[190:191]
	v_pk_fma_f32 v[98:99], v[196:197], v[48:49], v[12:13]
	v_pk_fma_f32 v[48:49], v[32:33], v[92:93], v[10:11]
	v_lshl_add_u64 v[84:85], v[84:85], 0, v[146:147]
	v_cvt_pk_bf16_f32 v48, v48, v49
	v_cvt_pk_bf16_f32 v49, v98, v99
	global_store_dwordx4 v[84:85], v[46:49], off
	s_waitcnt lgkmcnt(0)
	v_pk_mul_f32 v[98:99], v[184:185], v[26:27] op_sel_hi:[1,0]
	v_pk_mul_f32 v[46:47], v[162:163], v[26:27] op_sel_hi:[1,0]
	v_pk_mul_f32 v[48:49], v[164:165], v[26:27] op_sel_hi:[1,0]
	v_pk_fma_f32 v[92:93], v[34:35], v[46:47], v[16:17]
	v_pk_fma_f32 v[46:47], v[36:37], v[48:49], v[14:15]
	v_pk_mul_f32 v[48:49], v[182:183], v[26:27] op_sel_hi:[1,0]
	v_cvt_pk_bf16_f32 v46, v46, v47
	v_cvt_pk_bf16_f32 v47, v92, v93
	v_lshl_add_u64 v[92:93], s[22:23], 0, v[192:193]
	v_pk_fma_f32 v[100:101], v[196:197], v[48:49], v[12:13]
	v_pk_fma_f32 v[48:49], v[32:33], v[98:99], v[10:11]
	v_lshl_add_u64 v[92:93], v[92:93], 0, v[146:147]
	v_cvt_pk_bf16_f32 v48, v48, v49
	v_cvt_pk_bf16_f32 v49, v100, v101
	global_store_dwordx4 v[92:93], v[46:49], off
	s_nop 1
	v_mov_b32_e32 v46, v27
	v_pk_mul_f32 v[48:49], v[144:145], v[46:47] op_sel_hi:[1,0]
	v_pk_mul_f32 v[98:99], v[142:143], v[46:47] op_sel_hi:[1,0]
	v_pk_fma_f32 v[16:17], v[34:35], v[48:49], v[16:17]
	v_pk_fma_f32 v[14:15], v[36:37], v[98:99], v[14:15]
	v_pk_mul_f32 v[34:35], v[140:141], v[46:47] op_sel_hi:[1,0]
	v_pk_mul_f32 v[36:37], v[138:139], v[46:47] op_sel_hi:[1,0]
	v_pk_fma_f32 v[34:35], v[196:197], v[34:35], v[12:13]
	v_pk_fma_f32 v[12:13], v[32:33], v[36:37], v[10:11]
	v_cvt_pk_bf16_f32 v10, v14, v15
	v_lshl_add_u64 v[14:15], s[22:23], 0, v[194:195]
	v_cvt_pk_bf16_f32 v11, v16, v17
	v_cvt_pk_bf16_f32 v12, v12, v13
	v_cvt_pk_bf16_f32 v13, v34, v35
	v_lshl_add_u64 v[14:15], v[14:15], 0, v[146:147]
	global_store_dwordx4 v[14:15], v[10:13], off
	v_pk_mul_f32 v[32:33], v[114:115], v[38:39] op_sel_hi:[1,0]
	s_nop 0
	v_pk_mul_f32 v[10:11], v[120:121], v[38:39] op_sel_hi:[1,0]
	v_pk_mul_f32 v[12:13], v[118:119], v[38:39] op_sel_hi:[1,0]
	v_pk_fma_f32 v[16:17], v[18:19], v[10:11], v[8:9]
	v_pk_fma_f32 v[10:11], v[20:21], v[12:13], v[6:7]
	v_pk_mul_f32 v[12:13], v[116:117], v[38:39] op_sel_hi:[1,0]
	v_cvt_pk_bf16_f32 v10, v10, v11
	v_cvt_pk_bf16_f32 v11, v16, v17
	s_nop 0
	v_pk_fma_f32 v[34:35], v[24:25], v[12:13], v[4:5]
	v_pk_fma_f32 v[12:13], v[22:23], v[32:33], v[2:3]
	v_pk_mul_f32 v[32:33], v[94:95], v[0:1] op_sel_hi:[1,0]
	v_cvt_pk_bf16_f32 v12, v12, v13
	v_cvt_pk_bf16_f32 v13, v34, v35
	global_store_dwordx4 v[40:41], v[10:13], off offset:256
	s_nop 1
	v_pk_mul_f32 v[10:11], v[104:105], v[0:1] op_sel_hi:[1,0]
	v_pk_mul_f32 v[12:13], v[102:103], v[0:1] op_sel_hi:[1,0]
	v_pk_fma_f32 v[16:17], v[18:19], v[10:11], v[8:9]
	v_pk_fma_f32 v[10:11], v[20:21], v[12:13], v[6:7]
	v_pk_mul_f32 v[12:13], v[96:97], v[0:1] op_sel_hi:[1,0]
	v_cvt_pk_bf16_f32 v10, v10, v11
	v_cvt_pk_bf16_f32 v11, v16, v17
	s_nop 0
	v_pk_fma_f32 v[34:35], v[24:25], v[12:13], v[4:5]
	v_pk_fma_f32 v[12:13], v[22:23], v[32:33], v[2:3]
	s_nop 0
	v_cvt_pk_bf16_f32 v12, v12, v13
	v_cvt_pk_bf16_f32 v13, v34, v35
	global_store_dwordx4 v[44:45], v[10:13], off offset:256
	s_nop 1
	v_pk_mul_f32 v[10:11], v[88:89], v[30:31] op_sel_hi:[1,0]
	v_pk_mul_f32 v[12:13], v[86:87], v[30:31] op_sel_hi:[1,0]
	v_pk_fma_f32 v[16:17], v[18:19], v[10:11], v[8:9]
	v_pk_fma_f32 v[10:11], v[20:21], v[12:13], v[6:7]
	v_pk_mul_f32 v[12:13], v[80:81], v[30:31] op_sel_hi:[1,0]
	v_pk_mul_f32 v[30:31], v[78:79], v[30:31] op_sel_hi:[1,0]
	v_pk_fma_f32 v[32:33], v[24:25], v[12:13], v[4:5]
	v_pk_fma_f32 v[12:13], v[22:23], v[30:31], v[2:3]
	v_cvt_pk_bf16_f32 v10, v10, v11
	v_cvt_pk_bf16_f32 v11, v16, v17
	v_pk_mul_f32 v[30:31], v[66:67], v[42:43] op_sel_hi:[1,0]
	v_cvt_pk_bf16_f32 v12, v12, v13
	v_cvt_pk_bf16_f32 v13, v32, v33
	global_store_dwordx4 v[90:91], v[10:13], off offset:256
	s_nop 1
	v_pk_mul_f32 v[10:11], v[72:73], v[42:43] op_sel_hi:[1,0]
	v_pk_mul_f32 v[12:13], v[70:71], v[42:43] op_sel_hi:[1,0]
	v_pk_fma_f32 v[16:17], v[18:19], v[10:11], v[8:9]
	v_pk_fma_f32 v[10:11], v[20:21], v[12:13], v[6:7]
	v_pk_mul_f32 v[12:13], v[68:69], v[42:43] op_sel_hi:[1,0]
	v_cvt_pk_bf16_f32 v10, v10, v11
	v_cvt_pk_bf16_f32 v11, v16, v17
	s_nop 0
	v_pk_fma_f32 v[32:33], v[24:25], v[12:13], v[4:5]
	v_pk_fma_f32 v[12:13], v[22:23], v[30:31], v[2:3]
	s_nop 0
	v_cvt_pk_bf16_f32 v12, v12, v13
	v_cvt_pk_bf16_f32 v13, v32, v33
	global_store_dwordx4 v[74:75], v[10:13], off offset:256
	s_nop 1
	v_pk_mul_f32 v[10:11], v[56:57], v[28:29] op_sel_hi:[1,0]
	v_pk_mul_f32 v[12:13], v[54:55], v[28:29] op_sel_hi:[1,0]
	v_pk_fma_f32 v[16:17], v[18:19], v[10:11], v[8:9]
	v_pk_fma_f32 v[10:11], v[20:21], v[12:13], v[6:7]
	v_pk_mul_f32 v[12:13], v[58:59], v[28:29] op_sel_hi:[1,0]
	v_pk_mul_f32 v[28:29], v[60:61], v[28:29] op_sel_hi:[1,0]
	v_pk_fma_f32 v[30:31], v[24:25], v[12:13], v[4:5]
	v_pk_fma_f32 v[12:13], v[22:23], v[28:29], v[2:3]
	v_cvt_pk_bf16_f32 v10, v10, v11
	v_cvt_pk_bf16_f32 v11, v16, v17
	v_pk_mul_f32 v[28:29], v[64:65], v[82:83] op_sel_hi:[1,0]
	v_cvt_pk_bf16_f32 v12, v12, v13
	v_cvt_pk_bf16_f32 v13, v30, v31
	global_store_dwordx4 v[76:77], v[10:13], off offset:256
	s_nop 1
	v_pk_mul_f32 v[10:11], v[50:51], v[82:83] op_sel_hi:[1,0]
	v_pk_mul_f32 v[12:13], v[62:63], v[82:83] op_sel_hi:[1,0]
	v_pk_fma_f32 v[16:17], v[18:19], v[10:11], v[8:9]
	v_pk_fma_f32 v[10:11], v[20:21], v[12:13], v[6:7]
	v_pk_mul_f32 v[12:13], v[52:53], v[82:83] op_sel_hi:[1,0]
	v_cvt_pk_bf16_f32 v10, v10, v11
	v_cvt_pk_bf16_f32 v11, v16, v17
	s_nop 0
	v_pk_fma_f32 v[30:31], v[24:25], v[12:13], v[4:5]
	v_pk_fma_f32 v[12:13], v[22:23], v[28:29], v[2:3]
	s_nop 0
	v_cvt_pk_bf16_f32 v12, v12, v13
	v_cvt_pk_bf16_f32 v13, v30, v31
	global_store_dwordx4 v[84:85], v[10:13], off offset:256
	s_nop 1
	v_pk_mul_f32 v[10:11], v[154:155], v[26:27] op_sel_hi:[1,0]
	v_pk_mul_f32 v[12:13], v[156:157], v[26:27] op_sel_hi:[1,0]
	v_pk_fma_f32 v[16:17], v[18:19], v[10:11], v[8:9]
	v_pk_fma_f32 v[10:11], v[20:21], v[12:13], v[6:7]
	v_pk_mul_f32 v[12:13], v[158:159], v[26:27] op_sel_hi:[1,0]
	v_pk_mul_f32 v[26:27], v[160:161], v[26:27] op_sel_hi:[1,0]
	v_pk_fma_f32 v[28:29], v[24:25], v[12:13], v[4:5]
	v_pk_fma_f32 v[12:13], v[22:23], v[26:27], v[2:3]
	v_cvt_pk_bf16_f32 v10, v10, v11
	v_cvt_pk_bf16_f32 v11, v16, v17
	s_nop 0
	v_cvt_pk_bf16_f32 v12, v12, v13
	v_cvt_pk_bf16_f32 v13, v28, v29
	global_store_dwordx4 v[92:93], v[10:13], off offset:256
	s_nop 1
	v_pk_mul_f32 v[10:11], v[136:137], v[46:47] op_sel_hi:[1,0]
	v_pk_mul_f32 v[12:13], v[134:135], v[46:47] op_sel_hi:[1,0]
	v_pk_fma_f32 v[8:9], v[18:19], v[10:11], v[8:9]
	v_pk_fma_f32 v[6:7], v[20:21], v[12:13], v[6:7]
	v_pk_mul_f32 v[10:11], v[132:133], v[46:47] op_sel_hi:[1,0]
	v_pk_mul_f32 v[12:13], v[130:131], v[46:47] op_sel_hi:[1,0]
	v_pk_fma_f32 v[10:11], v[24:25], v[10:11], v[4:5]
	v_pk_fma_f32 v[4:5], v[22:23], v[12:13], v[2:3]
	v_cvt_pk_bf16_f32 v2, v6, v7
	v_cvt_pk_bf16_f32 v3, v8, v9
	v_lshl_add_u64 v[6:7], v[14:15], 0, s[4:5]
	v_cvt_pk_bf16_f32 v4, v4, v5
	v_cvt_pk_bf16_f32 v5, v10, v11
	s_and_b64 vcc, exec, s[14:15]
	s_cbranch_vccz .LBB0_992

.LBB0_974:
	s_or_b64 exec, exec, s[18:19]
	s_add_u32 s10, s10, 0x15e12000
	v_ashrrev_i32_e32 v151, 31, v150
	s_addc_u32 s11, s11, 0
	v_lshlrev_b64 v[128:129], 12, v[150:151]
	v_lshl_add_u64 v[2:3], s[10:11], 0, v[128:129]
	v_lshlrev_b64 v[126:127], 1, v[146:147]
	v_lshl_add_u64 v[6:7], v[2:3], 0, v[126:127]
	v_cvt_pk_bf16_f32 v2, v142, v143
	v_cvt_pk_bf16_f32 v3, v144, v145
	v_ashrrev_i32_e32 v161, 31, v160
	v_cvt_pk_bf16_f32 v4, v138, v139
	v_cvt_pk_bf16_f32 v5, v140, v141
	global_store_dwordx4 v[6:7], v[2:5], off
	v_lshlrev_b64 v[150:151], 12, v[160:161]
	v_ashrrev_i32_e32 v179, 31, v178
	v_cvt_pk_bf16_f32 v2, v134, v135
	v_cvt_pk_bf16_f32 v3, v136, v137
	v_cvt_pk_bf16_f32 v4, v130, v131
	v_cvt_pk_bf16_f32 v5, v132, v133
	global_store_dwordx4 v[6:7], v[2:5], off offset:256
	v_lshlrev_b64 v[160:161], 12, v[178:179]
	v_ashrrev_i32_e32 v189, 31, v188
	v_lshl_add_u64 v[2:3], s[10:11], 0, v[150:151]
	v_lshl_add_u64 v[6:7], v[2:3], 0, v[126:127]
	v_cvt_pk_bf16_f32 v2, v110, v111
	v_cvt_pk_bf16_f32 v3, v112, v113
	v_cvt_pk_bf16_f32 v4, v106, v107
	v_cvt_pk_bf16_f32 v5, v108, v109
	global_store_dwordx4 v[6:7], v[2:5], off
	v_lshlrev_b64 v[178:179], 12, v[188:189]
	v_ashrrev_i32_e32 v195, 31, v194
	v_cvt_pk_bf16_f32 v2, v102, v103
	v_cvt_pk_bf16_f32 v3, v104, v105
	v_cvt_pk_bf16_f32 v4, v98, v99
	v_cvt_pk_bf16_f32 v5, v100, v101
	global_store_dwordx4 v[6:7], v[2:5], off offset:256
	v_lshlrev_b64 v[188:189], 12, v[194:195]
	v_ashrrev_i32_e32 v197, 31, v196
	v_lshl_add_u64 v[2:3], s[10:11], 0, v[160:161]
	v_lshl_add_u64 v[6:7], v[2:3], 0, v[126:127]
	v_cvt_pk_bf16_f32 v2, v94, v95
	v_cvt_pk_bf16_f32 v3, v96, v97
	v_cvt_pk_bf16_f32 v4, v90, v91
	v_cvt_pk_bf16_f32 v5, v92, v93
	global_store_dwordx4 v[6:7], v[2:5], off
	v_lshlrev_b64 v[194:195], 12, v[196:197]
	v_ashrrev_i32_e32 v35, 31, v34
	v_cvt_pk_bf16_f32 v2, v86, v87
	v_cvt_pk_bf16_f32 v3, v88, v89
	v_cvt_pk_bf16_f32 v4, v82, v83
	v_cvt_pk_bf16_f32 v5, v84, v85
	global_store_dwordx4 v[6:7], v[2:5], off offset:256
	v_lshlrev_b64 v[196:197], 12, v[34:35]
	v_ashrrev_i32_e32 v19, 31, v18
	v_lshl_add_u64 v[2:3], s[10:11], 0, v[178:179]
	v_lshl_add_u64 v[6:7], v[2:3], 0, v[126:127]
	v_cvt_pk_bf16_f32 v2, v78, v79
	v_cvt_pk_bf16_f32 v3, v80, v81
	v_cvt_pk_bf16_f32 v4, v74, v75
	v_cvt_pk_bf16_f32 v5, v76, v77
	global_store_dwordx4 v[6:7], v[2:5], off
	v_lshlrev_b64 v[198:199], 12, v[18:19]
	v_and_b32_e32 v0, 7, v220
	v_cvt_pk_bf16_f32 v2, v70, v71
	v_cvt_pk_bf16_f32 v3, v72, v73
	v_cvt_pk_bf16_f32 v4, v66, v67
	v_cvt_pk_bf16_f32 v5, v68, v69
	global_store_dwordx4 v[6:7], v[2:5], off offset:256
	v_lshlrev_b32_e32 v0, 3, v0
	v_mov_b64_e32 v[238:239], 0x100
	v_lshl_add_u64 v[2:3], s[10:11], 0, v[188:189]
	v_lshl_add_u64 v[6:7], v[2:3], 0, v[126:127]
	v_cvt_pk_bf16_f32 v2, v62, v63
	v_cvt_pk_bf16_f32 v3, v64, v65
	v_cvt_pk_bf16_f32 v4, v58, v59
	v_cvt_pk_bf16_f32 v5, v60, v61
	global_store_dwordx4 v[6:7], v[2:5], off
	s_nop 1
	v_cvt_pk_bf16_f32 v2, v54, v55
	v_cvt_pk_bf16_f32 v3, v56, v57
	v_cvt_pk_bf16_f32 v4, v50, v51
	v_cvt_pk_bf16_f32 v5, v52, v53
	global_store_dwordx4 v[6:7], v[2:5], off offset:256
	s_nop 1
	v_lshl_add_u64 v[2:3], s[10:11], 0, v[194:195]
	v_lshl_add_u64 v[6:7], v[2:3], 0, v[126:127]
	v_cvt_pk_bf16_f32 v2, v168, v169
	v_cvt_pk_bf16_f32 v3, v166, v167
	v_cvt_pk_bf16_f32 v4, v164, v165
	v_cvt_pk_bf16_f32 v5, v162, v163
	global_store_dwordx4 v[6:7], v[2:5], off
	s_nop 1
	v_cvt_pk_bf16_f32 v2, v154, v155
	v_cvt_pk_bf16_f32 v3, v152, v153
	v_cvt_pk_bf16_f32 v4, v158, v159
	v_cvt_pk_bf16_f32 v5, v156, v157
	global_store_dwordx4 v[6:7], v[2:5], off offset:256
	s_nop 1
	v_lshl_add_u64 v[2:3], s[10:11], 0, v[196:197]
	v_lshl_add_u64 v[6:7], v[2:3], 0, v[126:127]
	v_cvt_pk_bf16_f32 v2, v186, v187
	v_cvt_pk_bf16_f32 v3, v184, v185
	v_cvt_pk_bf16_f32 v4, v182, v183
	v_cvt_pk_bf16_f32 v5, v180, v181
	global_store_dwordx4 v[6:7], v[2:5], off
	s_nop 1
	v_cvt_pk_bf16_f32 v2, v172, v173
	v_cvt_pk_bf16_f32 v3, v170, v171
	v_cvt_pk_bf16_f32 v4, v176, v177
	v_cvt_pk_bf16_f32 v5, v174, v175
	global_store_dwordx4 v[6:7], v[2:5], off offset:256
	s_nop 1
	v_lshl_add_u64 v[2:3], s[10:11], 0, v[198:199]
	s_add_u32 s10, s6, 0x8000
	v_lshl_add_u64 v[6:7], v[2:3], 0, v[126:127]
	v_cvt_pk_bf16_f32 v2, v192, v193
	v_cvt_pk_bf16_f32 v3, v190, v191
	v_cvt_pk_bf16_f32 v4, v124, v125
	v_cvt_pk_bf16_f32 v5, v122, v123
	s_addc_u32 s11, s7, 0
	global_store_dwordx4 v[6:7], v[2:5], off
	s_add_u32 s6, s6, 0x6000
	s_addc_u32 s7, s7, 0
	v_cvt_pk_bf16_f32 v2, v114, v115
	v_cvt_pk_bf16_f32 v3, v116, v117
	v_cvt_pk_bf16_f32 v4, v118, v119
	v_cvt_pk_bf16_f32 v5, v120, v121
	global_store_dwordx4 v[6:7], v[2:5], off offset:256
	s_nop 1
	v_lshl_add_u64 v[2:3], s[14:15], 0, v[148:149]
	v_lshl_add_u64 v[4:5], s[10:11], 0, v[148:149]
	global_load_dwordx4 v[18:21], v[2:3], off offset:16
	global_load_dwordx4 v[26:29], v[2:3], off
	global_load_dwordx4 v[30:33], v[4:5], off offset:16
	global_load_dwordx4 v[34:37], v[4:5], off
	v_lshl_add_u64 v[4:5], s[6:7], 0, v[148:149]
	global_load_dwordx4 v[10:13], v[4:5], off offset:16
	global_load_dwordx4 v[14:17], v[4:5], off
	v_or_b32_e32 v4, 0x80, v146
	v_ashrrev_i32_e32 v5, 31, v4
	global_load_dwordx4 v[22:25], v[2:3], off offset:528
	global_load_dwordx4 v[38:41], v[2:3], off offset:512
	v_lshlrev_b64 v[2:3], 2, v[4:5]
	v_lshl_add_u64 v[4:5], s[10:11], 0, v[2:3]
	v_lshl_add_u64 v[6:7], s[6:7], 0, v[2:3]
	global_load_dwordx4 v[42:45], v[4:5], off offset:16
	global_load_dwordx4 v[46:49], v[4:5], off
	s_nop 0
	global_load_dwordx4 v[2:5], v[6:7], off offset:16
	s_nop 0
	global_load_dwordx4 v[6:9], v[6:7], off
	s_add_i32 s6, s26, s20
	s_memrealtime s[24:25]
	s_ashr_i32 s7, s6, 31
	s_lshl_b64 s[6:7], s[6:7], 6
	s_add_u32 s6, s8, s6
	s_addc_u32 s7, s9, s7
	v_lshl_add_u64 v[146:147], s[6:7], 0, v[0:1]
	v_cmp_gt_u32_e64 s[6:7], 8, v226
	s_branch .LBB0_976

.LBB0_991:
	s_or_b64 exec, exec, s[6:7]
	s_lshl_b32 s4, s86, 2
	v_pk_add_f32 v[36:37], v[36:37], 1.0 op_sel_hi:[1,0]
	v_pk_add_f32 v[146:147], v[34:35], 1.0 op_sel_hi:[1,0]
	s_add_i32 s4, s4, 0
	v_pk_mul_f32 v[34:35], v[28:29], v[36:37]
	v_pk_mul_f32 v[36:37], v[26:27], v[146:147]
	v_pk_add_f32 v[26:27], v[32:33], 1.0 op_sel_hi:[1,0]
	v_lshl_add_u32 v0, v221, 2, s4
	v_pk_mul_f32 v[146:147], v[20:21], v[26:27]
	v_pk_add_f32 v[20:21], v[46:47], 1.0 op_sel_hi:[1,0]
	s_waitcnt lgkmcnt(0)
	s_barrier
	v_add_u32_e32 v0, 0x2000, v0
	v_pk_mul_f32 v[20:21], v[38:39], v[20:21]
	ds_read2_b32 v[38:39], v0 offset1:16
	v_pk_add_f32 v[28:29], v[30:31], 1.0 op_sel_hi:[1,0]
	v_pk_add_f32 v[26:27], v[44:45], 1.0 op_sel_hi:[1,0]
	v_pk_mul_f32 v[32:33], v[18:19], v[28:29]
	v_pk_add_f32 v[18:19], v[48:49], 1.0 op_sel_hi:[1,0]
	v_pk_add_f32 v[28:29], v[42:43], 1.0 op_sel_hi:[1,0]
	v_pk_mul_f32 v[18:19], v[40:41], v[18:19]
	s_waitcnt lgkmcnt(0)
	v_pk_mul_f32 v[40:41], v[144:145], v[38:39] op_sel_hi:[1,0]
	v_pk_mul_f32 v[42:43], v[142:143], v[38:39] op_sel_hi:[1,0]
	v_pk_fma_f32 v[40:41], v[34:35], v[40:41], v[16:17]
	v_pk_fma_f32 v[42:43], v[36:37], v[42:43], v[14:15]
	v_pk_mul_f32 v[22:23], v[22:23], v[28:29]
	v_pk_mul_f32 v[24:25], v[24:25], v[26:27]
	ds_read2_b32 v[30:31], v0 offset0:32 offset1:48
	ds_read2_b32 v[28:29], v0 offset0:128 offset1:144
	ds_read2_b32 v[26:27], v0 offset0:160 offset1:176
	v_pk_mul_f32 v[44:45], v[140:141], v[38:39] op_sel_hi:[1,0]
	v_pk_mul_f32 v[46:47], v[138:139], v[38:39] op_sel_hi:[1,0]
	v_cvt_pk_bf16_f32 v42, v42, v43
	v_cvt_pk_bf16_f32 v43, v40, v41
	v_lshl_add_u64 v[40:41], s[22:23], 0, v[128:129]
	v_pk_fma_f32 v[48:49], v[146:147], v[44:45], v[12:13]
	v_pk_fma_f32 v[44:45], v[32:33], v[46:47], v[10:11]
	v_lshl_add_u64 v[40:41], v[40:41], 0, v[126:127]
	v_mov_b32_e32 v0, v39
	v_cvt_pk_bf16_f32 v44, v44, v45
	v_cvt_pk_bf16_f32 v45, v48, v49
	global_store_dwordx4 v[40:41], v[42:45], off
	v_pk_mul_f32 v[46:47], v[108:109], v[0:1] op_sel_hi:[1,0]
	v_pk_mul_f32 v[48:49], v[106:107], v[0:1] op_sel_hi:[1,0]
	v_pk_mul_f32 v[42:43], v[112:113], v[0:1] op_sel_hi:[1,0]
	v_pk_mul_f32 v[44:45], v[110:111], v[0:1] op_sel_hi:[1,0]
	v_pk_fma_f32 v[42:43], v[34:35], v[42:43], v[16:17]
	v_pk_fma_f32 v[44:45], v[36:37], v[44:45], v[14:15]
	v_pk_fma_f32 v[106:107], v[146:147], v[46:47], v[12:13]
	v_cvt_pk_bf16_f32 v46, v44, v45
	v_cvt_pk_bf16_f32 v47, v42, v43
	v_lshl_add_u64 v[42:43], s[22:23], 0, v[150:151]
	v_pk_fma_f32 v[48:49], v[32:33], v[48:49], v[10:11]
	v_lshl_add_u64 v[44:45], v[42:43], 0, v[126:127]
	v_cvt_pk_bf16_f32 v48, v48, v49
	v_cvt_pk_bf16_f32 v49, v106, v107
	global_store_dwordx4 v[44:45], v[46:49], off
	s_waitcnt lgkmcnt(2)
	v_pk_mul_f32 v[42:43], v[96:97], v[30:31] op_sel_hi:[1,0]
	v_pk_mul_f32 v[90:91], v[90:91], v[30:31] op_sel_hi:[1,0]
	v_pk_mul_f32 v[46:47], v[94:95], v[30:31] op_sel_hi:[1,0]
	v_pk_fma_f32 v[42:43], v[34:35], v[42:43], v[16:17]
	v_pk_fma_f32 v[46:47], v[36:37], v[46:47], v[14:15]
	v_pk_mul_f32 v[48:49], v[92:93], v[30:31] op_sel_hi:[1,0]
	v_cvt_pk_bf16_f32 v46, v46, v47
	v_cvt_pk_bf16_f32 v47, v42, v43
	v_lshl_add_u64 v[42:43], s[22:23], 0, v[160:161]
	v_pk_fma_f32 v[92:93], v[146:147], v[48:49], v[12:13]
	v_pk_fma_f32 v[48:49], v[32:33], v[90:91], v[10:11]
	v_lshl_add_u64 v[90:91], v[42:43], 0, v[126:127]
	v_cvt_pk_bf16_f32 v48, v48, v49
	v_cvt_pk_bf16_f32 v49, v92, v93
	v_mov_b32_e32 v42, v31
	global_store_dwordx4 v[90:91], v[46:49], off
	v_pk_mul_f32 v[74:75], v[74:75], v[42:43] op_sel_hi:[1,0]
	s_waitcnt lgkmcnt(1)
	v_pk_mul_f32 v[58:59], v[58:59], v[28:29] op_sel_hi:[1,0]
	v_pk_mul_f32 v[46:47], v[80:81], v[42:43] op_sel_hi:[1,0]
	v_pk_mul_f32 v[48:49], v[78:79], v[42:43] op_sel_hi:[1,0]
	v_pk_fma_f32 v[78:79], v[34:35], v[46:47], v[16:17]
	v_pk_fma_f32 v[46:47], v[36:37], v[48:49], v[14:15]
	v_pk_mul_f32 v[48:49], v[76:77], v[42:43] op_sel_hi:[1,0]
	v_cvt_pk_bf16_f32 v46, v46, v47
	v_cvt_pk_bf16_f32 v47, v78, v79
	s_mov_b64 s[4:5], 0x100
	v_pk_fma_f32 v[76:77], v[146:147], v[48:49], v[12:13]
	v_pk_fma_f32 v[48:49], v[32:33], v[74:75], v[10:11]
	v_lshl_add_u64 v[74:75], s[22:23], 0, v[178:179]
	v_cvt_pk_bf16_f32 v48, v48, v49
	v_cvt_pk_bf16_f32 v49, v76, v77
	v_lshl_add_u64 v[74:75], v[74:75], 0, v[126:127]
	global_store_dwordx4 v[74:75], v[46:49], off
	s_mov_b64 s[16:17], -1
	s_nop 0
	v_pk_mul_f32 v[46:47], v[64:65], v[28:29] op_sel_hi:[1,0]
	v_pk_mul_f32 v[48:49], v[62:63], v[28:29] op_sel_hi:[1,0]
	v_pk_fma_f32 v[62:63], v[34:35], v[46:47], v[16:17]
	v_pk_fma_f32 v[46:47], v[36:37], v[48:49], v[14:15]
	v_pk_mul_f32 v[48:49], v[60:61], v[28:29] op_sel_hi:[1,0]
	v_cvt_pk_bf16_f32 v46, v46, v47
	v_cvt_pk_bf16_f32 v47, v62, v63
	s_nop 0
	v_pk_fma_f32 v[60:61], v[146:147], v[48:49], v[12:13]
	v_pk_fma_f32 v[48:49], v[32:33], v[58:59], v[10:11]
	v_lshl_add_u64 v[58:59], s[22:23], 0, v[188:189]
	v_cvt_pk_bf16_f32 v48, v48, v49
	v_cvt_pk_bf16_f32 v49, v60, v61
	v_lshl_add_u64 v[58:59], v[58:59], 0, v[126:127]
	v_mov_b32_e32 v60, v29
	global_store_dwordx4 v[58:59], v[46:49], off
	v_pk_mul_f32 v[64:65], v[164:165], v[60:61] op_sel_hi:[1,0]
	s_nop 0
	v_pk_mul_f32 v[46:47], v[166:167], v[60:61] op_sel_hi:[1,0]
	v_pk_mul_f32 v[48:49], v[168:169], v[60:61] op_sel_hi:[1,0]
	v_pk_fma_f32 v[62:63], v[34:35], v[46:47], v[16:17]
	v_pk_fma_f32 v[46:47], v[36:37], v[48:49], v[14:15]
	v_pk_mul_f32 v[48:49], v[162:163], v[60:61] op_sel_hi:[1,0]
	v_cvt_pk_bf16_f32 v46, v46, v47
	v_cvt_pk_bf16_f32 v47, v62, v63
	v_lshl_add_u64 v[62:63], s[22:23], 0, v[194:195]
	v_pk_fma_f32 v[76:77], v[146:147], v[48:49], v[12:13]
	v_pk_fma_f32 v[48:49], v[32:33], v[64:65], v[10:11]
	v_lshl_add_u64 v[62:63], v[62:63], 0, v[126:127]
	v_cvt_pk_bf16_f32 v48, v48, v49
	v_cvt_pk_bf16_f32 v49, v76, v77
	global_store_dwordx4 v[62:63], v[46:49], off
	s_waitcnt lgkmcnt(0)
	v_pk_mul_f32 v[76:77], v[182:183], v[26:27] op_sel_hi:[1,0]
	v_pk_mul_f32 v[46:47], v[184:185], v[26:27] op_sel_hi:[1,0]
	v_pk_mul_f32 v[48:49], v[186:187], v[26:27] op_sel_hi:[1,0]
	v_pk_fma_f32 v[64:65], v[34:35], v[46:47], v[16:17]
	v_pk_fma_f32 v[46:47], v[36:37], v[48:49], v[14:15]
	v_pk_mul_f32 v[48:49], v[180:181], v[26:27] op_sel_hi:[1,0]
	v_cvt_pk_bf16_f32 v46, v46, v47
	v_cvt_pk_bf16_f32 v47, v64, v65
	v_lshl_add_u64 v[64:65], s[22:23], 0, v[196:197]
	v_pk_fma_f32 v[78:79], v[146:147], v[48:49], v[12:13]
	v_pk_fma_f32 v[48:49], v[32:33], v[76:77], v[10:11]
	v_lshl_add_u64 v[64:65], v[64:65], 0, v[126:127]
	v_cvt_pk_bf16_f32 v48, v48, v49
	v_cvt_pk_bf16_f32 v49, v78, v79
	global_store_dwordx4 v[64:65], v[46:49], off
	s_nop 1
	v_mov_b32_e32 v46, v27
	v_pk_mul_f32 v[48:49], v[190:191], v[46:47] op_sel_hi:[1,0]
	v_pk_mul_f32 v[76:77], v[192:193], v[46:47] op_sel_hi:[1,0]
	v_pk_fma_f32 v[16:17], v[34:35], v[48:49], v[16:17]
	v_pk_fma_f32 v[14:15], v[36:37], v[76:77], v[14:15]
	v_pk_mul_f32 v[34:35], v[122:123], v[46:47] op_sel_hi:[1,0]
	v_pk_mul_f32 v[36:37], v[124:125], v[46:47] op_sel_hi:[1,0]
	v_pk_fma_f32 v[34:35], v[146:147], v[34:35], v[12:13]
	v_pk_fma_f32 v[12:13], v[32:33], v[36:37], v[10:11]
	v_cvt_pk_bf16_f32 v10, v14, v15
	v_lshl_add_u64 v[14:15], s[22:23], 0, v[198:199]
	v_cvt_pk_bf16_f32 v11, v16, v17
	v_cvt_pk_bf16_f32 v12, v12, v13
	v_cvt_pk_bf16_f32 v13, v34, v35
	v_lshl_add_u64 v[14:15], v[14:15], 0, v[126:127]
	global_store_dwordx4 v[14:15], v[10:13], off
	v_pk_mul_f32 v[32:33], v[130:131], v[38:39] op_sel_hi:[1,0]
	s_nop 0
	v_pk_mul_f32 v[10:11], v[136:137], v[38:39] op_sel_hi:[1,0]
	v_pk_mul_f32 v[12:13], v[134:135], v[38:39] op_sel_hi:[1,0]
	v_pk_fma_f32 v[16:17], v[18:19], v[10:11], v[8:9]
	v_pk_fma_f32 v[10:11], v[20:21], v[12:13], v[6:7]
	v_pk_mul_f32 v[12:13], v[132:133], v[38:39] op_sel_hi:[1,0]
	v_cvt_pk_bf16_f32 v10, v10, v11
	v_cvt_pk_bf16_f32 v11, v16, v17
	s_nop 0
	v_pk_fma_f32 v[34:35], v[24:25], v[12:13], v[4:5]
	v_pk_fma_f32 v[12:13], v[22:23], v[32:33], v[2:3]
	v_pk_mul_f32 v[32:33], v[98:99], v[0:1] op_sel_hi:[1,0]
	v_cvt_pk_bf16_f32 v12, v12, v13
	v_cvt_pk_bf16_f32 v13, v34, v35
	global_store_dwordx4 v[40:41], v[10:13], off offset:256
	s_nop 1
	v_pk_mul_f32 v[10:11], v[104:105], v[0:1] op_sel_hi:[1,0]
	v_pk_mul_f32 v[12:13], v[102:103], v[0:1] op_sel_hi:[1,0]
	v_pk_fma_f32 v[16:17], v[18:19], v[10:11], v[8:9]
	v_pk_fma_f32 v[10:11], v[20:21], v[12:13], v[6:7]
	v_pk_mul_f32 v[12:13], v[100:101], v[0:1] op_sel_hi:[1,0]
	v_cvt_pk_bf16_f32 v10, v10, v11
	v_cvt_pk_bf16_f32 v11, v16, v17
	s_nop 0
	v_pk_fma_f32 v[34:35], v[24:25], v[12:13], v[4:5]
	v_pk_fma_f32 v[12:13], v[22:23], v[32:33], v[2:3]
	s_nop 0
	v_cvt_pk_bf16_f32 v12, v12, v13
	v_cvt_pk_bf16_f32 v13, v34, v35
	global_store_dwordx4 v[44:45], v[10:13], off offset:256
	s_nop 1
	v_pk_mul_f32 v[10:11], v[88:89], v[30:31] op_sel_hi:[1,0]
	v_pk_mul_f32 v[12:13], v[86:87], v[30:31] op_sel_hi:[1,0]
	v_pk_fma_f32 v[16:17], v[18:19], v[10:11], v[8:9]
	v_pk_fma_f32 v[10:11], v[20:21], v[12:13], v[6:7]
	v_pk_mul_f32 v[12:13], v[84:85], v[30:31] op_sel_hi:[1,0]
	v_pk_mul_f32 v[30:31], v[82:83], v[30:31] op_sel_hi:[1,0]
	v_pk_fma_f32 v[32:33], v[24:25], v[12:13], v[4:5]
	v_pk_fma_f32 v[12:13], v[22:23], v[30:31], v[2:3]
	v_cvt_pk_bf16_f32 v10, v10, v11
	v_cvt_pk_bf16_f32 v11, v16, v17
	v_pk_mul_f32 v[30:31], v[66:67], v[42:43] op_sel_hi:[1,0]
	v_cvt_pk_bf16_f32 v12, v12, v13
	v_cvt_pk_bf16_f32 v13, v32, v33
	global_store_dwordx4 v[90:91], v[10:13], off offset:256
	s_nop 1
	v_pk_mul_f32 v[10:11], v[72:73], v[42:43] op_sel_hi:[1,0]
	v_pk_mul_f32 v[12:13], v[70:71], v[42:43] op_sel_hi:[1,0]
	v_pk_fma_f32 v[16:17], v[18:19], v[10:11], v[8:9]
	v_pk_fma_f32 v[10:11], v[20:21], v[12:13], v[6:7]
	v_pk_mul_f32 v[12:13], v[68:69], v[42:43] op_sel_hi:[1,0]
	v_cvt_pk_bf16_f32 v10, v10, v11
	v_cvt_pk_bf16_f32 v11, v16, v17
	s_nop 0
	v_pk_fma_f32 v[32:33], v[24:25], v[12:13], v[4:5]
	v_pk_fma_f32 v[12:13], v[22:23], v[30:31], v[2:3]
	s_nop 0
	v_cvt_pk_bf16_f32 v12, v12, v13
	v_cvt_pk_bf16_f32 v13, v32, v33
	global_store_dwordx4 v[74:75], v[10:13], off offset:256
	s_nop 1
	v_pk_mul_f32 v[10:11], v[56:57], v[28:29] op_sel_hi:[1,0]
	v_pk_mul_f32 v[12:13], v[54:55], v[28:29] op_sel_hi:[1,0]
	v_pk_fma_f32 v[16:17], v[18:19], v[10:11], v[8:9]
	v_pk_fma_f32 v[10:11], v[20:21], v[12:13], v[6:7]
	v_pk_mul_f32 v[12:13], v[52:53], v[28:29] op_sel_hi:[1,0]
	v_pk_mul_f32 v[28:29], v[50:51], v[28:29] op_sel_hi:[1,0]
	v_pk_fma_f32 v[30:31], v[24:25], v[12:13], v[4:5]
	v_pk_fma_f32 v[12:13], v[22:23], v[28:29], v[2:3]
	v_cvt_pk_bf16_f32 v10, v10, v11
	v_cvt_pk_bf16_f32 v11, v16, v17
	v_pk_mul_f32 v[28:29], v[158:159], v[60:61] op_sel_hi:[1,0]
	v_cvt_pk_bf16_f32 v12, v12, v13
	v_cvt_pk_bf16_f32 v13, v30, v31
	global_store_dwordx4 v[58:59], v[10:13], off offset:256
	s_nop 1
	v_pk_mul_f32 v[10:11], v[152:153], v[60:61] op_sel_hi:[1,0]
	v_pk_mul_f32 v[12:13], v[154:155], v[60:61] op_sel_hi:[1,0]
	v_pk_fma_f32 v[16:17], v[18:19], v[10:11], v[8:9]
	v_pk_fma_f32 v[10:11], v[20:21], v[12:13], v[6:7]
	v_pk_mul_f32 v[12:13], v[156:157], v[60:61] op_sel_hi:[1,0]
	v_cvt_pk_bf16_f32 v10, v10, v11
	v_cvt_pk_bf16_f32 v11, v16, v17
	s_nop 0
	v_pk_fma_f32 v[30:31], v[24:25], v[12:13], v[4:5]
	v_pk_fma_f32 v[12:13], v[22:23], v[28:29], v[2:3]
	s_nop 0
	v_cvt_pk_bf16_f32 v12, v12, v13
	v_cvt_pk_bf16_f32 v13, v30, v31
	global_store_dwordx4 v[62:63], v[10:13], off offset:256
	s_nop 1
	v_pk_mul_f32 v[10:11], v[170:171], v[26:27] op_sel_hi:[1,0]
	v_pk_mul_f32 v[12:13], v[172:173], v[26:27] op_sel_hi:[1,0]
	v_pk_fma_f32 v[16:17], v[18:19], v[10:11], v[8:9]
	v_pk_fma_f32 v[10:11], v[20:21], v[12:13], v[6:7]
	v_pk_mul_f32 v[12:13], v[174:175], v[26:27] op_sel_hi:[1,0]
	v_pk_mul_f32 v[26:27], v[176:177], v[26:27] op_sel_hi:[1,0]
	v_pk_fma_f32 v[28:29], v[24:25], v[12:13], v[4:5]
	v_pk_fma_f32 v[12:13], v[22:23], v[26:27], v[2:3]
	v_cvt_pk_bf16_f32 v10, v10, v11
	v_cvt_pk_bf16_f32 v11, v16, v17
	s_nop 0
	v_cvt_pk_bf16_f32 v12, v12, v13
	v_cvt_pk_bf16_f32 v13, v28, v29
	global_store_dwordx4 v[64:65], v[10:13], off offset:256
	s_nop 1
	v_pk_mul_f32 v[10:11], v[116:117], v[46:47] op_sel_hi:[1,0]
	v_pk_mul_f32 v[12:13], v[114:115], v[46:47] op_sel_hi:[1,0]
	v_pk_fma_f32 v[8:9], v[18:19], v[10:11], v[8:9]
	v_pk_fma_f32 v[6:7], v[20:21], v[12:13], v[6:7]
	v_pk_mul_f32 v[10:11], v[120:121], v[46:47] op_sel_hi:[1,0]
	v_pk_mul_f32 v[12:13], v[118:119], v[46:47] op_sel_hi:[1,0]
	v_pk_fma_f32 v[10:11], v[24:25], v[10:11], v[4:5]
	v_pk_fma_f32 v[4:5], v[22:23], v[12:13], v[2:3]
	v_cvt_pk_bf16_f32 v2, v6, v7
	v_cvt_pk_bf16_f32 v3, v8, v9
	v_lshl_add_u64 v[6:7], v[14:15], 0, s[4:5]
	v_cvt_pk_bf16_f32 v4, v4, v5
	v_cvt_pk_bf16_f32 v5, v10, v11
.LBB0_992:
	s_and_b64 vcc, exec, s[16:17]
	s_cbranch_vccz .LBB0_994
	global_store_dwordx4 v[6:7], v[2:5], off

.LBB0_1063:
	v_mul_f32_e32 v144, 0xbfb8aa3b, v126
	v_exp_f32_e32 v144, v144
	v_lshl_or_b32 v142, s25, 7, v139
	v_lshl_add_u32 v141, s24, 8, v137
	v_ashrrev_i32_e32 v143, 31, v142
	v_add_f32_e32 v144, 1.0, v144
	v_rcp_f32_e32 v144, v144
	s_andn2_b64 vcc, exec, s[4:5]
	v_mul_f32_e32 v126, v126, v144
	v_mul_f32_e32 v122, v126, v122
	v_mul_f32_e32 v126, 0xbfb8aa3b, v127
	v_exp_f32_e32 v126, v126
	s_nop 0
	v_add_f32_e32 v126, 1.0, v126
	v_rcp_f32_e32 v126, v126
	s_nop 0
	v_mul_f32_e32 v126, v127, v126
	v_mul_f32_e32 v123, v126, v123
	v_mul_f32_e32 v126, 0xbfb8aa3b, v128
	v_exp_f32_e32 v126, v126
	s_nop 0
	v_add_f32_e32 v126, 1.0, v126
	v_rcp_f32_e32 v126, v126
	s_nop 0
	v_mul_f32_e32 v126, v128, v126
	v_mul_f32_e32 v124, v126, v124
	v_mul_f32_e32 v126, 0xbfb8aa3b, v129
	v_exp_f32_e32 v126, v126
	s_nop 0
	v_add_f32_e32 v126, 1.0, v126
	v_rcp_f32_e32 v126, v126
	s_nop 0
	v_mul_f32_e32 v126, v129, v126
	v_mul_f32_e32 v125, v126, v125
	v_mul_f32_e32 v126, 0xbfb8aa3b, v118
	v_exp_f32_e32 v126, v126
	s_nop 0
	v_add_f32_e32 v126, 1.0, v126
	v_rcp_f32_e32 v126, v126
	s_nop 0
	v_mul_f32_e32 v118, v118, v126
	v_mul_f32_e32 v114, v118, v114
	v_mul_f32_e32 v118, 0xbfb8aa3b, v119
	v_exp_f32_e32 v118, v118
	s_nop 0
	v_add_f32_e32 v118, 1.0, v118
	v_rcp_f32_e32 v118, v118
	s_nop 0
	v_mul_f32_e32 v118, v119, v118
	v_mul_f32_e32 v115, v118, v115
	v_mul_f32_e32 v118, 0xbfb8aa3b, v120
	v_exp_f32_e32 v118, v118
	s_nop 0
	v_add_f32_e32 v118, 1.0, v118
	v_rcp_f32_e32 v118, v118
	s_nop 0
	v_mul_f32_e32 v118, v120, v118
	v_mul_f32_e32 v116, v118, v116
	v_mul_f32_e32 v118, 0xbfb8aa3b, v121
	v_exp_f32_e32 v118, v118
	s_nop 0
	v_add_f32_e32 v118, 1.0, v118
	v_rcp_f32_e32 v118, v118
	s_nop 0
	v_mul_f32_e32 v118, v121, v118
	v_mul_f32_e32 v117, v118, v117
	v_cvt_pk_bf16_f32 v118, v122, v123
	v_cvt_pk_bf16_f32 v119, v124, v125
	v_cvt_pk_bf16_f32 v120, v114, v115
	v_mov_b64_e32 v[114:115], s[10:11]
	v_cvt_pk_bf16_f32 v121, v116, v117
	v_mad_i64_i32 v[122:123], s[24:25], v141, s53, v[114:115]
	v_lshlrev_b64 v[116:117], 1, v[142:143]
	v_lshl_add_u64 v[122:123], v[122:123], 0, v[116:117]
	global_store_dwordx4 v[122:123], v[118:121], off
	s_nop 1
	v_mul_f32_e32 v118, 0xbfb8aa3b, v110
	v_exp_f32_e32 v118, v118
	s_nop 0
	v_add_f32_e32 v118, 1.0, v118
	v_rcp_f32_e32 v118, v118
	s_nop 0
	v_mul_f32_e32 v110, v110, v118
	v_mul_f32_e32 v106, v110, v106
	v_mul_f32_e32 v110, 0xbfb8aa3b, v111
	v_exp_f32_e32 v110, v110
	s_nop 0
	v_add_f32_e32 v110, 1.0, v110
	v_rcp_f32_e32 v110, v110
	s_nop 0
	v_mul_f32_e32 v110, v111, v110
	v_mul_f32_e32 v107, v110, v107
	v_mul_f32_e32 v110, 0xbfb8aa3b, v112
	v_exp_f32_e32 v110, v110
	s_nop 0
	v_add_f32_e32 v110, 1.0, v110
	v_rcp_f32_e32 v110, v110
	s_nop 0
	v_mul_f32_e32 v110, v112, v110
	v_mul_f32_e32 v108, v110, v108
	v_mul_f32_e32 v110, 0xbfb8aa3b, v113
	v_exp_f32_e32 v110, v110
	s_nop 0
	v_add_f32_e32 v110, 1.0, v110
	v_rcp_f32_e32 v110, v110
	s_nop 0
	v_mul_f32_e32 v110, v113, v110
	v_mul_f32_e32 v109, v110, v109
	v_mul_f32_e32 v110, 0xbfb8aa3b, v102
	v_exp_f32_e32 v110, v110
	s_nop 0
	v_add_f32_e32 v110, 1.0, v110
	v_rcp_f32_e32 v110, v110
	s_nop 0
	v_mul_f32_e32 v102, v102, v110
	v_mul_f32_e32 v102, v102, v98
	v_mul_f32_e32 v98, 0xbfb8aa3b, v103
	v_exp_f32_e32 v98, v98
	s_nop 0
	v_add_f32_e32 v98, 1.0, v98
	v_rcp_f32_e32 v98, v98
	s_nop 0
	v_mul_f32_e32 v98, v103, v98
	v_mul_f32_e32 v103, v98, v99
	v_mul_f32_e32 v98, 0xbfb8aa3b, v104
	v_exp_f32_e32 v98, v98
	s_nop 0
	v_add_f32_e32 v98, 1.0, v98
	v_rcp_f32_e32 v98, v98
	s_nop 0
	v_mul_f32_e32 v98, v104, v98
	v_mul_f32_e32 v104, v98, v100
	v_mul_f32_e32 v98, 0xbfb8aa3b, v105
	v_exp_f32_e32 v98, v98
	s_nop 0
	v_add_f32_e32 v98, 1.0, v98
	v_rcp_f32_e32 v98, v98
	s_nop 0
	v_mul_f32_e32 v98, v105, v98
	v_or_b32_e32 v105, 16, v141
	v_mul_f32_e32 v101, v98, v101
	v_cvt_pk_bf16_f32 v98, v106, v107
	v_cvt_pk_bf16_f32 v99, v108, v109
	v_cvt_pk_bf16_f32 v100, v102, v103
	v_mad_i64_i32 v[102:103], s[24:25], v105, s53, v[114:115]
	v_lshl_add_u64 v[102:103], v[102:103], 0, v[116:117]
	v_cvt_pk_bf16_f32 v101, v104, v101
	global_store_dwordx4 v[102:103], v[98:101], off
	s_nop 1
	v_mul_f32_e32 v98, 0xbfb8aa3b, v94
	v_exp_f32_e32 v98, v98
	s_nop 0
	v_add_f32_e32 v98, 1.0, v98
	v_rcp_f32_e32 v98, v98
	s_nop 0
	v_mul_f32_e32 v94, v94, v98
	v_mul_f32_e32 v90, v94, v90
	v_mul_f32_e32 v94, 0xbfb8aa3b, v95
	v_exp_f32_e32 v94, v94
	s_nop 0
	v_add_f32_e32 v94, 1.0, v94
	v_rcp_f32_e32 v94, v94
	s_nop 0
	v_mul_f32_e32 v94, v95, v94
	v_mul_f32_e32 v91, v94, v91
	v_mul_f32_e32 v94, 0xbfb8aa3b, v96
	v_exp_f32_e32 v94, v94
	s_nop 0
	v_add_f32_e32 v94, 1.0, v94
	v_rcp_f32_e32 v94, v94
	s_nop 0
	v_mul_f32_e32 v94, v96, v94
	v_mul_f32_e32 v92, v94, v92
	v_mul_f32_e32 v94, 0xbfb8aa3b, v97
	v_exp_f32_e32 v94, v94
	s_nop 0
	v_add_f32_e32 v94, 1.0, v94
	v_rcp_f32_e32 v94, v94
	s_nop 0
	v_mul_f32_e32 v94, v97, v94
	v_mul_f32_e32 v93, v94, v93
	v_mul_f32_e32 v94, 0xbfb8aa3b, v86
	v_exp_f32_e32 v94, v94
	s_nop 0
	v_add_f32_e32 v94, 1.0, v94
	v_rcp_f32_e32 v94, v94
	s_nop 0
	v_mul_f32_e32 v86, v86, v94
	v_mul_f32_e32 v86, v86, v82
	v_mul_f32_e32 v82, 0xbfb8aa3b, v87
	v_exp_f32_e32 v82, v82
	s_nop 0
	v_add_f32_e32 v82, 1.0, v82
	v_rcp_f32_e32 v82, v82
	s_nop 0
	v_mul_f32_e32 v82, v87, v82
	v_mul_f32_e32 v87, v82, v83
	v_mul_f32_e32 v82, 0xbfb8aa3b, v88
	v_exp_f32_e32 v82, v82
	s_nop 0
	v_add_f32_e32 v82, 1.0, v82
	v_rcp_f32_e32 v82, v82
	s_nop 0
	v_mul_f32_e32 v82, v88, v82
	v_mul_f32_e32 v88, v82, v84
	v_mul_f32_e32 v82, 0xbfb8aa3b, v89
	v_exp_f32_e32 v82, v82
	s_nop 0
	v_add_f32_e32 v82, 1.0, v82
	v_rcp_f32_e32 v82, v82
	s_nop 0
	v_mul_f32_e32 v82, v89, v82
	v_or_b32_e32 v89, 32, v141
	v_mul_f32_e32 v85, v82, v85
	v_cvt_pk_bf16_f32 v82, v90, v91
	v_cvt_pk_bf16_f32 v83, v92, v93
	v_cvt_pk_bf16_f32 v84, v86, v87
	v_mad_i64_i32 v[86:87], s[24:25], v89, s53, v[114:115]
	v_lshl_add_u64 v[86:87], v[86:87], 0, v[116:117]
	v_cvt_pk_bf16_f32 v85, v88, v85
	global_store_dwordx4 v[86:87], v[82:85], off
	s_nop 1
	v_mul_f32_e32 v82, 0xbfb8aa3b, v78
	v_exp_f32_e32 v82, v82
	s_nop 0
	v_add_f32_e32 v82, 1.0, v82
	v_rcp_f32_e32 v82, v82
	s_nop 0
	v_mul_f32_e32 v78, v78, v82
	v_mul_f32_e32 v74, v78, v74
	v_mul_f32_e32 v78, 0xbfb8aa3b, v79
	v_exp_f32_e32 v78, v78
	s_nop 0
	v_add_f32_e32 v78, 1.0, v78
	v_rcp_f32_e32 v78, v78
	s_nop 0
	v_mul_f32_e32 v78, v79, v78
	v_mul_f32_e32 v75, v78, v75
	v_mul_f32_e32 v78, 0xbfb8aa3b, v80
	v_exp_f32_e32 v78, v78
	s_nop 0
	v_add_f32_e32 v78, 1.0, v78
	v_rcp_f32_e32 v78, v78
	s_nop 0
	v_mul_f32_e32 v78, v80, v78
	v_mul_f32_e32 v76, v78, v76
	v_mul_f32_e32 v78, 0xbfb8aa3b, v81
	v_exp_f32_e32 v78, v78
	s_nop 0
	v_add_f32_e32 v78, 1.0, v78
	v_rcp_f32_e32 v78, v78
	s_nop 0
	v_mul_f32_e32 v78, v81, v78
	v_mul_f32_e32 v77, v78, v77
	v_mul_f32_e32 v78, 0xbfb8aa3b, v70
	v_exp_f32_e32 v78, v78
	s_nop 0
	v_add_f32_e32 v78, 1.0, v78
	v_rcp_f32_e32 v78, v78
	s_nop 0
	v_mul_f32_e32 v70, v70, v78
	v_mul_f32_e32 v70, v70, v66
	v_mul_f32_e32 v66, 0xbfb8aa3b, v71
	v_exp_f32_e32 v66, v66
	s_nop 0
	v_add_f32_e32 v66, 1.0, v66
	v_rcp_f32_e32 v66, v66
	s_nop 0
	v_mul_f32_e32 v66, v71, v66
	v_mul_f32_e32 v71, v66, v67
	v_mul_f32_e32 v66, 0xbfb8aa3b, v72
	v_exp_f32_e32 v66, v66
	s_nop 0
	v_add_f32_e32 v66, 1.0, v66
	v_rcp_f32_e32 v66, v66
	s_nop 0
	v_mul_f32_e32 v66, v72, v66
	v_mul_f32_e32 v72, v66, v68
	v_mul_f32_e32 v66, 0xbfb8aa3b, v73
	v_exp_f32_e32 v66, v66
	s_nop 0
	v_add_f32_e32 v66, 1.0, v66
	v_rcp_f32_e32 v66, v66
	s_nop 0
	v_mul_f32_e32 v66, v73, v66
	v_or_b32_e32 v73, 48, v141
	v_mul_f32_e32 v69, v66, v69
	v_cvt_pk_bf16_f32 v66, v74, v75
	v_cvt_pk_bf16_f32 v67, v76, v77
	v_cvt_pk_bf16_f32 v68, v70, v71
	v_mad_i64_i32 v[70:71], s[24:25], v73, s53, v[114:115]
	v_lshl_add_u64 v[70:71], v[70:71], 0, v[116:117]
	v_cvt_pk_bf16_f32 v69, v72, v69
	global_store_dwordx4 v[70:71], v[66:69], off
	s_nop 1
	v_mul_f32_e32 v67, 0xbfb8aa3b, v62
	v_exp_f32_e32 v67, v67
	v_add_u32_e32 v66, 0x80, v141
	v_add_f32_e32 v67, 1.0, v67
	v_rcp_f32_e32 v67, v67
	s_nop 0
	v_mul_f32_e32 v62, v62, v67
	v_mul_f32_e32 v58, v62, v58
	v_mul_f32_e32 v62, 0xbfb8aa3b, v63
	v_exp_f32_e32 v62, v62
	s_nop 0
	v_add_f32_e32 v62, 1.0, v62
	v_rcp_f32_e32 v62, v62
	s_nop 0
	v_mul_f32_e32 v62, v63, v62
	v_mul_f32_e32 v59, v62, v59
	v_mul_f32_e32 v62, 0xbfb8aa3b, v64
	v_exp_f32_e32 v62, v62
	s_nop 0
	v_add_f32_e32 v62, 1.0, v62
	v_rcp_f32_e32 v62, v62
	s_nop 0
	v_mul_f32_e32 v62, v64, v62
	v_mul_f32_e32 v60, v62, v60
	v_mul_f32_e32 v62, 0xbfb8aa3b, v65
	v_exp_f32_e32 v62, v62
	s_nop 0
	v_add_f32_e32 v62, 1.0, v62
	v_rcp_f32_e32 v62, v62
	s_nop 0
	v_mul_f32_e32 v62, v65, v62
	v_mul_f32_e32 v61, v62, v61
	v_mul_f32_e32 v62, 0xbfb8aa3b, v54
	v_exp_f32_e32 v62, v62
	s_nop 0
	v_add_f32_e32 v62, 1.0, v62
	v_rcp_f32_e32 v62, v62
	s_nop 0
	v_mul_f32_e32 v54, v54, v62
	v_mul_f32_e32 v54, v54, v50
	v_mul_f32_e32 v50, 0xbfb8aa3b, v55
	v_exp_f32_e32 v50, v50
	s_nop 0
	v_add_f32_e32 v50, 1.0, v50
	v_rcp_f32_e32 v50, v50
	s_nop 0
	v_mul_f32_e32 v50, v55, v50
	v_mul_f32_e32 v55, v50, v51
	v_mul_f32_e32 v50, 0xbfb8aa3b, v56
	v_exp_f32_e32 v50, v50
	s_nop 0
	v_add_f32_e32 v50, 1.0, v50
	v_rcp_f32_e32 v50, v50
	s_nop 0
	v_mul_f32_e32 v50, v56, v50
	v_mul_f32_e32 v56, v50, v52
	v_mul_f32_e32 v50, 0xbfb8aa3b, v57
	v_exp_f32_e32 v50, v50
	s_nop 0
	v_add_f32_e32 v50, 1.0, v50
	v_rcp_f32_e32 v50, v50
	s_nop 0
	v_mul_f32_e32 v50, v57, v50
	v_mul_f32_e32 v53, v50, v53
	v_cvt_pk_bf16_f32 v50, v58, v59
	v_cvt_pk_bf16_f32 v51, v60, v61
	v_cvt_pk_bf16_f32 v52, v54, v55
	v_mad_i64_i32 v[54:55], s[24:25], v66, s53, v[114:115]
	v_lshl_add_u64 v[54:55], v[54:55], 0, v[116:117]
	v_cvt_pk_bf16_f32 v53, v56, v53
	global_store_dwordx4 v[54:55], v[50:53], off
	s_nop 1
	v_mul_f32_e32 v50, 0xbfb8aa3b, v46
	v_exp_f32_e32 v50, v50
	s_nop 0
	v_add_f32_e32 v50, 1.0, v50
	v_rcp_f32_e32 v50, v50
	s_nop 0
	v_mul_f32_e32 v46, v46, v50
	v_mul_f32_e32 v42, v46, v42
	v_mul_f32_e32 v46, 0xbfb8aa3b, v47
	v_exp_f32_e32 v46, v46
	s_nop 0
	v_add_f32_e32 v46, 1.0, v46
	v_rcp_f32_e32 v46, v46
	s_nop 0
	v_mul_f32_e32 v46, v47, v46
	v_mul_f32_e32 v43, v46, v43
	v_mul_f32_e32 v46, 0xbfb8aa3b, v48
	v_exp_f32_e32 v46, v46
	s_nop 0
	v_add_f32_e32 v46, 1.0, v46
	v_rcp_f32_e32 v46, v46
	s_nop 0
	v_mul_f32_e32 v46, v48, v46
	v_mul_f32_e32 v44, v46, v44
	v_mul_f32_e32 v46, 0xbfb8aa3b, v49
	v_exp_f32_e32 v46, v46
	s_nop 0
	v_add_f32_e32 v46, 1.0, v46
	v_rcp_f32_e32 v46, v46
	s_nop 0
	v_mul_f32_e32 v46, v49, v46
	v_mul_f32_e32 v45, v46, v45
	v_mul_f32_e32 v46, 0xbfb8aa3b, v38
	v_exp_f32_e32 v46, v46
	s_nop 0
	v_add_f32_e32 v46, 1.0, v46
	v_rcp_f32_e32 v46, v46
	s_nop 0
	v_mul_f32_e32 v38, v38, v46
	v_mul_f32_e32 v38, v38, v34
	v_mul_f32_e32 v34, 0xbfb8aa3b, v39
	v_exp_f32_e32 v34, v34
	s_nop 0
	v_add_f32_e32 v34, 1.0, v34
	v_rcp_f32_e32 v34, v34
	s_nop 0
	v_mul_f32_e32 v34, v39, v34
	v_mul_f32_e32 v39, v34, v35
	v_mul_f32_e32 v34, 0xbfb8aa3b, v40
	v_exp_f32_e32 v34, v34
	s_nop 0
	v_add_f32_e32 v34, 1.0, v34
	v_rcp_f32_e32 v34, v34
	s_nop 0
	v_mul_f32_e32 v34, v40, v34
	v_mul_f32_e32 v40, v34, v36
	v_mul_f32_e32 v34, 0xbfb8aa3b, v41
	v_exp_f32_e32 v34, v34
	s_nop 0
	v_add_f32_e32 v34, 1.0, v34
	v_rcp_f32_e32 v34, v34
	s_nop 0
	v_mul_f32_e32 v34, v41, v34
	v_add_u32_e32 v41, 0x90, v141
	v_mul_f32_e32 v37, v34, v37
	v_cvt_pk_bf16_f32 v34, v42, v43
	v_cvt_pk_bf16_f32 v35, v44, v45
	v_cvt_pk_bf16_f32 v36, v38, v39
	v_mad_i64_i32 v[38:39], s[24:25], v41, s53, v[114:115]
	v_lshl_add_u64 v[38:39], v[38:39], 0, v[116:117]
	v_cvt_pk_bf16_f32 v37, v40, v37
	global_store_dwordx4 v[38:39], v[34:37], off
	s_nop 1
	v_mul_f32_e32 v34, 0xbfb8aa3b, v30
	v_exp_f32_e32 v34, v34
	s_nop 0
	v_add_f32_e32 v34, 1.0, v34
	v_rcp_f32_e32 v34, v34
	s_nop 0
	v_mul_f32_e32 v30, v30, v34
	v_mul_f32_e32 v26, v30, v26
	v_mul_f32_e32 v30, 0xbfb8aa3b, v31
	v_exp_f32_e32 v30, v30
	s_nop 0
	v_add_f32_e32 v30, 1.0, v30
	v_rcp_f32_e32 v30, v30
	s_nop 0
	v_mul_f32_e32 v30, v31, v30
	v_mul_f32_e32 v27, v30, v27
	v_mul_f32_e32 v30, 0xbfb8aa3b, v32
	v_exp_f32_e32 v30, v30
	s_nop 0
	v_add_f32_e32 v30, 1.0, v30
	v_rcp_f32_e32 v30, v30
	s_nop 0
	v_mul_f32_e32 v30, v32, v30
	v_mul_f32_e32 v28, v30, v28
	v_mul_f32_e32 v30, 0xbfb8aa3b, v33
	v_exp_f32_e32 v30, v30
	s_nop 0
	v_add_f32_e32 v30, 1.0, v30
	v_rcp_f32_e32 v30, v30
	s_nop 0
	v_mul_f32_e32 v30, v33, v30
	v_mul_f32_e32 v29, v30, v29
	v_mul_f32_e32 v30, 0xbfb8aa3b, v22
	v_exp_f32_e32 v30, v30
	s_nop 0
	v_add_f32_e32 v30, 1.0, v30
	v_rcp_f32_e32 v30, v30
	s_nop 0
	v_mul_f32_e32 v22, v22, v30
	v_mul_f32_e32 v22, v22, v18
	v_mul_f32_e32 v18, 0xbfb8aa3b, v23
	v_exp_f32_e32 v18, v18
	s_nop 0
	v_add_f32_e32 v18, 1.0, v18
	v_rcp_f32_e32 v18, v18
	s_nop 0
	v_mul_f32_e32 v18, v23, v18
	v_mul_f32_e32 v23, v18, v19
	v_mul_f32_e32 v18, 0xbfb8aa3b, v24
	v_exp_f32_e32 v18, v18
	s_nop 0
	v_add_f32_e32 v18, 1.0, v18
	v_rcp_f32_e32 v18, v18
	s_nop 0
	v_mul_f32_e32 v18, v24, v18
	v_mul_f32_e32 v24, v18, v20
	v_mul_f32_e32 v18, 0xbfb8aa3b, v25
	v_exp_f32_e32 v18, v18
	s_nop 0
	v_add_f32_e32 v18, 1.0, v18
	v_rcp_f32_e32 v18, v18
	s_nop 0
	v_mul_f32_e32 v18, v25, v18
	v_add_u32_e32 v25, 0xa0, v141
	v_mul_f32_e32 v21, v18, v21
	v_cvt_pk_bf16_f32 v18, v26, v27
	v_cvt_pk_bf16_f32 v19, v28, v29
	v_cvt_pk_bf16_f32 v20, v22, v23
	v_mad_i64_i32 v[22:23], s[24:25], v25, s53, v[114:115]
	v_lshl_add_u64 v[22:23], v[22:23], 0, v[116:117]
	v_cvt_pk_bf16_f32 v21, v24, v21
	global_store_dwordx4 v[22:23], v[18:21], off
	s_nop 1
	v_mul_f32_e32 v18, 0xbfb8aa3b, v14
	v_exp_f32_e32 v18, v18
	s_nop 0
	v_add_f32_e32 v18, 1.0, v18
	v_rcp_f32_e32 v18, v18
	s_nop 0
	v_mul_f32_e32 v14, v14, v18
	v_mul_f32_e32 v10, v14, v10
	v_mul_f32_e32 v14, 0xbfb8aa3b, v15
	v_exp_f32_e32 v14, v14
	s_nop 0
	v_add_f32_e32 v14, 1.0, v14
	v_rcp_f32_e32 v14, v14
	s_nop 0
	v_mul_f32_e32 v14, v15, v14
	v_mul_f32_e32 v11, v14, v11
	v_mul_f32_e32 v14, 0xbfb8aa3b, v16
	v_exp_f32_e32 v14, v14
	s_nop 0
	v_add_f32_e32 v14, 1.0, v14
	v_rcp_f32_e32 v14, v14
	s_nop 0
	v_mul_f32_e32 v14, v16, v14
	v_mul_f32_e32 v12, v14, v12
	v_mul_f32_e32 v14, 0xbfb8aa3b, v17
	v_exp_f32_e32 v14, v14
	s_nop 0
	v_add_f32_e32 v14, 1.0, v14
	v_rcp_f32_e32 v14, v14
	s_nop 0
	v_mul_f32_e32 v14, v17, v14
	v_mul_f32_e32 v13, v14, v13
	v_mul_f32_e32 v14, 0xbfb8aa3b, v6
	v_exp_f32_e32 v14, v14
	s_nop 0
	v_add_f32_e32 v14, 1.0, v14
	v_rcp_f32_e32 v14, v14
	s_nop 0
	v_mul_f32_e32 v6, v6, v14
	v_mul_f32_e32 v6, v6, v2
	v_mul_f32_e32 v2, 0xbfb8aa3b, v7
	v_exp_f32_e32 v2, v2
	s_nop 0
	v_add_f32_e32 v2, 1.0, v2
	v_rcp_f32_e32 v2, v2
	s_nop 0
	v_mul_f32_e32 v2, v7, v2
	v_mul_f32_e32 v7, v2, v3
	v_mul_f32_e32 v2, 0xbfb8aa3b, v8
	v_exp_f32_e32 v2, v2
	s_nop 0
	v_add_f32_e32 v2, 1.0, v2
	v_rcp_f32_e32 v2, v2
	s_nop 0
	v_mul_f32_e32 v2, v8, v2
	v_mul_f32_e32 v8, v2, v4
	v_mul_f32_e32 v2, 0xbfb8aa3b, v9
	v_exp_f32_e32 v2, v2
	s_nop 0
	v_add_f32_e32 v2, 1.0, v2
	v_rcp_f32_e32 v2, v2
	s_nop 0
	v_mul_f32_e32 v2, v9, v2
	v_add_u32_e32 v9, 0xb0, v141
	v_mul_f32_e32 v5, v2, v5
	v_cvt_pk_bf16_f32 v2, v10, v11
	v_cvt_pk_bf16_f32 v3, v12, v13
	v_cvt_pk_bf16_f32 v4, v6, v7
	v_mad_i64_i32 v[6:7], s[24:25], v9, s53, v[114:115]
	v_lshl_add_u64 v[6:7], v[6:7], 0, v[116:117]
	s_mov_b64 s[24:25], -1
	v_cvt_pk_bf16_f32 v5, v8, v5
	global_store_dwordx4 v[6:7], v[2:5], off
	s_cbranch_vccnz .LBB0_1056
	s_andn2_b64 vcc, exec, s[8:9]
	s_cbranch_vccnz .LBB0_1055
	s_barrier
	s_branch .LBB0_1055

.LBB0_1067:
	s_abs_i32 s4, s36
	v_cvt_f32_u32_e32 v0, s4
	s_sub_i32 s5, 0, s4
	v_rcp_iflag_f32_e32 v0, v0
	s_nop 0
	v_mul_f32_e32 v0, 0x4f7ffffe, v0
	v_cvt_u32_f32_e32 v0, v0
	s_nop 0
	v_readfirstlane_b32 s8, v0
	s_mul_i32 s5, s5, s8
	s_mul_hi_u32 s5, s8, s5
	s_add_i32 s8, s8, s5
	s_mul_hi_u32 s5, s8, 0x580
	s_mul_i32 s5, s5, s4
	s_sub_i32 s5, 0x580, s5
	s_sub_i32 s8, s5, s4
	s_cmp_ge_u32 s5, s4
	s_cselect_b32 s5, s8, s5
	s_sub_i32 s8, s5, s4
	s_cmp_ge_u32 s5, s4
	s_cselect_b32 s4, s8, s5
	s_cmp_lt_i32 s37, s4
	s_cbranch_scc1 .LBB0_1128
	s_ashr_i32 s5, s38, 6
	s_and_b64 s[8:9], s[74:75], exec
	s_waitcnt lgkmcnt(0)
	s_cselect_b32 s11, s90, 0x1340
	s_add_i32 s8, s56, 1
	s_lshr_b32 s9, s8, 1
	s_bitcmp1_b32 s8, 0
	s_mul_i32 s9, s9, 0xab40
	s_cselect_b32 s8, 0x5600, 0
	s_add_i32 s14, s9, s8
	s_and_b64 s[8:9], s[74:75], exec
	s_cselect_b32 s8, 0x1340, s90
	s_add_i32 s14, s14, s8
	s_cmp_eq_u32 s57, 1
	s_mov_b32 s8, 0x8200
	s_mul_i32 s10, s76, 0xab40
	s_cselect_b32 s8, s8, 0x2c00
	s_add_i32 s8, s8, s10
	s_add_i32 s8, s8, s11
	s_add_i32 s8, s8, s5
	s_cmp_lg_u32 s56, 3
	s_cselect_b32 s16, s14, 0x15680
	s_sub_i32 s9, s37, s4
	s_lshl_b32 s9, s9, 3
	s_add_i32 s17, s8, s9
	s_cmp_ge_i32 s17, s16
	s_cbranch_scc1 .LBB0_1128
	s_sub_i32 s4, s36, s4
	s_lshl_b32 s18, s4, 3
	s_lshl_b32 s4, s5, 14
	s_add_i32 s4, s4, 0
	s_add_u32 s19, s6, 0x10612000
	s_addc_u32 s20, s7, 0
	s_add_u32 s21, s6, 0x4612000
	s_addc_u32 s22, s7, 0
	s_add_u32 s23, s6, 0x3e12000
	s_addc_u32 s24, s7, 0
	s_add_u32 s25, s6, 0x3812000
	s_addc_u32 s26, s7, 0
	s_add_u32 s27, s6, 0x2e12000
	s_addc_u32 s28, s7, 0
	s_add_u32 s29, s6, 0x1e12000
	v_bfe_u32 v10, v136, 3, 3
	s_addc_u32 s30, s7, 0
	v_lshlrev_b32_e32 v0, 2, v136
	v_and_b32_e32 v3, 7, v136
	v_lshlrev_b32_e32 v6, 2, v10
	s_add_u32 s31, s6, 0x612000
	v_and_b32_e32 v0, 28, v0
	v_lshl_add_u32 v4, v3, 4, s4
	v_mul_u32_u24_e32 v5, 0x84, v10
	v_lshlrev_b32_e32 v2, 3, v3
	v_mul_u32_u24_e32 v3, 0x420, v3
	v_and_b32_e32 v14, 16, v6
	s_addc_u32 s33, s7, 0
	v_or_b32_e32 v11, 8, v10
	v_or_b32_e32 v12, 16, v10
	v_or_b32_e32 v13, 24, v10
	v_add3_u32 v15, s4, v3, v6
	v_or_b32_e32 v16, 4, v14
	v_or_b32_e32 v17, 8, v14
	v_or_b32_e32 v18, 12, v6
	v_lshlrev_b32_e32 v0, 2, v0
	v_add_u32_e32 v19, v4, v5
	v_lshlrev_b32_e32 v6, 1, v2
	s_mov_b32 s99, 0
	s_branch .LBB0_1072

.LBB0_1104:
	s_lshr_b32 s8, s45, 5
	v_cvt_f32_u32_e32 v2, s8
	s_sub_i32 s15, 0, s8
	s_abs_i32 s14, s39
	s_ashr_i32 s9, s39, 31
	v_rcp_iflag_f32_e32 v2, v2
	s_nop 0
	v_mul_f32_e32 v2, 0x4f7ffffe, v2
	v_cvt_u32_f32_e32 v2, v2
	s_nop 0
	v_readfirstlane_b32 s37, v2
	s_mul_i32 s15, s15, s37
	s_mul_hi_u32 s15, s37, s15
	s_add_i32 s37, s37, s15
	s_mul_hi_u32 s15, s14, s37
	s_mul_i32 s37, s15, s8
	s_sub_i32 s14, s14, s37
	s_add_i32 s37, s15, 1
	s_sub_i32 s38, s14, s8
	s_cmp_ge_u32 s14, s8
	s_cselect_b32 s15, s37, s15
	s_cselect_b32 s14, s38, s14
	s_add_i32 s37, s15, 1
	s_cmp_ge_u32 s14, s8
	s_cselect_b32 s14, s37, s15
	s_xor_b32 s14, s14, s9
	s_sub_i32 s9, s14, s9
	s_lshl_b32 s14, s9, 6
	s_mul_i32 s8, s9, s8
	v_or_b32_e32 v2, s14, v10
	s_ashr_i32 s15, s14, 31
	s_sub_i32 s37, s39, s8
	s_mul_i32 s9, s15, s45
	v_mad_u64_u32 v[2:3], s[38:39], v2, s45, 0
	s_lshl_b32 s8, s37, 5
	v_add_u32_e32 v3, s9, v3
	v_lshl_add_u64 v[2:3], v[2:3], 2, s[10:11]
	s_ashr_i32 s9, s8, 31
	v_lshl_add_u64 v[2:3], s[8:9], 2, v[2:3]
	v_lshl_add_u64 v[8:9], v[2:3], 0, v[0:1]
	s_lshl_b32 s10, s45, 3
	s_mov_b32 s11, s50
	global_load_dwordx4 v[2:5], v[8:9], off nt
	v_lshl_add_u64 v[20:21], s[10:11], 2, v[8:9]
	global_load_dwordx4 v[20:23], v[20:21], off nt
	s_lshl_b32 s10, s45, 4
	v_lshl_add_u64 v[24:25], s[10:11], 2, v[8:9]
	global_load_dwordx4 v[24:27], v[24:25], off nt
	s_mul_i32 s10, s45, 24
	v_lshl_add_u64 v[28:29], s[10:11], 2, v[8:9]
	global_load_dwordx4 v[28:31], v[28:29], off nt
	s_lshl_b32 s10, s45, 5
	v_lshl_add_u64 v[32:33], s[10:11], 2, v[8:9]
	global_load_dwordx4 v[32:35], v[32:33], off nt
	s_mul_i32 s10, s45, 40
	v_lshl_add_u64 v[36:37], s[10:11], 2, v[8:9]
	global_load_dwordx4 v[36:39], v[36:37], off nt
	s_mul_i32 s10, s45, 48
	v_lshl_add_u64 v[40:41], s[10:11], 2, v[8:9]
	global_load_dwordx4 v[40:43], v[40:41], off nt
	s_mul_i32 s10, s45, 56
	v_lshl_add_u64 v[8:9], s[10:11], 2, v[8:9]
	global_load_dwordx4 v[44:47], v[8:9], off nt
	v_writelane_b32 v255, s4, 40
	v_writelane_b32 v255, s5, 41
	v_writelane_b32 v255, s6, 42
	v_writelane_b32 v255, s7, 43
	v_writelane_b32 v255, s8, 44
	v_writelane_b32 v255, s9, 45
	v_writelane_b32 v255, s10, 46
	v_writelane_b32 v255, s11, 47
	v_writelane_b32 v255, s14, 48
	v_writelane_b32 v255, s15, 49
	v_writelane_b32 v255, s36, 50
	v_writelane_b32 v255, s37, 51
	v_writelane_b32 v255, s48, 52
	s_cmp_eq_u32 s99, 1
	s_cbranch_scc1 .Lcv_tail_G3

.Lcv_tail_G3:
	s_nop 1
	v_readlane_b32 s4, v255, 16
	v_readlane_b32 s5, v255, 17
	v_readlane_b32 s6, v255, 18
	v_readlane_b32 s7, v255, 19
	v_readlane_b32 s8, v255, 20
	v_readlane_b32 s9, v255, 21
	v_readlane_b32 s10, v255, 22
	v_readlane_b32 s11, v255, 23
	v_readlane_b32 s14, v255, 24
	v_readlane_b32 s15, v255, 25
	v_readlane_b32 s36, v255, 26
	v_readlane_b32 s37, v255, 27
	v_readlane_b32 s48, v255, 28
	s_nop 4
	v_mov_b32_e32 v106, v6
	v_or_b32_e32 v107, s8, v10
	s_cmp_gt_i32 s36, 2
	s_mov_b64 s[10:11], -1
	ds_read2_b32 v[102:103], v15 offset1:33
	s_waitcnt lgkmcnt(0)
	v_cvt_pk_bf16_f32 v102, v102, v103
	ds_read2_b32 v[104:105], v15 offset0:66 offset1:99
	s_waitcnt lgkmcnt(0)
	v_cvt_pk_bf16_f32 v103, v104, v105
	ds_read2_b32 v[104:105], v15 offset0:132 offset1:165
	s_waitcnt lgkmcnt(0)
	v_cvt_pk_bf16_f32 v104, v104, v105
	ds_read2_b32 v[108:109], v15 offset0:198 offset1:231
	s_waitcnt lgkmcnt(0)
	v_cvt_pk_bf16_f32 v105, v108, v109
	s_cbranch_scc0 .LBB0_1106
	v_and_or_b32 v121, v107, s91, v14
	s_mov_b64 s[10:11], 0
.LBB0_1106:
	s_lshl_b32 s9, s37, 6
	s_and_b32 s9, s9, 0xffffff00
	s_or_b32 s9, s48, s9
	s_andn2_b64 vcc, exec, s[10:11]
	v_or_b32_e32 v120, s9, v14
	s_cbranch_vccnz .LBB0_1110
	s_cmp_lg_u32 s36, 0
	s_cbranch_scc0 .LBB0_1109
	s_movk_i32 s9, 0x63
	v_and_or_b32 v107, v107, s9, v120

.LBB0_1110:
	s_lshl_b64 s[10:11], s[14:15], 1
	s_add_u32 s6, s6, s10
	s_addc_u32 s7, s7, s11
	v_mov_b32_e32 v107, v1
	v_lshl_add_u64 v[108:109], s[6:7], 0, v[106:107]
	v_ashrrev_i32_e32 v107, 31, v121
	v_mul_lo_u32 v126, s5, v121
	v_mul_lo_u32 v107, s4, v107
	v_mad_u64_u32 v[124:125], s[6:7], s4, v121, 0
	v_add3_u32 v125, v125, v107, v126
	v_lshl_add_u64 v[124:125], v[124:125], 1, v[108:109]
	ds_read2_b32 v[122:123], v15 offset0:8 offset1:41
	global_store_dwordx4 v[124:125], v[102:105], off
	v_or_b32_e32 v121, s8, v11
	s_cmp_gt_i32 s36, 2
	s_waitcnt lgkmcnt(0)
	v_cvt_pk_bf16_f32 v102, v122, v123
	ds_read2_b32 v[104:105], v15 offset0:74 offset1:107
	s_waitcnt lgkmcnt(0)
	v_cvt_pk_bf16_f32 v103, v104, v105
	ds_read2_b32 v[104:105], v15 offset0:140 offset1:173
	s_mov_b64 s[6:7], -1
	s_waitcnt lgkmcnt(0)
	v_cvt_pk_bf16_f32 v104, v104, v105
	ds_read2_b32 v[122:123], v15 offset0:206 offset1:239
	s_waitcnt lgkmcnt(0)
	v_cvt_pk_bf16_f32 v105, v122, v123
	s_cbranch_scc0 .LBB0_1112
	v_and_or_b32 v107, v121, s91, v16
	s_mov_b64 s[6:7], 0
.LBB0_1112:
	s_andn2_b64 vcc, exec, s[6:7]
	s_cbranch_vccnz .LBB0_1116
	s_cmp_lg_u32 s36, 0
	s_cbranch_scc0 .LBB0_1115
	v_and_b32_e32 v107, 0x63, v121
	v_or3_b32 v121, v107, v120, 4

.LBB0_1116:
	v_ashrrev_i32_e32 v121, 31, v107
	v_mul_lo_u32 v126, s5, v107
	v_mul_lo_u32 v121, s4, v121
	v_mad_u64_u32 v[124:125], s[6:7], s4, v107, 0
	v_add3_u32 v125, v125, v121, v126
	v_lshl_add_u64 v[124:125], v[124:125], 1, v[108:109]
	ds_read2_b32 v[122:123], v15 offset0:16 offset1:49
	global_store_dwordx4 v[124:125], v[102:105], off
	v_or_b32_e32 v121, s8, v12
	s_cmp_gt_i32 s36, 2
	s_waitcnt lgkmcnt(0)
	v_cvt_pk_bf16_f32 v102, v122, v123
	ds_read2_b32 v[104:105], v15 offset0:82 offset1:115
	s_waitcnt lgkmcnt(0)
	v_cvt_pk_bf16_f32 v103, v104, v105
	ds_read2_b32 v[104:105], v15 offset0:148 offset1:181
	s_mov_b64 s[6:7], -1
	s_waitcnt lgkmcnt(0)
	v_cvt_pk_bf16_f32 v104, v104, v105
	ds_read2_b32 v[122:123], v15 offset0:214 offset1:247
	s_waitcnt lgkmcnt(0)
	v_cvt_pk_bf16_f32 v105, v122, v123
	s_cbranch_scc0 .LBB0_1118
	v_and_or_b32 v107, v121, s91, v17
	s_mov_b64 s[6:7], 0
.LBB0_1118:
	s_andn2_b64 vcc, exec, s[6:7]
	s_cbranch_vccnz .LBB0_1122
	s_cmp_lg_u32 s36, 0
	s_cbranch_scc0 .LBB0_1121
	v_and_b32_e32 v107, 0x63, v121
	v_or3_b32 v121, v107, v120, 8

.LBB0_1122:
	v_ashrrev_i32_e32 v121, 31, v107
	v_mul_lo_u32 v126, s5, v107
	v_mul_lo_u32 v121, s4, v121
	v_mad_u64_u32 v[124:125], s[6:7], s4, v107, 0
	v_add3_u32 v125, v125, v121, v126
	v_lshl_add_u64 v[124:125], v[124:125], 1, v[108:109]
	ds_read2_b32 v[122:123], v15 offset0:24 offset1:57
	global_store_dwordx4 v[124:125], v[102:105], off
	v_or_b32_e32 v107, s8, v13
	s_cmp_gt_i32 s36, 2
	s_waitcnt lgkmcnt(0)
	v_cvt_pk_bf16_f32 v102, v122, v123
	ds_read2_b32 v[104:105], v15 offset0:90 offset1:123
	s_waitcnt lgkmcnt(0)
	v_cvt_pk_bf16_f32 v103, v104, v105
	ds_read2_b32 v[104:105], v15 offset0:156 offset1:189
	s_mov_b64 s[6:7], -1
	s_waitcnt lgkmcnt(0)
	v_cvt_pk_bf16_f32 v104, v104, v105
	ds_read2_b32 v[122:123], v15 offset0:222 offset1:255
	s_waitcnt lgkmcnt(0)
	v_cvt_pk_bf16_f32 v105, v122, v123
	s_cbranch_scc0 .LBB0_1124
	v_and_or_b32 v121, v107, s91, v18
	s_mov_b64 s[6:7], 0
.LBB0_1124:
	s_andn2_b64 vcc, exec, s[6:7]
	s_cbranch_vccnz .LBB0_1071
	s_cmp_lg_u32 s36, 0
	s_cbranch_scc0 .LBB0_1070
	v_and_b32_e32 v107, 0x63, v107
	v_or3_b32 v107, v107, v120, 12
	s_branch .LBB0_1070

.LBB0_1225:
	s_or_b64 exec, exec, s[4:5]
	v_cndmask_b32_e64 v0, 0, 1, s[14:15]
	v_or_b32_e32 v130, 16, v210
	v_or_b32_e32 v92, 32, v210
	v_or_b32_e32 v90, 48, v210
	s_mov_b64 s[16:17], 0
	v_cmp_ne_u32_e64 s[4:5], 1, v0
	s_andn2_b64 vcc, exec, s[14:15]
	v_ashrrev_i32_e32 v211, 31, v210
	v_ashrrev_i32_e32 v131, 31, v130
	v_ashrrev_i32_e32 v93, 31, v92
	v_ashrrev_i32_e32 v91, 31, v90
	s_cbranch_vccnz .LBB0_1227
	s_waitcnt lgkmcnt(0)
	v_lshlrev_b64 v[2:3], 12, v[210:211]
	v_lshl_add_u64 v[2:3], s[8:9], 0, v[2:3]
	v_lshlrev_b64 v[8:9], 1, v[208:209]
	v_lshl_add_u64 v[2:3], v[2:3], 0, v[8:9]
	v_cvt_pk_bf16_f32 v4, v126, v127
	v_cvt_pk_bf16_f32 v5, v128, v129
	v_cvt_pk_bf16_f32 v6, v122, v123
	v_cvt_pk_bf16_f32 v7, v124, v125
	global_store_dwordx4 v[2:3], v[4:7], off
	s_add_u32 s16, s22, 0x24000
	s_addc_u32 s17, s23, 0
	v_cvt_pk_bf16_f32 v4, v118, v119
	v_cvt_pk_bf16_f32 v5, v120, v121
	v_cvt_pk_bf16_f32 v6, v114, v115
	v_cvt_pk_bf16_f32 v7, v116, v117
	global_store_dwordx4 v[2:3], v[4:7], off offset:256
	s_nop 1
	v_lshlrev_b64 v[4:5], 12, v[130:131]
	v_lshl_add_u64 v[4:5], s[8:9], 0, v[4:5]
	v_lshl_add_u64 v[10:11], v[4:5], 0, v[8:9]
	v_cvt_pk_bf16_f32 v4, v110, v111
	v_cvt_pk_bf16_f32 v5, v112, v113
	v_cvt_pk_bf16_f32 v6, v106, v107
	v_cvt_pk_bf16_f32 v7, v108, v109
	global_store_dwordx4 v[10:11], v[4:7], off
	s_nop 1
	v_cvt_pk_bf16_f32 v4, v102, v103
	v_cvt_pk_bf16_f32 v5, v104, v105
	v_cvt_pk_bf16_f32 v6, v94, v95
	v_cvt_pk_bf16_f32 v7, v96, v97
	global_store_dwordx4 v[10:11], v[4:7], off offset:256
	s_nop 1
	v_lshlrev_b64 v[4:5], 12, v[92:93]
	v_lshl_add_u64 v[4:5], s[8:9], 0, v[4:5]
	v_lshl_add_u64 v[10:11], v[4:5], 0, v[8:9]
	v_cvt_pk_bf16_f32 v4, v192, v193
	v_cvt_pk_bf16_f32 v5, v100, v101
	v_cvt_pk_bf16_f32 v6, v190, v191
	v_cvt_pk_bf16_f32 v7, v98, v99
	global_store_dwordx4 v[10:11], v[4:7], off
	s_nop 1
	v_cvt_pk_bf16_f32 v4, v86, v87
	v_cvt_pk_bf16_f32 v5, v88, v89
	v_cvt_pk_bf16_f32 v6, v78, v79
	v_cvt_pk_bf16_f32 v7, v80, v81
	global_store_dwordx4 v[10:11], v[4:7], off offset:256
	s_nop 1
	v_lshlrev_b64 v[4:5], 12, v[90:91]
	v_lshl_add_u64 v[4:5], s[8:9], 0, v[4:5]
	v_lshl_add_u64 v[8:9], v[4:5], 0, v[8:9]
	v_cvt_pk_bf16_f32 v4, v188, v189
	v_cvt_pk_bf16_f32 v5, v180, v181
	v_cvt_pk_bf16_f32 v6, v186, v187
	v_cvt_pk_bf16_f32 v7, v178, v179
	s_mov_b64 s[8:9], 0x80000
	global_store_dwordx4 v[8:9], v[4:7], off
	s_nop 1
	v_cvt_pk_bf16_f32 v4, v70, v71
	v_cvt_pk_bf16_f32 v5, v72, v73
	v_cvt_pk_bf16_f32 v6, v66, v67
	v_cvt_pk_bf16_f32 v7, v68, v69
	global_store_dwordx4 v[8:9], v[4:7], off offset:256
	v_lshl_add_u64 v[8:9], v[2:3], 0, s[8:9]
	s_mov_b32 s8, 0x80000
	v_add_co_u32_e32 v10, vcc, s8, v2
	v_cvt_pk_bf16_f32 v4, v184, v185
	v_cvt_pk_bf16_f32 v5, v176, v177
	v_cvt_pk_bf16_f32 v6, v182, v183
	v_cvt_pk_bf16_f32 v7, v174, v175
	s_nop 1
	v_addc_co_u32_e32 v11, vcc, 0, v3, vcc
	s_mov_b64 s[8:9], 0x90000
	global_store_dwordx4 v[10:11], v[4:7], off
	s_nop 1
	v_cvt_pk_bf16_f32 v4, v54, v55
	v_cvt_pk_bf16_f32 v5, v56, v57
	v_cvt_pk_bf16_f32 v6, v46, v47
	v_cvt_pk_bf16_f32 v7, v48, v49
	global_store_dwordx4 v[8:9], v[4:7], off offset:256
	v_lshl_add_u64 v[8:9], v[2:3], 0, s[8:9]
	s_mov_b32 s8, 0x90000
	v_add_co_u32_e32 v10, vcc, s8, v2
	v_cvt_pk_bf16_f32 v4, v172, v173
	v_cvt_pk_bf16_f32 v5, v168, v169
	v_cvt_pk_bf16_f32 v6, v170, v171
	v_cvt_pk_bf16_f32 v7, v166, v167
	s_nop 1
	v_addc_co_u32_e32 v11, vcc, 0, v3, vcc
	s_mov_b64 s[8:9], 0xa0000
	global_store_dwordx4 v[10:11], v[4:7], off
	s_nop 1
	v_cvt_pk_bf16_f32 v4, v52, v53
	v_cvt_pk_bf16_f32 v5, v44, v45
	v_cvt_pk_bf16_f32 v6, v50, v51
	v_cvt_pk_bf16_f32 v7, v42, v43
	global_store_dwordx4 v[8:9], v[4:7], off offset:256
	v_lshl_add_u64 v[8:9], v[2:3], 0, s[8:9]
	s_mov_b32 s8, 0xa0000
	v_add_co_u32_e32 v10, vcc, s8, v2
	v_cvt_pk_bf16_f32 v4, v164, v165
	v_cvt_pk_bf16_f32 v5, v160, v161
	v_cvt_pk_bf16_f32 v6, v162, v163
	v_cvt_pk_bf16_f32 v7, v158, v159
	s_nop 1
	v_addc_co_u32_e32 v11, vcc, 0, v3, vcc
	s_mov_b64 s[8:9], 0xb0000
	global_store_dwordx4 v[10:11], v[4:7], off
	s_nop 1
	v_cvt_pk_bf16_f32 v4, v64, v65
	v_cvt_pk_bf16_f32 v5, v60, v61
	v_cvt_pk_bf16_f32 v6, v62, v63
	v_cvt_pk_bf16_f32 v7, v58, v59
	global_store_dwordx4 v[8:9], v[4:7], off offset:256
	v_lshl_add_u64 v[8:9], v[2:3], 0, s[8:9]
	s_mov_b32 s8, 0xb0000
	v_add_co_u32_e32 v2, vcc, s8, v2
	v_cvt_pk_bf16_f32 v4, v142, v143
	v_cvt_pk_bf16_f32 v5, v144, v145
	v_cvt_pk_bf16_f32 v6, v138, v139
	v_cvt_pk_bf16_f32 v7, v140, v141
	s_nop 1
	v_addc_co_u32_e32 v3, vcc, 0, v3, vcc
	global_store_dwordx4 v[2:3], v[4:7], off
	v_cvt_pk_bf16_f32 v2, v84, v85
	v_cvt_pk_bf16_f32 v3, v76, v77
	s_nop 1
	v_cvt_pk_bf16_f32 v4, v82, v83
	v_cvt_pk_bf16_f32 v5, v74, v75
	global_store_dwordx4 v[8:9], v[2:5], off offset:256

.LBB0_1249:
	s_or_b64 exec, exec, s[8:9]
	s_add_u32 s6, s26, 0x19e12000
	s_addc_u32 s7, s27, 0
	s_lshl_b32 s8, s34, 2
	s_add_i32 s8, s8, 0
	v_lshl_add_u32 v0, v212, 2, s8
	s_waitcnt lgkmcnt(0)
	s_barrier
	v_add_u32_e32 v0, 0x2000, v0
	ds_read2_b32 v[146:147], v0 offset1:16
	ds_read2_b32 v[136:137], v0 offset0:32 offset1:48
	ds_read2_b32 v[134:135], v0 offset0:128 offset1:144
	ds_read2_b32 v[132:133], v0 offset0:160 offset1:176
	s_and_b64 vcc, exec, s[4:5]
	s_waitcnt lgkmcnt(3)
	v_pk_mul_f32 v[34:35], v[128:129], v[146:147] op_sel_hi:[1,0]
	v_pk_mul_f32 v[38:39], v[126:127], v[146:147] op_sel_hi:[1,0]
	v_pk_fma_f32 v[36:37], v[24:25], v[34:35], v[32:33]
	v_pk_fma_f32 v[34:35], v[22:23], v[38:39], v[30:31]
	v_pk_mul_f32 v[40:41], v[124:125], v[146:147] op_sel_hi:[1,0]
	v_pk_mul_f32 v[38:39], v[122:123], v[146:147] op_sel_hi:[1,0]
	v_pk_fma_f32 v[40:41], v[20:21], v[40:41], v[28:29]
	v_pk_fma_f32 v[38:39], v[18:19], v[38:39], v[26:27]
	s_mov_b64 s[8:9], -1
	s_cbranch_vccnz .LBB0_1251
	v_lshlrev_b64 v[126:127], 12, v[210:211]
	v_lshl_add_u64 v[126:127], s[6:7], 0, v[126:127]
	v_lshl_add_u64 v[126:127], v[208:209], 1, v[126:127]
	s_mov_b64 s[8:9], 0
	v_cvt_pk_bf16_f32 v122, v34, v35
	v_cvt_pk_bf16_f32 v123, v36, v37
	v_cvt_pk_bf16_f32 v124, v38, v39
	v_cvt_pk_bf16_f32 v125, v40, v41
	global_store_dwordx4 v[126:127], v[122:125], off
.LBB0_1251:
	s_andn2_b64 vcc, exec, s[8:9]
	s_cbranch_vccnz .LBB0_1253
	v_lshlrev_b64 v[122:123], 13, v[210:211]
	v_lshl_add_u64 v[122:123], s[24:25], 0, v[122:123]
	v_lshl_add_u64 v[122:123], v[208:209], 2, v[122:123]
	global_store_dwordx4 v[122:123], v[34:37], off
	global_store_dwordx4 v[122:123], v[38:41], off offset:16
.LBB0_1253:
	v_mov_b32_e32 v0, v147
	v_pk_mul_f32 v[34:35], v[112:113], v[0:1] op_sel_hi:[1,0]
	v_pk_mul_f32 v[38:39], v[110:111], v[0:1] op_sel_hi:[1,0]
	v_pk_fma_f32 v[36:37], v[24:25], v[34:35], v[32:33]
	v_pk_fma_f32 v[34:35], v[22:23], v[38:39], v[30:31]
	v_pk_mul_f32 v[38:39], v[108:109], v[0:1] op_sel_hi:[1,0]
	v_pk_mul_f32 v[106:107], v[106:107], v[0:1] op_sel_hi:[1,0]
	v_pk_fma_f32 v[40:41], v[20:21], v[38:39], v[28:29]
	v_pk_fma_f32 v[38:39], v[18:19], v[106:107], v[26:27]
	s_and_b64 vcc, exec, s[4:5]
	s_mov_b64 s[8:9], -1
	s_cbranch_vccnz .LBB0_1255
	v_lshlrev_b64 v[110:111], 12, v[130:131]
	v_lshl_add_u64 v[110:111], s[6:7], 0, v[110:111]
	v_lshl_add_u64 v[110:111], v[208:209], 1, v[110:111]
	s_mov_b64 s[8:9], 0
	v_cvt_pk_bf16_f32 v106, v34, v35
	v_cvt_pk_bf16_f32 v107, v36, v37
	v_cvt_pk_bf16_f32 v108, v38, v39
	v_cvt_pk_bf16_f32 v109, v40, v41
	global_store_dwordx4 v[110:111], v[106:109], off
.LBB0_1255:
	s_andn2_b64 vcc, exec, s[8:9]
	s_cbranch_vccnz .LBB0_1257
	v_lshlrev_b64 v[106:107], 13, v[130:131]
	v_lshl_add_u64 v[106:107], s[24:25], 0, v[106:107]
	v_lshl_add_u64 v[106:107], v[208:209], 2, v[106:107]
	global_store_dwordx4 v[106:107], v[34:37], off
	global_store_dwordx4 v[106:107], v[38:41], off offset:16
.LBB0_1257:
	s_waitcnt lgkmcnt(2)
	v_pk_mul_f32 v[34:35], v[100:101], v[136:137] op_sel_hi:[1,0]
	v_pk_mul_f32 v[38:39], v[192:193], v[136:137] op_sel_hi:[1,0]
	v_pk_fma_f32 v[36:37], v[24:25], v[34:35], v[32:33]
	v_pk_fma_f32 v[34:35], v[22:23], v[38:39], v[30:31]
	v_pk_mul_f32 v[38:39], v[98:99], v[136:137] op_sel_hi:[1,0]
	v_pk_mul_f32 v[98:99], v[190:191], v[136:137] op_sel_hi:[1,0]
	v_pk_fma_f32 v[40:41], v[20:21], v[38:39], v[28:29]
	v_pk_fma_f32 v[38:39], v[18:19], v[98:99], v[26:27]
	s_and_b64 vcc, exec, s[4:5]
	s_mov_b64 s[8:9], -1
	s_cbranch_vccnz .LBB0_1259
	v_lshlrev_b64 v[106:107], 12, v[92:93]
	v_lshl_add_u64 v[106:107], s[6:7], 0, v[106:107]
	v_lshl_add_u64 v[106:107], v[208:209], 1, v[106:107]
	s_mov_b64 s[8:9], 0
	v_cvt_pk_bf16_f32 v98, v34, v35
	v_cvt_pk_bf16_f32 v99, v36, v37
	v_cvt_pk_bf16_f32 v100, v38, v39
	v_cvt_pk_bf16_f32 v101, v40, v41
	global_store_dwordx4 v[106:107], v[98:101], off
.LBB0_1259:
	s_andn2_b64 vcc, exec, s[8:9]
	s_cbranch_vccnz .LBB0_1261
	v_lshlrev_b64 v[98:99], 13, v[92:93]
	v_lshl_add_u64 v[98:99], s[24:25], 0, v[98:99]
	v_lshl_add_u64 v[98:99], v[208:209], 2, v[98:99]
	global_store_dwordx4 v[98:99], v[34:37], off
	global_store_dwordx4 v[98:99], v[38:41], off offset:16
.LBB0_1261:
	v_mov_b32_e32 v0, v137
	v_pk_mul_f32 v[34:35], v[180:181], v[0:1] op_sel_hi:[1,0]
	v_pk_mul_f32 v[38:39], v[188:189], v[0:1] op_sel_hi:[1,0]
	v_pk_fma_f32 v[36:37], v[24:25], v[34:35], v[32:33]
	v_pk_fma_f32 v[34:35], v[22:23], v[38:39], v[30:31]
	v_pk_mul_f32 v[38:39], v[178:179], v[0:1] op_sel_hi:[1,0]
	v_pk_mul_f32 v[98:99], v[186:187], v[0:1] op_sel_hi:[1,0]
	v_pk_fma_f32 v[40:41], v[20:21], v[38:39], v[28:29]
	v_pk_fma_f32 v[38:39], v[18:19], v[98:99], v[26:27]
	s_and_b64 vcc, exec, s[4:5]
	s_mov_b64 s[8:9], -1
	s_cbranch_vccnz .LBB0_1263
	v_lshlrev_b64 v[106:107], 12, v[90:91]
	v_lshl_add_u64 v[106:107], s[6:7], 0, v[106:107]
	v_lshl_add_u64 v[106:107], v[208:209], 1, v[106:107]
	s_mov_b64 s[8:9], 0
	v_cvt_pk_bf16_f32 v98, v34, v35
	v_cvt_pk_bf16_f32 v99, v36, v37
	v_cvt_pk_bf16_f32 v100, v38, v39
	v_cvt_pk_bf16_f32 v101, v40, v41
	global_store_dwordx4 v[106:107], v[98:101], off
.LBB0_1263:
	s_andn2_b64 vcc, exec, s[8:9]
	s_cbranch_vccnz .LBB0_1265
	v_lshlrev_b64 v[98:99], 13, v[90:91]
	v_lshl_add_u64 v[98:99], s[24:25], 0, v[98:99]
	v_lshl_add_u64 v[98:99], v[208:209], 2, v[98:99]
	global_store_dwordx4 v[98:99], v[34:37], off
	global_store_dwordx4 v[98:99], v[38:41], off offset:16
.LBB0_1265:
	s_waitcnt lgkmcnt(1)
	v_pk_mul_f32 v[34:35], v[176:177], v[134:135] op_sel_hi:[1,0]
	v_pk_mul_f32 v[38:39], v[184:185], v[134:135] op_sel_hi:[1,0]
	v_add_u32_e32 v106, 0x80, v210
	v_pk_fma_f32 v[36:37], v[24:25], v[34:35], v[32:33]
	v_pk_fma_f32 v[34:35], v[22:23], v[38:39], v[30:31]
	v_pk_mul_f32 v[38:39], v[174:175], v[134:135] op_sel_hi:[1,0]
	v_pk_mul_f32 v[98:99], v[182:183], v[134:135] op_sel_hi:[1,0]
	v_pk_fma_f32 v[40:41], v[20:21], v[38:39], v[28:29]
	v_pk_fma_f32 v[38:39], v[18:19], v[98:99], v[26:27]
	s_mov_b64 s[8:9], -1
	s_and_b64 vcc, exec, s[4:5]
	v_ashrrev_i32_e32 v107, 31, v106
	s_cbranch_vccnz .LBB0_1267
	v_lshlrev_b64 v[108:109], 12, v[106:107]
	v_lshl_add_u64 v[108:109], s[6:7], 0, v[108:109]
	v_lshl_add_u64 v[108:109], v[208:209], 1, v[108:109]
	s_mov_b64 s[8:9], 0
	v_cvt_pk_bf16_f32 v98, v34, v35
	v_cvt_pk_bf16_f32 v99, v36, v37
	v_cvt_pk_bf16_f32 v100, v38, v39
	v_cvt_pk_bf16_f32 v101, v40, v41
	global_store_dwordx4 v[108:109], v[98:101], off
.LBB0_1267:
	s_andn2_b64 vcc, exec, s[8:9]
	s_cbranch_vccnz .LBB0_1269
	v_lshlrev_b64 v[98:99], 13, v[106:107]
	v_lshl_add_u64 v[98:99], s[24:25], 0, v[98:99]
	v_lshl_add_u64 v[98:99], v[208:209], 2, v[98:99]
	global_store_dwordx4 v[98:99], v[34:37], off
	global_store_dwordx4 v[98:99], v[38:41], off offset:16
.LBB0_1269:
	v_mov_b32_e32 v0, v135
	v_pk_mul_f32 v[34:35], v[168:169], v[0:1] op_sel_hi:[1,0]
	v_pk_mul_f32 v[38:39], v[172:173], v[0:1] op_sel_hi:[1,0]
	v_add_u32_e32 v100, 0x90, v210
	v_pk_fma_f32 v[36:37], v[24:25], v[34:35], v[32:33]
	v_pk_fma_f32 v[34:35], v[22:23], v[38:39], v[30:31]
	v_pk_mul_f32 v[38:39], v[166:167], v[0:1] op_sel_hi:[1,0]
	v_pk_mul_f32 v[98:99], v[170:171], v[0:1] op_sel_hi:[1,0]
	v_pk_fma_f32 v[40:41], v[20:21], v[38:39], v[28:29]
	v_pk_fma_f32 v[38:39], v[18:19], v[98:99], v[26:27]
	s_mov_b64 s[8:9], -1
	s_and_b64 vcc, exec, s[4:5]
	v_ashrrev_i32_e32 v101, 31, v100
	s_cbranch_vccnz .LBB0_1271
	v_lshlrev_b64 v[98:99], 12, v[100:101]
	v_lshl_add_u64 v[98:99], s[6:7], 0, v[98:99]
	v_lshl_add_u64 v[98:99], v[208:209], 1, v[98:99]
	s_mov_b64 s[8:9], 0
	v_cvt_pk_bf16_f32 v108, v34, v35
	v_cvt_pk_bf16_f32 v109, v36, v37
	v_cvt_pk_bf16_f32 v110, v38, v39
	v_cvt_pk_bf16_f32 v111, v40, v41
	global_store_dwordx4 v[98:99], v[108:111], off
.LBB0_1271:
	s_andn2_b64 vcc, exec, s[8:9]
	s_cbranch_vccnz .LBB0_1273
	v_lshlrev_b64 v[98:99], 13, v[100:101]
	v_lshl_add_u64 v[98:99], s[24:25], 0, v[98:99]
	v_lshl_add_u64 v[98:99], v[208:209], 2, v[98:99]
	global_store_dwordx4 v[98:99], v[34:37], off
	global_store_dwordx4 v[98:99], v[38:41], off offset:16
.LBB0_1273:
	s_waitcnt lgkmcnt(0)
	v_pk_mul_f32 v[34:35], v[160:161], v[132:133] op_sel_hi:[1,0]
	v_pk_mul_f32 v[38:39], v[164:165], v[132:133] op_sel_hi:[1,0]
	v_add_u32_e32 v98, 0xa0, v210
	v_pk_fma_f32 v[36:37], v[24:25], v[34:35], v[32:33]
	v_pk_fma_f32 v[34:35], v[22:23], v[38:39], v[30:31]
	v_pk_mul_f32 v[38:39], v[158:159], v[132:133] op_sel_hi:[1,0]
	v_pk_mul_f32 v[108:109], v[162:163], v[132:133] op_sel_hi:[1,0]
	v_pk_fma_f32 v[40:41], v[20:21], v[38:39], v[28:29]
	v_pk_fma_f32 v[38:39], v[18:19], v[108:109], v[26:27]
	s_mov_b64 s[8:9], -1
	s_and_b64 vcc, exec, s[4:5]
	v_ashrrev_i32_e32 v99, 31, v98
	s_cbranch_vccnz .LBB0_1275
	v_lshlrev_b64 v[112:113], 12, v[98:99]
	v_lshl_add_u64 v[112:113], s[6:7], 0, v[112:113]
	v_lshl_add_u64 v[112:113], v[208:209], 1, v[112:113]
	s_mov_b64 s[8:9], 0
	v_cvt_pk_bf16_f32 v108, v34, v35
	v_cvt_pk_bf16_f32 v109, v36, v37
	v_cvt_pk_bf16_f32 v110, v38, v39
	v_cvt_pk_bf16_f32 v111, v40, v41
	global_store_dwordx4 v[112:113], v[108:111], off
.LBB0_1275:
	s_andn2_b64 vcc, exec, s[8:9]
	s_cbranch_vccnz .LBB0_1277
	v_lshlrev_b64 v[108:109], 13, v[98:99]
	v_lshl_add_u64 v[108:109], s[24:25], 0, v[108:109]
	v_lshl_add_u64 v[108:109], v[208:209], 2, v[108:109]
	global_store_dwordx4 v[108:109], v[34:37], off
	global_store_dwordx4 v[108:109], v[38:41], off offset:16
.LBB0_1277:
	v_mov_b32_e32 v0, v133
	v_pk_mul_f32 v[36:37], v[144:145], v[0:1] op_sel_hi:[1,0]
	v_pk_mul_f32 v[38:39], v[142:143], v[0:1] op_sel_hi:[1,0]
	v_add_u32_e32 v34, 0xb0, v210
	v_pk_fma_f32 v[24:25], v[24:25], v[36:37], v[32:33]
	v_pk_fma_f32 v[22:23], v[22:23], v[38:39], v[30:31]
	v_pk_mul_f32 v[30:31], v[140:141], v[0:1] op_sel_hi:[1,0]
	v_pk_mul_f32 v[32:33], v[138:139], v[0:1] op_sel_hi:[1,0]
	v_pk_fma_f32 v[20:21], v[20:21], v[30:31], v[28:29]
	v_pk_fma_f32 v[18:19], v[18:19], v[32:33], v[26:27]
	s_mov_b64 s[8:9], -1
	s_and_b64 vcc, exec, s[4:5]
	v_ashrrev_i32_e32 v35, 31, v34
	s_cbranch_vccnz .LBB0_1279
	v_lshlrev_b64 v[30:31], 12, v[34:35]
	v_lshl_add_u64 v[30:31], s[6:7], 0, v[30:31]
	v_lshl_add_u64 v[30:31], v[208:209], 1, v[30:31]
	s_mov_b64 s[8:9], 0
	v_cvt_pk_bf16_f32 v26, v22, v23
	v_cvt_pk_bf16_f32 v27, v24, v25
	v_cvt_pk_bf16_f32 v28, v18, v19
	v_cvt_pk_bf16_f32 v29, v20, v21
	global_store_dwordx4 v[30:31], v[26:29], off
.LBB0_1279:
	s_andn2_b64 vcc, exec, s[8:9]
	s_cbranch_vccnz .LBB0_1281
	v_lshlrev_b64 v[26:27], 13, v[34:35]
	v_lshl_add_u64 v[26:27], s[24:25], 0, v[26:27]
	v_lshl_add_u64 v[26:27], v[208:209], 2, v[26:27]
	global_store_dwordx4 v[26:27], v[22:25], off
	global_store_dwordx4 v[26:27], v[18:21], off offset:16
.LBB0_1281:
	s_nop 0
	v_mov_b32_e32 v22, v146
	v_mov_b32_e32 v23, v146
	v_mov_b32_e32 v24, v146
	v_mov_b32_e32 v25, v146
	v_pk_mul_f32 v[20:21], v[120:121], v[24:25]
	v_pk_mul_f32 v[18:19], v[118:119], v[22:23]
	v_pk_mul_f32 v[24:25], v[116:117], v[24:25]
	v_pk_mul_f32 v[22:23], v[114:115], v[22:23]
	v_pk_fma_f32 v[18:19], v[6:7], v[18:19], v[14:15]
	v_pk_fma_f32 v[20:21], v[8:9], v[20:21], v[16:17]
	v_pk_fma_f32 v[22:23], v[2:3], v[22:23], v[10:11]
	v_pk_fma_f32 v[24:25], v[4:5], v[24:25], v[12:13]
	s_and_b64 vcc, exec, s[4:5]
	s_mov_b64 s[8:9], -1
	s_cbranch_vccnz .LBB0_1283
	v_lshlrev_b64 v[30:31], 12, v[210:211]
	v_lshl_add_u64 v[30:31], s[6:7], 0, v[30:31]
	v_lshl_add_u64 v[30:31], v[208:209], 1, v[30:31]
	s_mov_b64 s[8:9], 0
	v_cvt_pk_bf16_f32 v26, v18, v19
	v_cvt_pk_bf16_f32 v27, v20, v21
	v_cvt_pk_bf16_f32 v28, v22, v23
	v_cvt_pk_bf16_f32 v29, v24, v25
	global_store_dwordx4 v[30:31], v[26:29], off offset:256
.LBB0_1283:
	s_andn2_b64 vcc, exec, s[8:9]
	s_cbranch_vccnz .LBB0_1285
	v_lshlrev_b64 v[26:27], 13, v[210:211]
	v_lshl_add_u64 v[26:27], s[24:25], 0, v[26:27]
	v_lshl_add_u64 v[26:27], v[208:209], 2, v[26:27]
	global_store_dwordx4 v[26:27], v[18:21], off offset:512
	global_store_dwordx4 v[26:27], v[22:25], off offset:528
.LBB0_1285:
	v_mov_b32_e32 v146, v147
	s_nop 0
	v_mov_b32_e32 v22, v147
	v_mov_b32_e32 v23, v147
	v_pk_mul_f32 v[18:19], v[104:105], v[22:23]
	v_pk_mul_f32 v[24:25], v[102:103], v[146:147]
	v_pk_mul_f32 v[22:23], v[96:97], v[22:23]
	v_pk_mul_f32 v[26:27], v[94:95], v[146:147]
	v_pk_fma_f32 v[20:21], v[8:9], v[18:19], v[16:17]
	v_pk_fma_f32 v[18:19], v[6:7], v[24:25], v[14:15]
	v_pk_fma_f32 v[24:25], v[4:5], v[22:23], v[12:13]
	v_pk_fma_f32 v[22:23], v[2:3], v[26:27], v[10:11]
	s_and_b64 vcc, exec, s[4:5]
	s_mov_b64 s[8:9], -1
	s_cbranch_vccnz .LBB0_1287
	v_lshlrev_b64 v[30:31], 12, v[130:131]
	v_lshl_add_u64 v[30:31], s[6:7], 0, v[30:31]
	v_lshl_add_u64 v[30:31], v[208:209], 1, v[30:31]
	s_mov_b64 s[8:9], 0
	v_cvt_pk_bf16_f32 v26, v18, v19
	v_cvt_pk_bf16_f32 v27, v20, v21
	v_cvt_pk_bf16_f32 v28, v22, v23
	v_cvt_pk_bf16_f32 v29, v24, v25
	global_store_dwordx4 v[30:31], v[26:29], off offset:256
.LBB0_1287:
	s_andn2_b64 vcc, exec, s[8:9]
	s_cbranch_vccnz .LBB0_1289
	v_lshlrev_b64 v[26:27], 13, v[130:131]
	v_lshl_add_u64 v[26:27], s[24:25], 0, v[26:27]
	v_lshl_add_u64 v[26:27], v[208:209], 2, v[26:27]
	global_store_dwordx4 v[26:27], v[18:21], off offset:512
	global_store_dwordx4 v[26:27], v[22:25], off offset:528
.LBB0_1289:
	s_nop 1
	v_mov_b32_e32 v22, v136
	v_mov_b32_e32 v23, v136
	v_mov_b32_e32 v24, v136
	v_mov_b32_e32 v25, v136
	v_pk_mul_f32 v[18:19], v[88:89], v[24:25]
	v_pk_mul_f32 v[26:27], v[86:87], v[22:23]
	v_pk_mul_f32 v[24:25], v[80:81], v[24:25]
	v_pk_mul_f32 v[22:23], v[78:79], v[22:23]
	v_pk_fma_f32 v[20:21], v[8:9], v[18:19], v[16:17]
	v_pk_fma_f32 v[18:19], v[6:7], v[26:27], v[14:15]
	v_pk_fma_f32 v[24:25], v[4:5], v[24:25], v[12:13]
	v_pk_fma_f32 v[22:23], v[2:3], v[22:23], v[10:11]
	s_and_b64 vcc, exec, s[4:5]
	s_mov_b64 s[8:9], -1
	s_cbranch_vccnz .LBB0_1291
	v_lshlrev_b64 v[30:31], 12, v[92:93]
	v_lshl_add_u64 v[30:31], s[6:7], 0, v[30:31]
	v_lshl_add_u64 v[30:31], v[208:209], 1, v[30:31]
	s_mov_b64 s[8:9], 0
	v_cvt_pk_bf16_f32 v26, v18, v19
	v_cvt_pk_bf16_f32 v27, v20, v21
	v_cvt_pk_bf16_f32 v28, v22, v23
	v_cvt_pk_bf16_f32 v29, v24, v25
	global_store_dwordx4 v[30:31], v[26:29], off offset:256
.LBB0_1291:
	s_andn2_b64 vcc, exec, s[8:9]
	s_cbranch_vccnz .LBB0_1293
	v_lshlrev_b64 v[26:27], 13, v[92:93]
	v_lshl_add_u64 v[26:27], s[24:25], 0, v[26:27]
	v_lshl_add_u64 v[26:27], v[208:209], 2, v[26:27]
	global_store_dwordx4 v[26:27], v[18:21], off offset:512
	global_store_dwordx4 v[26:27], v[22:25], off offset:528
.LBB0_1293:
	v_mov_b32_e32 v136, v137
	s_nop 0
	v_mov_b32_e32 v22, v137
	v_mov_b32_e32 v23, v137
	v_pk_mul_f32 v[18:19], v[72:73], v[22:23]
	v_pk_mul_f32 v[24:25], v[70:71], v[136:137]
	v_pk_mul_f32 v[22:23], v[68:69], v[22:23]
	v_pk_mul_f32 v[26:27], v[66:67], v[136:137]
	v_pk_fma_f32 v[20:21], v[8:9], v[18:19], v[16:17]
	v_pk_fma_f32 v[18:19], v[6:7], v[24:25], v[14:15]
	v_pk_fma_f32 v[24:25], v[4:5], v[22:23], v[12:13]
	v_pk_fma_f32 v[22:23], v[2:3], v[26:27], v[10:11]
	s_and_b64 vcc, exec, s[4:5]
	s_mov_b64 s[8:9], -1
	s_cbranch_vccnz .LBB0_1295
	v_lshlrev_b64 v[30:31], 12, v[90:91]
	v_lshl_add_u64 v[30:31], s[6:7], 0, v[30:31]
	v_lshl_add_u64 v[30:31], v[208:209], 1, v[30:31]
	s_mov_b64 s[8:9], 0
	v_cvt_pk_bf16_f32 v26, v18, v19
	v_cvt_pk_bf16_f32 v27, v20, v21
	v_cvt_pk_bf16_f32 v28, v22, v23
	v_cvt_pk_bf16_f32 v29, v24, v25
	global_store_dwordx4 v[30:31], v[26:29], off offset:256
.LBB0_1295:
	s_andn2_b64 vcc, exec, s[8:9]
	s_cbranch_vccnz .LBB0_1297
	v_lshlrev_b64 v[26:27], 13, v[90:91]
	v_lshl_add_u64 v[26:27], s[24:25], 0, v[26:27]
	v_lshl_add_u64 v[26:27], v[208:209], 2, v[26:27]
	global_store_dwordx4 v[26:27], v[18:21], off offset:512
	global_store_dwordx4 v[26:27], v[22:25], off offset:528
.LBB0_1297:
	s_nop 1
	v_mov_b32_e32 v22, v134
	v_mov_b32_e32 v23, v134
	v_mov_b32_e32 v24, v134
	v_mov_b32_e32 v25, v134
	v_pk_mul_f32 v[18:19], v[56:57], v[24:25]
	v_pk_mul_f32 v[26:27], v[54:55], v[22:23]
	v_pk_mul_f32 v[24:25], v[48:49], v[24:25]
	v_pk_mul_f32 v[22:23], v[46:47], v[22:23]
	v_pk_fma_f32 v[20:21], v[8:9], v[18:19], v[16:17]
	v_pk_fma_f32 v[18:19], v[6:7], v[26:27], v[14:15]
	v_pk_fma_f32 v[24:25], v[4:5], v[24:25], v[12:13]
	v_pk_fma_f32 v[22:23], v[2:3], v[22:23], v[10:11]
	s_and_b64 vcc, exec, s[4:5]
	s_mov_b64 s[8:9], -1
	s_cbranch_vccnz .LBB0_1299
	v_lshlrev_b64 v[30:31], 12, v[106:107]
	v_lshl_add_u64 v[30:31], s[6:7], 0, v[30:31]
	v_lshl_add_u64 v[30:31], v[208:209], 1, v[30:31]
	s_mov_b64 s[8:9], 0
	v_cvt_pk_bf16_f32 v26, v18, v19
	v_cvt_pk_bf16_f32 v27, v20, v21
	v_cvt_pk_bf16_f32 v28, v22, v23
	v_cvt_pk_bf16_f32 v29, v24, v25
	global_store_dwordx4 v[30:31], v[26:29], off offset:256
.LBB0_1299:
	s_andn2_b64 vcc, exec, s[8:9]
	s_cbranch_vccnz .LBB0_1301
	v_lshlrev_b64 v[26:27], 13, v[106:107]
	v_lshl_add_u64 v[26:27], s[24:25], 0, v[26:27]
	v_lshl_add_u64 v[26:27], v[208:209], 2, v[26:27]
	global_store_dwordx4 v[26:27], v[18:21], off offset:512
	global_store_dwordx4 v[26:27], v[22:25], off offset:528
.LBB0_1301:
	v_mov_b32_e32 v134, v135
	s_nop 0
	v_mov_b32_e32 v22, v135
	v_mov_b32_e32 v23, v135
	v_pk_mul_f32 v[18:19], v[44:45], v[22:23]
	v_pk_mul_f32 v[24:25], v[52:53], v[134:135]
	v_pk_mul_f32 v[22:23], v[42:43], v[22:23]
	v_pk_mul_f32 v[26:27], v[50:51], v[134:135]
	v_pk_fma_f32 v[20:21], v[8:9], v[18:19], v[16:17]
	v_pk_fma_f32 v[18:19], v[6:7], v[24:25], v[14:15]
	v_pk_fma_f32 v[24:25], v[4:5], v[22:23], v[12:13]
	v_pk_fma_f32 v[22:23], v[2:3], v[26:27], v[10:11]
	s_and_b64 vcc, exec, s[4:5]
	s_mov_b64 s[8:9], -1
	s_cbranch_vccnz .LBB0_1303
	v_lshlrev_b64 v[30:31], 12, v[100:101]
	v_lshl_add_u64 v[30:31], s[6:7], 0, v[30:31]
	v_lshl_add_u64 v[30:31], v[208:209], 1, v[30:31]
	s_mov_b64 s[8:9], 0
	v_cvt_pk_bf16_f32 v26, v18, v19
	v_cvt_pk_bf16_f32 v27, v20, v21
	v_cvt_pk_bf16_f32 v28, v22, v23
	v_cvt_pk_bf16_f32 v29, v24, v25
	global_store_dwordx4 v[30:31], v[26:29], off offset:256
.LBB0_1303:
	s_andn2_b64 vcc, exec, s[8:9]
	s_cbranch_vccnz .LBB0_1305
	v_lshlrev_b64 v[26:27], 13, v[100:101]
	v_lshl_add_u64 v[26:27], s[24:25], 0, v[26:27]
	v_lshl_add_u64 v[26:27], v[208:209], 2, v[26:27]
	global_store_dwordx4 v[26:27], v[18:21], off offset:512
	global_store_dwordx4 v[26:27], v[22:25], off offset:528
.LBB0_1305:
	s_nop 1
	v_mov_b32_e32 v22, v132
	v_mov_b32_e32 v23, v132
	v_mov_b32_e32 v24, v132
	v_mov_b32_e32 v25, v132
	v_pk_mul_f32 v[18:19], v[60:61], v[24:25]
	v_pk_mul_f32 v[26:27], v[64:65], v[22:23]
	v_pk_mul_f32 v[24:25], v[58:59], v[24:25]
	v_pk_mul_f32 v[22:23], v[62:63], v[22:23]
	v_pk_fma_f32 v[20:21], v[8:9], v[18:19], v[16:17]
	v_pk_fma_f32 v[18:19], v[6:7], v[26:27], v[14:15]
	v_pk_fma_f32 v[24:25], v[4:5], v[24:25], v[12:13]
	v_pk_fma_f32 v[22:23], v[2:3], v[22:23], v[10:11]
	s_and_b64 vcc, exec, s[4:5]
	s_mov_b64 s[8:9], -1
	s_cbranch_vccnz .LBB0_1307
	v_lshlrev_b64 v[30:31], 12, v[98:99]
	v_lshl_add_u64 v[30:31], s[6:7], 0, v[30:31]
	v_lshl_add_u64 v[30:31], v[208:209], 1, v[30:31]
	s_mov_b64 s[8:9], 0
	v_cvt_pk_bf16_f32 v26, v18, v19
	v_cvt_pk_bf16_f32 v27, v20, v21
	v_cvt_pk_bf16_f32 v28, v22, v23
	v_cvt_pk_bf16_f32 v29, v24, v25
	global_store_dwordx4 v[30:31], v[26:29], off offset:256
.LBB0_1307:
	s_andn2_b64 vcc, exec, s[8:9]
	s_cbranch_vccnz .LBB0_1309
	v_lshlrev_b64 v[26:27], 13, v[98:99]
	v_lshl_add_u64 v[26:27], s[24:25], 0, v[26:27]
	v_lshl_add_u64 v[26:27], v[208:209], 2, v[26:27]
	global_store_dwordx4 v[26:27], v[18:21], off offset:512
	global_store_dwordx4 v[26:27], v[22:25], off offset:528
.LBB0_1309:
	v_mov_b32_e32 v132, v133
	v_mov_b32_e32 v18, v133
	v_mov_b32_e32 v19, v133
	v_pk_mul_f32 v[20:21], v[76:77], v[18:19]
	v_pk_mul_f32 v[22:23], v[84:85], v[132:133]
	v_pk_fma_f32 v[8:9], v[8:9], v[20:21], v[16:17]
	v_pk_fma_f32 v[6:7], v[6:7], v[22:23], v[14:15]
	v_pk_mul_f32 v[14:15], v[74:75], v[18:19]
	v_pk_mul_f32 v[16:17], v[82:83], v[132:133]
	v_pk_fma_f32 v[4:5], v[4:5], v[14:15], v[12:13]
	v_pk_fma_f32 v[2:3], v[2:3], v[16:17], v[10:11]
	s_and_b64 vcc, exec, s[4:5]
	s_mov_b64 s[4:5], -1
	s_cbranch_vccnz .LBB0_1311
	v_lshlrev_b64 v[14:15], 12, v[34:35]
	v_lshl_add_u64 v[14:15], s[6:7], 0, v[14:15]
	v_lshl_add_u64 v[14:15], v[208:209], 1, v[14:15]
	s_mov_b64 s[4:5], 0
	v_cvt_pk_bf16_f32 v10, v6, v7
	v_cvt_pk_bf16_f32 v11, v8, v9
	v_cvt_pk_bf16_f32 v12, v2, v3
	v_cvt_pk_bf16_f32 v13, v4, v5
	global_store_dwordx4 v[14:15], v[10:13], off offset:256
.LBB0_1311:
	s_andn2_b64 vcc, exec, s[4:5]
	s_cbranch_vccnz .LBB0_1313
	v_lshlrev_b64 v[10:11], 13, v[34:35]
	v_lshl_add_u64 v[10:11], s[24:25], 0, v[10:11]
	v_lshl_add_u64 v[10:11], v[208:209], 2, v[10:11]
	global_store_dwordx4 v[10:11], v[6:9], off offset:512
	global_store_dwordx4 v[10:11], v[2:5], off offset:528

	.amdhsa_kernel _Z10fwd_kernel6Params
		.amdhsa_group_segment_fixed_size 0
		.amdhsa_private_segment_fixed_size 0
		.amdhsa_kernarg_size 480
		.amdhsa_user_sgpr_count 2
		.amdhsa_user_sgpr_dispatch_ptr 0
		.amdhsa_user_sgpr_queue_ptr 0
		.amdhsa_user_sgpr_kernarg_segment_ptr 1
		.amdhsa_user_sgpr_dispatch_id 0
		.amdhsa_user_sgpr_kernarg_preload_length 0
		.amdhsa_user_sgpr_kernarg_preload_offset 0
		.amdhsa_user_sgpr_private_segment_size 0
		.amdhsa_uses_dynamic_stack 0
		.amdhsa_enable_private_segment 0
		.amdhsa_system_sgpr_workgroup_id_x 1
		.amdhsa_system_sgpr_workgroup_id_y 0
		.amdhsa_system_sgpr_workgroup_id_z 0
		.amdhsa_system_sgpr_workgroup_info 0
		.amdhsa_system_vgpr_workitem_id 0
		.amdhsa_next_free_vgpr 256
		.amdhsa_next_free_sgpr 102
		.amdhsa_accum_offset 256
		.amdhsa_reserve_vcc 1
		.amdhsa_float_round_mode_32 0
		.amdhsa_float_round_mode_16_64 0
		.amdhsa_float_denorm_mode_32 3
		.amdhsa_float_denorm_mode_16_64 3
		.amdhsa_dx10_clamp 1
		.amdhsa_ieee_mode 1
		.amdhsa_fp16_overflow 0
		.amdhsa_tg_split 0
		.amdhsa_exception_fp_ieee_invalid_op 0
		.amdhsa_exception_fp_denorm_src 0
		.amdhsa_exception_fp_ieee_div_zero 0
		.amdhsa_exception_fp_ieee_overflow 0
		.amdhsa_exception_fp_ieee_underflow 0
		.amdhsa_exception_fp_ieee_inexact 0
		.amdhsa_exception_int_div_zero 0
	.end_amdhsa_kernel

amdhsa.kernels:
  - .agpr_count:     0
    .args:
      - .offset:         0
        .size:           224
        .value_kind:     by_value
      - .offset:         224
        .size:           4
        .value_kind:     hidden_block_count_x
      - .offset:         228
        .size:           4
        .value_kind:     hidden_block_count_y
      - .offset:         232
        .size:           4
        .value_kind:     hidden_block_count_z
      - .offset:         236
        .size:           2
        .value_kind:     hidden_group_size_x
      - .offset:         238
        .size:           2
        .value_kind:     hidden_group_size_y
      - .offset:         240
        .size:           2
        .value_kind:     hidden_group_size_z
      - .offset:         242
        .size:           2
        .value_kind:     hidden_remainder_x
      - .offset:         244
        .size:           2
        .value_kind:     hidden_remainder_y
      - .offset:         246
        .size:           2
        .value_kind:     hidden_remainder_z
      - .offset:         264
        .size:           8
        .value_kind:     hidden_global_offset_x
      - .offset:         272
        .size:           8
        .value_kind:     hidden_global_offset_y
      - .offset:         280
        .size:           8
        .value_kind:     hidden_global_offset_z
      - .offset:         288
        .size:           2
        .value_kind:     hidden_grid_dims
      - .offset:         344
        .size:           4
        .value_kind:     hidden_dynamic_lds_size
    .group_segment_fixed_size: 0
    .kernarg_segment_align: 8
    .kernarg_segment_size: 480
    .language:       OpenCL C
    .language_version:
      - 2
      - 0
    .max_flat_workgroup_size: 512
    .name:           _Z10fwd_kernel6Params
    .private_segment_fixed_size: 0
    .sgpr_count:     108
    .sgpr_spill_count: 7
    .symbol:         _Z10fwd_kernel6Params.kd
    .uniform_work_group_size: 1
    .uses_dynamic_stack: false
    .vgpr_count:     256
    .vgpr_spill_count: 0
    .wavefront_size: 64
